# v43 + static priority: per-MFMA-block s_setprio flips deleted in the five GEMM K-loops, waves 4-7 (trailing half) raised to prio 1 once per unit, prio 0 in epilogues
# speedup vs baseline: 1.0082x; 1.0059x over previous
; #define PG8_STAGE(bufoff, gbase, voff) do { _Pragma("unroll") for (int _i = 0; _i < 2; ++_i) \
;         __builtin_amdgcn_global_load_lds((const unsigned*)((const char*)(gbase) + (voff)[_i]), (PG8_LAS unsigned*)(lds + (bufoff) + ldsw + _i * 8192), 16, 0, 0); } while (0)
; #define PG8_LDA(dst, b, h) do { _Pragma("unroll") for (int m = 0; m < 4; ++m) _Pragma("unroll") for (int k = 0; k < 2; ++k) dst[m][k] = *(const PG8_LAS bf16x8*)(lds + PG8_SA(b, h) + aoff + m * 2048 + k * 1024); } while (0)
; #define PG8_LDB(dst, b, h) do { _Pragma("unroll") for (int n = 0; n < 2; ++n) _Pragma("unroll") for (int k = 0; k < 2; ++k) dst[n][k] = *(const PG8_LAS bf16x8*)(lds + PG8_SB(b, h) + boff + n * 2048 + k * 1024); } while (0)
; #define PG8_MMA(ai, bj, At, Bt) do { __builtin_amdgcn_s_setprio(1); _Pragma("unroll") for (int m = 0; m < 4; ++m) _Pragma("unroll") for (int n = 0; n < 2; ++n) _Pragma("unroll") for (int k = 0; k < 2; ++k) \
;         acc[ai][bj][m][n] = mma16<Epi::I8>(Bt[n][k], At[m][k], acc[ai][bj][m][n]); __builtin_amdgcn_s_setprio(0); } while (0)
; #define PG8_WAIT_V(n) asm volatile("s_waitcnt vmcnt(" #n ")" ::: "memory")
; #define PG8_WAIT_L(n) asm volatile("s_waitcnt lgkmcnt(" #n ")" ::: "memory")
; #define PG8_BAR __builtin_amdgcn_s_barrier()
; #define PG8_SCHED __builtin_amdgcn_sched_barrier(0)
; template <class Epi, class Sched, bool ALIGN_EPI = false, bool SP2 = false>
; __device__ __forceinline__ void gemm_phase(PG8_LAS unsigned char* lds, const Gemm g, const Sched& S, const Epi& E) {
;     ...
;             if (last && has_next) S.a_ready(nxt);
;             if constexpr (SP2) {
;             PG8_LDB(B0, 0, 0); PG8_LDB(B1, 0, 1); PG8_SCHED; PG8_LDA(At, 0, 0); PG8_STAGE(PG8_SA(1, 1), a1 + hstep, voffA);
;             PG8_WAIT_V(8); PG8_WAIT_L(0); PG8_BAR; PG8_MMA(0, 0, At, B0); PG8_MMA(0, 1, At, B1); PG8_BAR; PG8_SCHED;
;             PG8_LDA(At, 0, 1); PG8_STAGE(PG8_SB(0, 0), b2, voffB); PG8_STAGE(PG8_SB(0, 1), b2 + hstep, voffB); PG8_STAGE(PG8_SA(0, 0), a2, voffA);
;             PG8_WAIT_V(8); PG8_WAIT_L(0); PG8_BAR; PG8_MMA(1, 0, At, B0); PG8_MMA(1, 1, At, B1); PG8_BAR; PG8_SCHED;
.Lpeel80:
	v_readfirstlane_b32 s98, v246
	s_nop 0
	s_bitcmp1_b32 s98, 8
	s_cbranch_scc0 .Lprio80
	s_setprio 1
.Lprio80:
	s_add_u32 s8, s0, 0x100
	s_addc_u32 s9, s1, 0
	s_add_i32 vcc_hi, 0, 0x10000
	s_cmp_eq_u32 vcc_lo, 12
	s_cselect_b32 s13, s66, s9
	s_cselect_b32 s12, s67, s8
	s_cselect_b32 s7, s82, s97
	s_cselect_b32 s6, s83, s96
	s_add_i32 s4, 0, 0x14000
	v_add_u32_e32 v38, vcc_hi, v242
	v_add_u32_e32 v158, s4, v242
	ds_read_b128 v[18:21], v38
	ds_read_b128 v[22:25], v38 offset:1024
	ds_read_b128 v[34:37], v38 offset:2048
	ds_read_b128 v[38:41], v38 offset:3072
	ds_read_b128 v[130:133], v158
	ds_read_b128 v[134:137], v158 offset:1024
	ds_read_b128 v[154:157], v158 offset:2048
	ds_read_b128 v[158:161], v158 offset:3072
	s_add_i32 m0, s11, 0xc000
	ds_read_b128 v[162:165], v243
	ds_read_b128 v[166:169], v243 offset:1024
	ds_read_b128 v[170:173], v243 offset:2048
	ds_read_b128 v[174:177], v243 offset:3072
	ds_read_b128 v[178:181], v243 offset:4096
	ds_read_b128 v[182:185], v243 offset:5120
	ds_read_b128 v[186:189], v243 offset:6144
	ds_read_b128 v[190:193], v243 offset:7168
	global_load_lds_dwordx4 v216, s[0:1]
	s_add_i32 m0, s11, 0xe000
	s_nop 0
	global_load_lds_dwordx4 v218, s[0:1]
	s_waitcnt vmcnt(8)
	s_waitcnt lgkmcnt(0)
	s_barrier
	s_waitcnt lgkmcnt(0)
	v_mfma_i32_16x16x64_i8 v[150:153], v[18:21], v[162:165], 0
	v_mfma_i32_16x16x64_i8 v[146:149], v[34:37], v[162:165], 0
	v_mfma_i32_16x16x64_i8 v[110:113], v[34:37], v[170:173], 0
	v_mfma_i32_16x16x64_i8 v[118:121], v[18:21], v[170:173], 0
	v_mfma_i32_16x16x64_i8 v[54:57], v[18:21], v[178:181], 0
	v_mfma_i32_16x16x64_i8 v[30:33], v[34:37], v[178:181], 0
	v_mfma_i32_16x16x64_i8 v[58:61], v[34:37], v[186:189], 0
	v_mfma_i32_16x16x64_i8 v[94:97], v[18:21], v[186:189], 0
	v_mfma_i32_16x16x64_i8 v[150:153], v[22:25], v[166:169], v[150:153]
	v_mfma_i32_16x16x64_i8 v[146:149], v[38:41], v[166:169], v[146:149]
	v_mfma_i32_16x16x64_i8 v[110:113], v[38:41], v[174:177], v[110:113]
	v_mfma_i32_16x16x64_i8 v[118:121], v[22:25], v[174:177], v[118:121]
	v_mfma_i32_16x16x64_i8 v[54:57], v[22:25], v[182:185], v[54:57]
	v_mfma_i32_16x16x64_i8 v[30:33], v[38:41], v[182:185], v[30:33]
	v_mfma_i32_16x16x64_i8 v[58:61], v[38:41], v[190:193], v[58:61]
	v_mfma_i32_16x16x64_i8 v[94:97], v[22:25], v[190:193], v[94:97]
	v_mfma_i32_16x16x64_i8 v[142:145], v[130:133], v[162:165], 0
	v_mfma_i32_16x16x64_i8 v[138:141], v[154:157], v[162:165], 0
	v_mfma_i32_16x16x64_i8 v[98:101], v[154:157], v[170:173], 0
	v_mfma_i32_16x16x64_i8 v[102:105], v[130:133], v[170:173], 0
	v_mfma_i32_16x16x64_i8 v[42:45], v[130:133], v[178:181], 0
	v_mfma_i32_16x16x64_i8 v[26:29], v[154:157], v[178:181], 0
	v_mfma_i32_16x16x64_i8 v[62:65], v[154:157], v[186:189], 0
	v_mfma_i32_16x16x64_i8 v[78:81], v[130:133], v[186:189], 0
	v_mfma_i32_16x16x64_i8 v[142:145], v[134:137], v[166:169], v[142:145]
	v_mfma_i32_16x16x64_i8 v[138:141], v[158:161], v[166:169], v[138:141]
	v_mfma_i32_16x16x64_i8 v[98:101], v[158:161], v[174:177], v[98:101]
	v_mfma_i32_16x16x64_i8 v[102:105], v[134:137], v[174:177], v[102:105]
	v_mfma_i32_16x16x64_i8 v[42:45], v[134:137], v[182:185], v[42:45]
	v_mfma_i32_16x16x64_i8 v[26:29], v[158:161], v[182:185], v[26:29]
	v_mfma_i32_16x16x64_i8 v[62:65], v[158:161], v[190:193], v[62:65]
	v_mfma_i32_16x16x64_i8 v[78:81], v[134:137], v[190:193], v[78:81]
	s_barrier
	s_add_i32 s0, vcc_hi, s69
	v_lshl_add_u64 v[198:199], s[6:7], 0, v[0:1]
	s_mov_b32 m0, s0
	ds_read_b128 v[162:165], v243 offset:16384
	ds_read_b128 v[166:169], v243 offset:17408
	ds_read_b128 v[170:173], v243 offset:18432
	ds_read_b128 v[174:177], v243 offset:19456
	ds_read_b128 v[178:181], v243 offset:20480
	ds_read_b128 v[182:185], v243 offset:21504
	ds_read_b128 v[186:189], v243 offset:22528
	ds_read_b128 v[190:193], v243 offset:23552
	global_load_lds_dwordx4 v[198:199], off
	s_add_i32 m0, s0, 0x2000
	s_add_u32 s0, s6, 0x40000
	v_lshl_add_u64 v[200:201], s[6:7], 0, v[214:215]
	s_addc_u32 s1, s7, 0
	s_add_i32 s4, s4, s69
	global_load_lds_dwordx4 v[200:201], off
	s_mov_b32 m0, s4
	v_lshl_add_u64 v[206:207], s[12:13], 0, v[210:211]
	global_load_lds_dwordx4 v0, s[0:1]
	s_add_i32 m0, s4, 0x2000
	v_lshl_add_u64 v[220:221], s[12:13], 0, v[212:213]
	global_load_lds_dwordx4 v214, s[0:1]
	s_mov_b32 m0, s11
	s_nop 0
	global_load_lds_dwordx4 v[206:207], off
	s_mov_b32 m0, s71
	s_nop 0
	global_load_lds_dwordx4 v[220:221], off
	s_waitcnt vmcnt(8)
	s_waitcnt lgkmcnt(0)
	s_barrier
	s_waitcnt lgkmcnt(0)
	v_mfma_i32_16x16x64_i8 v[106:109], v[18:21], v[162:165], 0
	v_mfma_i32_16x16x64_i8 v[46:49], v[34:37], v[162:165], 0
	v_mfma_i32_16x16x64_i8 v[6:9], v[34:37], v[170:173], 0
	v_mfma_i32_16x16x64_i8 v[14:17], v[18:21], v[170:173], 0
	v_mfma_i32_16x16x64_i8 v[90:93], v[18:21], v[178:181], 0
	v_mfma_i32_16x16x64_i8 v[86:89], v[34:37], v[178:181], 0
	v_mfma_i32_16x16x64_i8 v[18:21], v[18:21], v[186:189], 0
	v_mfma_i32_16x16x64_i8 v[106:109], v[22:25], v[166:169], v[106:109]
	v_mfma_i32_16x16x64_i8 v[46:49], v[38:41], v[166:169], v[46:49]
	v_mfma_i32_16x16x64_i8 v[6:9], v[38:41], v[174:177], v[6:9]
	v_mfma_i32_16x16x64_i8 v[14:17], v[22:25], v[174:177], v[14:17]
	v_mfma_i32_16x16x64_i8 v[90:93], v[22:25], v[182:185], v[90:93]
	v_mfma_i32_16x16x64_i8 v[86:89], v[38:41], v[182:185], v[86:89]
	v_mfma_i32_16x16x64_i8 v[18:21], v[22:25], v[190:193], v[18:21]
	v_mfma_i32_16x16x64_i8 v[22:25], v[34:37], v[186:189], 0
	v_mfma_i32_16x16x64_i8 v[22:25], v[38:41], v[190:193], v[22:25]
	v_mfma_i32_16x16x64_i8 v[38:41], v[154:157], v[162:165], 0
	v_mfma_i32_16x16x64_i8 v[2:5], v[154:157], v[170:173], 0
	v_mfma_i32_16x16x64_i8 v[10:13], v[130:133], v[170:173], 0
	v_mfma_i32_16x16x64_i8 v[50:53], v[130:133], v[178:181], 0
	v_mfma_i32_16x16x64_i8 v[34:37], v[130:133], v[162:165], 0
	v_mfma_i32_16x16x64_i8 v[82:85], v[134:137], v[182:185], v[50:53]
	v_mfma_i32_16x16x64_i8 v[50:53], v[154:157], v[178:181], 0
	v_mfma_i32_16x16x64_i8 v[2:5], v[158:161], v[174:177], v[2:5]
	v_mfma_i32_16x16x64_i8 v[10:13], v[134:137], v[174:177], v[10:13]
	v_mfma_i32_16x16x64_i8 v[38:41], v[158:161], v[166:169], v[38:41]
	v_mfma_i32_16x16x64_i8 v[34:37], v[134:137], v[166:169], v[34:37]
	v_mfma_i32_16x16x64_i8 v[74:77], v[158:161], v[182:185], v[50:53]
	v_mfma_i32_16x16x64_i8 v[50:53], v[130:133], v[186:189], 0
	v_mfma_i32_16x16x64_i8 v[122:125], v[134:137], v[190:193], v[50:53]
	v_mfma_i32_16x16x64_i8 v[50:53], v[154:157], v[186:189], 0
	v_mfma_i32_16x16x64_i8 v[70:73], v[158:161], v[190:193], v[50:53]
	s_barrier
; #define PG8_STAGE(bufoff, gbase, voff) do { _Pragma("unroll") for (int _i = 0; _i < 2; ++_i) \
;         __builtin_amdgcn_global_load_lds((const unsigned*)((const char*)(gbase) + (voff)[_i]), (PG8_LAS unsigned*)(lds + (bufoff) + ldsw + _i * 8192), 16, 0, 0); } while (0)
; #define PG8_LDA(dst, b, h) do { _Pragma("unroll") for (int m = 0; m < 4; ++m) _Pragma("unroll") for (int k = 0; k < 2; ++k) dst[m][k] = *(const PG8_LAS bf16x8*)(lds + PG8_SA(b, h) + aoff + m * 2048 + k * 1024); } while (0)
; #define PG8_LDB(dst, b, h) do { _Pragma("unroll") for (int n = 0; n < 2; ++n) _Pragma("unroll") for (int k = 0; k < 2; ++k) dst[n][k] = *(const PG8_LAS bf16x8*)(lds + PG8_SB(b, h) + boff + n * 2048 + k * 1024); } while (0)
; #define PG8_MMA(ai, bj, At, Bt) do { __builtin_amdgcn_s_setprio(1); _Pragma("unroll") for (int m = 0; m < 4; ++m) _Pragma("unroll") for (int n = 0; n < 2; ++n) _Pragma("unroll") for (int k = 0; k < 2; ++k) \
;         acc[ai][bj][m][n] = mma16<Epi::I8>(Bt[n][k], At[m][k], acc[ai][bj][m][n]); __builtin_amdgcn_s_setprio(0); } while (0)
; #define PG8_WAIT_V(n) asm volatile("s_waitcnt vmcnt(" #n ")" ::: "memory")
; #define PG8_WAIT_L(n) asm volatile("s_waitcnt lgkmcnt(" #n ")" ::: "memory")
; #define PG8_BAR __builtin_amdgcn_s_barrier()
; #define PG8_SCHED __builtin_amdgcn_sched_barrier(0)
; template <class Epi, class Sched, bool ALIGN_EPI = false, bool SP2 = false>
; __device__ __forceinline__ void gemm_phase(PG8_LAS unsigned char* lds, const Gemm g, const Sched& S, const Epi& E) {
;     ...
;             PG8_LDB(B0, 1, 0); PG8_LDB(B1, 1, 1); PG8_SCHED; PG8_LDA(At, 1, 0); PG8_STAGE(PG8_SA(0, 1), a2 + hstep, voffA);
;             PG8_WAIT_V(8); PG8_WAIT_L(0); PG8_BAR; PG8_MMA(0, 0, At, B0); PG8_MMA(0, 1, At, B1); PG8_BAR; PG8_SCHED;
;             PG8_LDA(At, 1, 1); PG8_STAGE(PG8_SB(1, 0), b3, voffB); PG8_STAGE(PG8_SB(1, 1), b3 + hstep, voffB); PG8_STAGE(PG8_SA(1, 0), a3, voffA);
;             PG8_WAIT_V(8); PG8_WAIT_L(0); PG8_BAR; PG8_MMA(1, 0, At, B0); PG8_MMA(1, 1, At, B1); PG8_BAR; PG8_SCHED;
	s_add_i32 s4, 0, 0x18000
	v_add_u32_e32 v126, s4, v242
	s_add_i32 s5, 0, 0x1c000
	ds_read_b128 v[50:53], v126
	ds_read_b128 v[66:69], v126 offset:1024
	ds_read_b128 v[114:117], v126 offset:2048
	ds_read_b128 v[130:133], v126 offset:3072
	v_add_u32_e32 v126, s5, v242
	ds_read_b128 v[134:137], v126
	ds_read_b128 v[154:157], v126 offset:1024
	ds_read_b128 v[158:161], v126 offset:2048
	ds_read_b128 v[162:165], v126 offset:3072
	s_add_u32 s0, s12, 0x40000
	s_addc_u32 s1, s13, 0
	s_mov_b32 m0, s80
	ds_read_b128 v[126:129], v243 offset:32768
	ds_read_b128 v[166:169], v243 offset:33792
	ds_read_b128 v[170:173], v243 offset:34816
	ds_read_b128 v[174:177], v243 offset:35840
	ds_read_b128 v[178:181], v243 offset:36864
	ds_read_b128 v[182:185], v243 offset:37888
	ds_read_b128 v[186:189], v243 offset:38912
	ds_read_b128 v[190:193], v243 offset:39936
	global_load_lds_dwordx4 v210, s[0:1]
	s_mov_b32 m0, s81
	s_nop 0
	global_load_lds_dwordx4 v212, s[0:1]
	s_waitcnt vmcnt(8)
	s_waitcnt lgkmcnt(0)
	s_barrier
	s_waitcnt lgkmcnt(0)
	v_mfma_i32_16x16x64_i8 v[150:153], v[50:53], v[126:129], v[150:153]
	v_mfma_i32_16x16x64_i8 v[146:149], v[114:117], v[126:129], v[146:149]
	v_mfma_i32_16x16x64_i8 v[110:113], v[114:117], v[170:173], v[110:113]
	v_mfma_i32_16x16x64_i8 v[118:121], v[50:53], v[170:173], v[118:121]
	v_mfma_i32_16x16x64_i8 v[54:57], v[50:53], v[178:181], v[54:57]
	v_mfma_i32_16x16x64_i8 v[30:33], v[114:117], v[178:181], v[30:33]
	v_mfma_i32_16x16x64_i8 v[58:61], v[114:117], v[186:189], v[58:61]
	v_mfma_i32_16x16x64_i8 v[94:97], v[50:53], v[186:189], v[94:97]
	v_mfma_i32_16x16x64_i8 v[150:153], v[66:69], v[166:169], v[150:153]
	v_mfma_i32_16x16x64_i8 v[146:149], v[130:133], v[166:169], v[146:149]
	v_mfma_i32_16x16x64_i8 v[110:113], v[130:133], v[174:177], v[110:113]
	v_mfma_i32_16x16x64_i8 v[118:121], v[66:69], v[174:177], v[118:121]
	v_mfma_i32_16x16x64_i8 v[54:57], v[66:69], v[182:185], v[54:57]
	v_mfma_i32_16x16x64_i8 v[30:33], v[130:133], v[182:185], v[30:33]
	v_mfma_i32_16x16x64_i8 v[58:61], v[130:133], v[190:193], v[58:61]
	v_mfma_i32_16x16x64_i8 v[94:97], v[66:69], v[190:193], v[94:97]
	v_mfma_i32_16x16x64_i8 v[142:145], v[134:137], v[126:129], v[142:145]
	v_mfma_i32_16x16x64_i8 v[126:129], v[158:161], v[126:129], v[138:141]
	v_mfma_i32_16x16x64_i8 v[98:101], v[158:161], v[170:173], v[98:101]
	v_mfma_i32_16x16x64_i8 v[102:105], v[134:137], v[170:173], v[102:105]
	v_mfma_i32_16x16x64_i8 v[42:45], v[134:137], v[178:181], v[42:45]
	v_mfma_i32_16x16x64_i8 v[26:29], v[158:161], v[178:181], v[26:29]
	v_mfma_i32_16x16x64_i8 v[62:65], v[158:161], v[186:189], v[62:65]
	v_mfma_i32_16x16x64_i8 v[78:81], v[134:137], v[186:189], v[78:81]
	v_mfma_i32_16x16x64_i8 v[142:145], v[154:157], v[166:169], v[142:145]
	v_mfma_i32_16x16x64_i8 v[138:141], v[162:165], v[166:169], v[126:129]
	v_mfma_i32_16x16x64_i8 v[98:101], v[162:165], v[174:177], v[98:101]
	v_mfma_i32_16x16x64_i8 v[102:105], v[154:157], v[174:177], v[102:105]
	v_mfma_i32_16x16x64_i8 v[42:45], v[154:157], v[182:185], v[42:45]
	v_mfma_i32_16x16x64_i8 v[26:29], v[162:165], v[182:185], v[26:29]
	v_mfma_i32_16x16x64_i8 v[62:65], v[162:165], v[190:193], v[62:65]
	v_mfma_i32_16x16x64_i8 v[78:81], v[154:157], v[190:193], v[78:81]
	s_barrier
	s_add_i32 s0, s4, s69
	v_lshl_add_u64 v[126:127], v[198:199], 0, s[92:93]
	s_mov_b32 m0, s0
	ds_read_b128 v[166:169], v243 offset:49152
	ds_read_b128 v[170:173], v243 offset:50176
	ds_read_b128 v[174:177], v243 offset:51200
	ds_read_b128 v[178:181], v243 offset:52224
	ds_read_b128 v[182:185], v243 offset:53248
	ds_read_b128 v[186:189], v243 offset:54272
	ds_read_b128 v[190:193], v243 offset:55296
	ds_read_b128 v[194:197], v243 offset:56320
	global_load_lds_dwordx4 v[126:127], off
	s_add_i32 m0, s0, 0x2000
	s_add_u32 s0, s6, 0x40080
	v_lshl_add_u64 v[126:127], v[200:201], 0, s[92:93]
	s_addc_u32 s1, s7, 0
	s_add_i32 s4, s5, s69
	global_load_lds_dwordx4 v[126:127], off
	s_mov_b32 m0, s4
	s_nop 0
	global_load_lds_dwordx4 v0, s[0:1]
	s_add_i32 m0, s4, 0x2000
	s_nop 0
	global_load_lds_dwordx4 v214, s[0:1]
	v_lshl_add_u64 v[126:127], v[206:207], 0, s[92:93]
	s_mov_b32 m0, s84
	s_nop 0
	global_load_lds_dwordx4 v[126:127], off
	v_lshl_add_u64 v[126:127], v[220:221], 0, s[92:93]
	s_mov_b32 m0, s85
	s_nop 0
	global_load_lds_dwordx4 v[126:127], off
	s_waitcnt vmcnt(8)
	s_waitcnt lgkmcnt(0)
	s_barrier
	s_waitcnt lgkmcnt(0)
	v_mfma_i32_16x16x64_i8 v[18:21], v[50:53], v[190:193], v[18:21]
	v_mfma_i32_16x16x64_i8 v[106:109], v[50:53], v[166:169], v[106:109]
	v_mfma_i32_16x16x64_i8 v[46:49], v[114:117], v[166:169], v[46:49]
	v_mfma_i32_16x16x64_i8 v[6:9], v[114:117], v[174:177], v[6:9]
	v_mfma_i32_16x16x64_i8 v[14:17], v[50:53], v[174:177], v[14:17]
	v_mfma_i32_16x16x64_i8 v[90:93], v[50:53], v[182:185], v[90:93]
	v_mfma_i32_16x16x64_i8 v[86:89], v[114:117], v[182:185], v[86:89]
	v_mfma_i32_16x16x64_i8 v[126:129], v[66:69], v[194:197], v[18:21]
	v_mfma_i32_16x16x64_i8 v[106:109], v[66:69], v[170:173], v[106:109]
	v_mfma_i32_16x16x64_i8 v[46:49], v[130:133], v[170:173], v[46:49]
	v_mfma_i32_16x16x64_i8 v[6:9], v[130:133], v[178:181], v[6:9]
	v_mfma_i32_16x16x64_i8 v[14:17], v[66:69], v[178:181], v[14:17]
	v_mfma_i32_16x16x64_i8 v[90:93], v[66:69], v[186:189], v[90:93]
	v_mfma_i32_16x16x64_i8 v[86:89], v[130:133], v[186:189], v[86:89]
	v_mfma_i32_16x16x64_i8 v[18:21], v[114:117], v[190:193], v[22:25]
	v_mfma_i32_16x16x64_i8 v[66:69], v[130:133], v[194:197], v[18:21]
	v_mfma_i32_16x16x64_i8 v[18:21], v[134:137], v[166:169], v[34:37]
	v_mfma_i32_16x16x64_i8 v[10:13], v[134:137], v[174:177], v[10:13]
	v_mfma_i32_16x16x64_i8 v[2:5], v[158:161], v[174:177], v[2:5]
	v_mfma_i32_16x16x64_i8 v[114:117], v[154:157], v[170:173], v[18:21]
	v_mfma_i32_16x16x64_i8 v[18:21], v[158:161], v[166:169], v[38:41]
	v_mfma_i32_16x16x64_i8 v[50:53], v[162:165], v[170:173], v[18:21]
	v_mfma_i32_16x16x64_i8 v[18:21], v[134:137], v[182:185], v[82:85]
	v_mfma_i32_16x16x64_i8 v[10:13], v[154:157], v[178:181], v[10:13]
	v_mfma_i32_16x16x64_i8 v[2:5], v[162:165], v[178:181], v[2:5]
	v_mfma_i32_16x16x64_i8 v[82:85], v[154:157], v[186:189], v[18:21]
	v_mfma_i32_16x16x64_i8 v[18:21], v[158:161], v[182:185], v[74:77]
	v_mfma_i32_16x16x64_i8 v[74:77], v[162:165], v[186:189], v[18:21]
	v_mfma_i32_16x16x64_i8 v[18:21], v[134:137], v[190:193], v[122:125]
	v_mfma_i32_16x16x64_i8 v[122:125], v[154:157], v[194:197], v[18:21]
	v_mfma_i32_16x16x64_i8 v[18:21], v[158:161], v[190:193], v[70:73]
	v_mfma_i32_16x16x64_i8 v[70:73], v[162:165], v[194:197], v[18:21]
	s_barrier
	s_add_i32 vcc_lo, vcc_lo, 2
	s_add_u32 s96, s96, 0x100
	s_addc_u32 s97, s97, 0
	s_cmp_gt_u32 vcc_lo, 13
	s_mov_b64 s[0:1], s[8:9]
	s_cbranch_scc0 .LBB0_80
	s_branch .Lpeelx80
; #define PG8_STAGE(bufoff, gbase, voff) do { _Pragma("unroll") for (int _i = 0; _i < 2; ++_i) \
;         __builtin_amdgcn_global_load_lds((const unsigned*)((const char*)(gbase) + (voff)[_i]), (PG8_LAS unsigned*)(lds + (bufoff) + ldsw + _i * 8192), 16, 0, 0); } while (0)
; #define PG8_LDA(dst, b, h) do { _Pragma("unroll") for (int m = 0; m < 4; ++m) _Pragma("unroll") for (int k = 0; k < 2; ++k) dst[m][k] = *(const PG8_LAS bf16x8*)(lds + PG8_SA(b, h) + aoff + m * 2048 + k * 1024); } while (0)
; #define PG8_LDB(dst, b, h) do { _Pragma("unroll") for (int n = 0; n < 2; ++n) _Pragma("unroll") for (int k = 0; k < 2; ++k) dst[n][k] = *(const PG8_LAS bf16x8*)(lds + PG8_SB(b, h) + boff + n * 2048 + k * 1024); } while (0)
; #define PG8_MMA(ai, bj, At, Bt) do { __builtin_amdgcn_s_setprio(1); _Pragma("unroll") for (int m = 0; m < 4; ++m) _Pragma("unroll") for (int n = 0; n < 2; ++n) _Pragma("unroll") for (int k = 0; k < 2; ++k) \
;         acc[ai][bj][m][n] = mma16<Epi::I8>(Bt[n][k], At[m][k], acc[ai][bj][m][n]); __builtin_amdgcn_s_setprio(0); } while (0)
; #define PG8_WAIT_V(n) asm volatile("s_waitcnt vmcnt(" #n ")" ::: "memory")
; #define PG8_WAIT_L(n) asm volatile("s_waitcnt lgkmcnt(" #n ")" ::: "memory")
; #define PG8_BAR __builtin_amdgcn_s_barrier()
; #define PG8_SCHED __builtin_amdgcn_sched_barrier(0)
; template <class Epi, class Sched, bool ALIGN_EPI = false, bool SP2 = false>
; __device__ __forceinline__ void gemm_phase(PG8_LAS unsigned char* lds, const Gemm g, const Sched& S, const Epi& E) {
;     ...
;             PG8_LDB(B0, 0, 0); PG8_LDB(B1, 0, 1); PG8_SCHED; PG8_LDA(At, 0, 0); PG8_STAGE(PG8_SA(1, 1), a1 + hstep, voffA);
;             PG8_WAIT_V(8); PG8_WAIT_L(0); PG8_BAR; PG8_MMA(0, 0, At, B0); PG8_MMA(0, 1, At, B1); PG8_BAR; PG8_SCHED;
;             PG8_LDA(At, 0, 1); PG8_STAGE(PG8_SB(0, 0), b2, voffB); PG8_STAGE(PG8_SB(0, 1), b2 + hstep, voffB); PG8_STAGE(PG8_SA(0, 0), a2, voffA);
;             PG8_WAIT_V(8); PG8_WAIT_L(0); PG8_BAR; PG8_MMA(1, 0, At, B0); PG8_MMA(1, 1, At, B1); PG8_BAR; PG8_SCHED;
.LBB0_80:
	s_add_u32 s8, s0, 0x100
	s_addc_u32 s9, s1, 0
	s_add_i32 vcc_hi, 0, 0x10000
	s_cmp_eq_u32 vcc_lo, 12
	s_cselect_b32 s13, s66, s9
	s_cselect_b32 s12, s67, s8
	s_cselect_b32 s7, s82, s97
	s_cselect_b32 s6, s83, s96
	s_add_i32 s4, 0, 0x14000
	v_add_u32_e32 v38, vcc_hi, v242
	v_add_u32_e32 v158, s4, v242
	ds_read_b128 v[18:21], v38
	ds_read_b128 v[22:25], v38 offset:1024
	ds_read_b128 v[34:37], v38 offset:2048
	ds_read_b128 v[38:41], v38 offset:3072
	ds_read_b128 v[130:133], v158
	ds_read_b128 v[134:137], v158 offset:1024
	ds_read_b128 v[154:157], v158 offset:2048
	ds_read_b128 v[158:161], v158 offset:3072
	s_add_i32 m0, s11, 0xc000
	ds_read_b128 v[162:165], v243
	ds_read_b128 v[166:169], v243 offset:1024
	ds_read_b128 v[170:173], v243 offset:2048
	ds_read_b128 v[174:177], v243 offset:3072
	ds_read_b128 v[178:181], v243 offset:4096
	ds_read_b128 v[182:185], v243 offset:5120
	ds_read_b128 v[186:189], v243 offset:6144
	ds_read_b128 v[190:193], v243 offset:7168
	global_load_lds_dwordx4 v216, s[0:1]
	s_add_i32 m0, s11, 0xe000
	s_nop 0
	global_load_lds_dwordx4 v218, s[0:1]
	s_waitcnt vmcnt(8)
	s_waitcnt lgkmcnt(0)
	s_barrier
	s_waitcnt lgkmcnt(0)
	v_mfma_i32_16x16x64_i8 v[150:153], v[18:21], v[162:165], v[150:153]
	v_mfma_i32_16x16x64_i8 v[146:149], v[34:37], v[162:165], v[146:149]
	v_mfma_i32_16x16x64_i8 v[110:113], v[34:37], v[170:173], v[110:113]
	v_mfma_i32_16x16x64_i8 v[118:121], v[18:21], v[170:173], v[118:121]
	v_mfma_i32_16x16x64_i8 v[54:57], v[18:21], v[178:181], v[54:57]
	v_mfma_i32_16x16x64_i8 v[30:33], v[34:37], v[178:181], v[30:33]
	v_mfma_i32_16x16x64_i8 v[58:61], v[34:37], v[186:189], v[58:61]
	v_mfma_i32_16x16x64_i8 v[94:97], v[18:21], v[186:189], v[94:97]
	v_mfma_i32_16x16x64_i8 v[150:153], v[22:25], v[166:169], v[150:153]
	v_mfma_i32_16x16x64_i8 v[146:149], v[38:41], v[166:169], v[146:149]
	v_mfma_i32_16x16x64_i8 v[110:113], v[38:41], v[174:177], v[110:113]
	v_mfma_i32_16x16x64_i8 v[118:121], v[22:25], v[174:177], v[118:121]
	v_mfma_i32_16x16x64_i8 v[54:57], v[22:25], v[182:185], v[54:57]
	v_mfma_i32_16x16x64_i8 v[30:33], v[38:41], v[182:185], v[30:33]
	v_mfma_i32_16x16x64_i8 v[58:61], v[38:41], v[190:193], v[58:61]
	v_mfma_i32_16x16x64_i8 v[94:97], v[22:25], v[190:193], v[94:97]
	v_mfma_i32_16x16x64_i8 v[142:145], v[130:133], v[162:165], v[142:145]
	v_mfma_i32_16x16x64_i8 v[138:141], v[154:157], v[162:165], v[138:141]
	v_mfma_i32_16x16x64_i8 v[98:101], v[154:157], v[170:173], v[98:101]
	v_mfma_i32_16x16x64_i8 v[102:105], v[130:133], v[170:173], v[102:105]
	v_mfma_i32_16x16x64_i8 v[42:45], v[130:133], v[178:181], v[42:45]
	v_mfma_i32_16x16x64_i8 v[26:29], v[154:157], v[178:181], v[26:29]
	v_mfma_i32_16x16x64_i8 v[62:65], v[154:157], v[186:189], v[62:65]
	v_mfma_i32_16x16x64_i8 v[78:81], v[130:133], v[186:189], v[78:81]
	v_mfma_i32_16x16x64_i8 v[142:145], v[134:137], v[166:169], v[142:145]
	v_mfma_i32_16x16x64_i8 v[138:141], v[158:161], v[166:169], v[138:141]
	v_mfma_i32_16x16x64_i8 v[98:101], v[158:161], v[174:177], v[98:101]
	v_mfma_i32_16x16x64_i8 v[102:105], v[134:137], v[174:177], v[102:105]
	v_mfma_i32_16x16x64_i8 v[42:45], v[134:137], v[182:185], v[42:45]
	v_mfma_i32_16x16x64_i8 v[26:29], v[158:161], v[182:185], v[26:29]
	v_mfma_i32_16x16x64_i8 v[62:65], v[158:161], v[190:193], v[62:65]
	v_mfma_i32_16x16x64_i8 v[78:81], v[134:137], v[190:193], v[78:81]
	s_barrier
	s_add_i32 s0, vcc_hi, s69
	v_lshl_add_u64 v[198:199], s[6:7], 0, v[0:1]
	s_mov_b32 m0, s0
	ds_read_b128 v[162:165], v243 offset:16384
	ds_read_b128 v[166:169], v243 offset:17408
	ds_read_b128 v[170:173], v243 offset:18432
	ds_read_b128 v[174:177], v243 offset:19456
	ds_read_b128 v[178:181], v243 offset:20480
	ds_read_b128 v[182:185], v243 offset:21504
	ds_read_b128 v[186:189], v243 offset:22528
	ds_read_b128 v[190:193], v243 offset:23552
	global_load_lds_dwordx4 v[198:199], off
	s_add_i32 m0, s0, 0x2000
	s_add_u32 s0, s6, 0x40000
	v_lshl_add_u64 v[200:201], s[6:7], 0, v[214:215]
	s_addc_u32 s1, s7, 0
	s_add_i32 s4, s4, s69
	global_load_lds_dwordx4 v[200:201], off
	s_mov_b32 m0, s4
	v_lshl_add_u64 v[206:207], s[12:13], 0, v[210:211]
	global_load_lds_dwordx4 v0, s[0:1]
	s_add_i32 m0, s4, 0x2000
	v_lshl_add_u64 v[220:221], s[12:13], 0, v[212:213]
	global_load_lds_dwordx4 v214, s[0:1]
	s_mov_b32 m0, s11
	s_nop 0
	global_load_lds_dwordx4 v[206:207], off
	s_mov_b32 m0, s71
	s_nop 0
	global_load_lds_dwordx4 v[220:221], off
	s_waitcnt vmcnt(8)
	s_waitcnt lgkmcnt(0)
	s_barrier
	s_waitcnt lgkmcnt(0)
	v_mfma_i32_16x16x64_i8 v[106:109], v[18:21], v[162:165], v[106:109]
	v_mfma_i32_16x16x64_i8 v[46:49], v[34:37], v[162:165], v[46:49]
	v_mfma_i32_16x16x64_i8 v[6:9], v[34:37], v[170:173], v[6:9]
	v_mfma_i32_16x16x64_i8 v[14:17], v[18:21], v[170:173], v[14:17]
	v_mfma_i32_16x16x64_i8 v[90:93], v[18:21], v[178:181], v[90:93]
	v_mfma_i32_16x16x64_i8 v[86:89], v[34:37], v[178:181], v[86:89]
	v_mfma_i32_16x16x64_i8 v[18:21], v[18:21], v[186:189], v[126:129]
	v_mfma_i32_16x16x64_i8 v[106:109], v[22:25], v[166:169], v[106:109]
	v_mfma_i32_16x16x64_i8 v[46:49], v[38:41], v[166:169], v[46:49]
	v_mfma_i32_16x16x64_i8 v[6:9], v[38:41], v[174:177], v[6:9]
	v_mfma_i32_16x16x64_i8 v[14:17], v[22:25], v[174:177], v[14:17]
	v_mfma_i32_16x16x64_i8 v[90:93], v[22:25], v[182:185], v[90:93]
	v_mfma_i32_16x16x64_i8 v[86:89], v[38:41], v[182:185], v[86:89]
	v_mfma_i32_16x16x64_i8 v[18:21], v[22:25], v[190:193], v[18:21]
	v_mfma_i32_16x16x64_i8 v[22:25], v[34:37], v[186:189], v[66:69]
	v_mfma_i32_16x16x64_i8 v[22:25], v[38:41], v[190:193], v[22:25]
	v_mfma_i32_16x16x64_i8 v[38:41], v[154:157], v[162:165], v[50:53]
	v_mfma_i32_16x16x64_i8 v[2:5], v[154:157], v[170:173], v[2:5]
	v_mfma_i32_16x16x64_i8 v[10:13], v[130:133], v[170:173], v[10:13]
	v_mfma_i32_16x16x64_i8 v[50:53], v[130:133], v[178:181], v[82:85]
	v_mfma_i32_16x16x64_i8 v[34:37], v[130:133], v[162:165], v[114:117]
	v_mfma_i32_16x16x64_i8 v[82:85], v[134:137], v[182:185], v[50:53]
	v_mfma_i32_16x16x64_i8 v[50:53], v[154:157], v[178:181], v[74:77]
	v_mfma_i32_16x16x64_i8 v[2:5], v[158:161], v[174:177], v[2:5]
	v_mfma_i32_16x16x64_i8 v[10:13], v[134:137], v[174:177], v[10:13]
	v_mfma_i32_16x16x64_i8 v[38:41], v[158:161], v[166:169], v[38:41]
	v_mfma_i32_16x16x64_i8 v[34:37], v[134:137], v[166:169], v[34:37]
	v_mfma_i32_16x16x64_i8 v[74:77], v[158:161], v[182:185], v[50:53]
	v_mfma_i32_16x16x64_i8 v[50:53], v[130:133], v[186:189], v[122:125]
	v_mfma_i32_16x16x64_i8 v[122:125], v[134:137], v[190:193], v[50:53]
	v_mfma_i32_16x16x64_i8 v[50:53], v[154:157], v[186:189], v[70:73]
	v_mfma_i32_16x16x64_i8 v[70:73], v[158:161], v[190:193], v[50:53]
	s_barrier
; #define PG8_STAGE(bufoff, gbase, voff) do { _Pragma("unroll") for (int _i = 0; _i < 2; ++_i) \
;         __builtin_amdgcn_global_load_lds((const unsigned*)((const char*)(gbase) + (voff)[_i]), (PG8_LAS unsigned*)(lds + (bufoff) + ldsw + _i * 8192), 16, 0, 0); } while (0)
; #define PG8_LDA(dst, b, h) do { _Pragma("unroll") for (int m = 0; m < 4; ++m) _Pragma("unroll") for (int k = 0; k < 2; ++k) dst[m][k] = *(const PG8_LAS bf16x8*)(lds + PG8_SA(b, h) + aoff + m * 2048 + k * 1024); } while (0)
; #define PG8_LDB(dst, b, h) do { _Pragma("unroll") for (int n = 0; n < 2; ++n) _Pragma("unroll") for (int k = 0; k < 2; ++k) dst[n][k] = *(const PG8_LAS bf16x8*)(lds + PG8_SB(b, h) + boff + n * 2048 + k * 1024); } while (0)
; #define PG8_MMA(ai, bj, At, Bt) do { __builtin_amdgcn_s_setprio(1); _Pragma("unroll") for (int m = 0; m < 4; ++m) _Pragma("unroll") for (int n = 0; n < 2; ++n) _Pragma("unroll") for (int k = 0; k < 2; ++k) \
;         acc[ai][bj][m][n] = mma16<Epi::I8>(Bt[n][k], At[m][k], acc[ai][bj][m][n]); __builtin_amdgcn_s_setprio(0); } while (0)
; #define PG8_WAIT_V(n) asm volatile("s_waitcnt vmcnt(" #n ")" ::: "memory")
; #define PG8_WAIT_L(n) asm volatile("s_waitcnt lgkmcnt(" #n ")" ::: "memory")
; #define PG8_BAR __builtin_amdgcn_s_barrier()
; #define PG8_SCHED __builtin_amdgcn_sched_barrier(0)
; template <class Epi, class Sched, bool ALIGN_EPI = false, bool SP2 = false>
; __device__ __forceinline__ void gemm_phase(PG8_LAS unsigned char* lds, const Gemm g, const Sched& S, const Epi& E) {
;     ...
;             PG8_LDB(B0, 1, 0); PG8_LDB(B1, 1, 1); PG8_SCHED; PG8_LDA(At, 1, 0); PG8_STAGE(PG8_SA(0, 1), a2 + hstep, voffA);
;             PG8_WAIT_V(8); PG8_WAIT_L(0); PG8_BAR; PG8_MMA(0, 0, At, B0); PG8_MMA(0, 1, At, B1); PG8_BAR; PG8_SCHED;
;             PG8_LDA(At, 1, 1); PG8_STAGE(PG8_SB(1, 0), b3, voffB); PG8_STAGE(PG8_SB(1, 1), b3 + hstep, voffB); PG8_STAGE(PG8_SA(1, 0), a3, voffA);
;             PG8_WAIT_V(8); PG8_WAIT_L(0); PG8_BAR; PG8_MMA(1, 0, At, B0); PG8_MMA(1, 1, At, B1); PG8_BAR; PG8_SCHED;
;     ...
;         if constexpr (ALIGN_EPI) { if (wr == 0) PG8_BAR; }
;         if constexpr (!Epi::AFTER_DRAIN) { E(acc, cur, wr, wc, fr, fq); S.done(cur); }
	s_add_i32 s4, 0, 0x18000
	v_add_u32_e32 v126, s4, v242
	s_add_i32 s5, 0, 0x1c000
	ds_read_b128 v[50:53], v126
	ds_read_b128 v[66:69], v126 offset:1024
	ds_read_b128 v[114:117], v126 offset:2048
	ds_read_b128 v[130:133], v126 offset:3072
	v_add_u32_e32 v126, s5, v242
	ds_read_b128 v[134:137], v126
	ds_read_b128 v[154:157], v126 offset:1024
	ds_read_b128 v[158:161], v126 offset:2048
	ds_read_b128 v[162:165], v126 offset:3072
	s_add_u32 s0, s12, 0x40000
	s_addc_u32 s1, s13, 0
	s_mov_b32 m0, s80
	ds_read_b128 v[126:129], v243 offset:32768
	ds_read_b128 v[166:169], v243 offset:33792
	ds_read_b128 v[170:173], v243 offset:34816
	ds_read_b128 v[174:177], v243 offset:35840
	ds_read_b128 v[178:181], v243 offset:36864
	ds_read_b128 v[182:185], v243 offset:37888
	ds_read_b128 v[186:189], v243 offset:38912
	ds_read_b128 v[190:193], v243 offset:39936
	global_load_lds_dwordx4 v210, s[0:1]
	s_mov_b32 m0, s81
	s_nop 0
	global_load_lds_dwordx4 v212, s[0:1]
	s_waitcnt vmcnt(8)
	s_waitcnt lgkmcnt(0)
	s_barrier
	s_waitcnt lgkmcnt(0)
	v_mfma_i32_16x16x64_i8 v[150:153], v[50:53], v[126:129], v[150:153]
	v_mfma_i32_16x16x64_i8 v[146:149], v[114:117], v[126:129], v[146:149]
	v_mfma_i32_16x16x64_i8 v[110:113], v[114:117], v[170:173], v[110:113]
	v_mfma_i32_16x16x64_i8 v[118:121], v[50:53], v[170:173], v[118:121]
	v_mfma_i32_16x16x64_i8 v[54:57], v[50:53], v[178:181], v[54:57]
	v_mfma_i32_16x16x64_i8 v[30:33], v[114:117], v[178:181], v[30:33]
	v_mfma_i32_16x16x64_i8 v[58:61], v[114:117], v[186:189], v[58:61]
	v_mfma_i32_16x16x64_i8 v[94:97], v[50:53], v[186:189], v[94:97]
	v_mfma_i32_16x16x64_i8 v[150:153], v[66:69], v[166:169], v[150:153]
	v_mfma_i32_16x16x64_i8 v[146:149], v[130:133], v[166:169], v[146:149]
	v_mfma_i32_16x16x64_i8 v[110:113], v[130:133], v[174:177], v[110:113]
	v_mfma_i32_16x16x64_i8 v[118:121], v[66:69], v[174:177], v[118:121]
	v_mfma_i32_16x16x64_i8 v[54:57], v[66:69], v[182:185], v[54:57]
	v_mfma_i32_16x16x64_i8 v[30:33], v[130:133], v[182:185], v[30:33]
	v_mfma_i32_16x16x64_i8 v[58:61], v[130:133], v[190:193], v[58:61]
	v_mfma_i32_16x16x64_i8 v[94:97], v[66:69], v[190:193], v[94:97]
	v_mfma_i32_16x16x64_i8 v[142:145], v[134:137], v[126:129], v[142:145]
	v_mfma_i32_16x16x64_i8 v[126:129], v[158:161], v[126:129], v[138:141]
	v_mfma_i32_16x16x64_i8 v[98:101], v[158:161], v[170:173], v[98:101]
	v_mfma_i32_16x16x64_i8 v[102:105], v[134:137], v[170:173], v[102:105]
	v_mfma_i32_16x16x64_i8 v[42:45], v[134:137], v[178:181], v[42:45]
	v_mfma_i32_16x16x64_i8 v[26:29], v[158:161], v[178:181], v[26:29]
	v_mfma_i32_16x16x64_i8 v[62:65], v[158:161], v[186:189], v[62:65]
	v_mfma_i32_16x16x64_i8 v[78:81], v[134:137], v[186:189], v[78:81]
	v_mfma_i32_16x16x64_i8 v[142:145], v[154:157], v[166:169], v[142:145]
	v_mfma_i32_16x16x64_i8 v[138:141], v[162:165], v[166:169], v[126:129]
	v_mfma_i32_16x16x64_i8 v[98:101], v[162:165], v[174:177], v[98:101]
	v_mfma_i32_16x16x64_i8 v[102:105], v[154:157], v[174:177], v[102:105]
	v_mfma_i32_16x16x64_i8 v[42:45], v[154:157], v[182:185], v[42:45]
	v_mfma_i32_16x16x64_i8 v[26:29], v[162:165], v[182:185], v[26:29]
	v_mfma_i32_16x16x64_i8 v[62:65], v[162:165], v[190:193], v[62:65]
	v_mfma_i32_16x16x64_i8 v[78:81], v[154:157], v[190:193], v[78:81]
	s_barrier
	s_add_i32 s0, s4, s69
	v_lshl_add_u64 v[126:127], v[198:199], 0, s[92:93]
	s_mov_b32 m0, s0
	ds_read_b128 v[166:169], v243 offset:49152
	ds_read_b128 v[170:173], v243 offset:50176
	ds_read_b128 v[174:177], v243 offset:51200
	ds_read_b128 v[178:181], v243 offset:52224
	ds_read_b128 v[182:185], v243 offset:53248
	ds_read_b128 v[186:189], v243 offset:54272
	ds_read_b128 v[190:193], v243 offset:55296
	ds_read_b128 v[194:197], v243 offset:56320
	global_load_lds_dwordx4 v[126:127], off
	s_add_i32 m0, s0, 0x2000
	s_add_u32 s0, s6, 0x40080
	v_lshl_add_u64 v[126:127], v[200:201], 0, s[92:93]
	s_addc_u32 s1, s7, 0
	s_add_i32 s4, s5, s69
	global_load_lds_dwordx4 v[126:127], off
	s_mov_b32 m0, s4
	s_nop 0
	global_load_lds_dwordx4 v0, s[0:1]
	s_add_i32 m0, s4, 0x2000
	s_nop 0
	global_load_lds_dwordx4 v214, s[0:1]
	v_lshl_add_u64 v[126:127], v[206:207], 0, s[92:93]
	s_mov_b32 m0, s84
	s_nop 0
	global_load_lds_dwordx4 v[126:127], off
	v_lshl_add_u64 v[126:127], v[220:221], 0, s[92:93]
	s_mov_b32 m0, s85
	s_nop 0
	global_load_lds_dwordx4 v[126:127], off
	s_waitcnt vmcnt(8)
	s_waitcnt lgkmcnt(0)
	s_barrier
	s_waitcnt lgkmcnt(0)
	v_mfma_i32_16x16x64_i8 v[18:21], v[50:53], v[190:193], v[18:21]
	v_mfma_i32_16x16x64_i8 v[106:109], v[50:53], v[166:169], v[106:109]
	v_mfma_i32_16x16x64_i8 v[46:49], v[114:117], v[166:169], v[46:49]
	v_mfma_i32_16x16x64_i8 v[6:9], v[114:117], v[174:177], v[6:9]
	v_mfma_i32_16x16x64_i8 v[14:17], v[50:53], v[174:177], v[14:17]
	v_mfma_i32_16x16x64_i8 v[90:93], v[50:53], v[182:185], v[90:93]
	v_mfma_i32_16x16x64_i8 v[86:89], v[114:117], v[182:185], v[86:89]
	v_mfma_i32_16x16x64_i8 v[126:129], v[66:69], v[194:197], v[18:21]
	v_mfma_i32_16x16x64_i8 v[106:109], v[66:69], v[170:173], v[106:109]
	v_mfma_i32_16x16x64_i8 v[46:49], v[130:133], v[170:173], v[46:49]
	v_mfma_i32_16x16x64_i8 v[6:9], v[130:133], v[178:181], v[6:9]
	v_mfma_i32_16x16x64_i8 v[14:17], v[66:69], v[178:181], v[14:17]
	v_mfma_i32_16x16x64_i8 v[90:93], v[66:69], v[186:189], v[90:93]
	v_mfma_i32_16x16x64_i8 v[86:89], v[130:133], v[186:189], v[86:89]
	v_mfma_i32_16x16x64_i8 v[18:21], v[114:117], v[190:193], v[22:25]
	v_mfma_i32_16x16x64_i8 v[66:69], v[130:133], v[194:197], v[18:21]
	v_mfma_i32_16x16x64_i8 v[18:21], v[134:137], v[166:169], v[34:37]
	v_mfma_i32_16x16x64_i8 v[10:13], v[134:137], v[174:177], v[10:13]
	v_mfma_i32_16x16x64_i8 v[2:5], v[158:161], v[174:177], v[2:5]
	v_mfma_i32_16x16x64_i8 v[114:117], v[154:157], v[170:173], v[18:21]
	v_mfma_i32_16x16x64_i8 v[18:21], v[158:161], v[166:169], v[38:41]
	v_mfma_i32_16x16x64_i8 v[50:53], v[162:165], v[170:173], v[18:21]
	v_mfma_i32_16x16x64_i8 v[18:21], v[134:137], v[182:185], v[82:85]
	v_mfma_i32_16x16x64_i8 v[10:13], v[154:157], v[178:181], v[10:13]
	v_mfma_i32_16x16x64_i8 v[2:5], v[162:165], v[178:181], v[2:5]
	v_mfma_i32_16x16x64_i8 v[82:85], v[154:157], v[186:189], v[18:21]
	v_mfma_i32_16x16x64_i8 v[18:21], v[158:161], v[182:185], v[74:77]
	v_mfma_i32_16x16x64_i8 v[74:77], v[162:165], v[186:189], v[18:21]
	v_mfma_i32_16x16x64_i8 v[18:21], v[134:137], v[190:193], v[122:125]
	v_mfma_i32_16x16x64_i8 v[122:125], v[154:157], v[194:197], v[18:21]
	v_mfma_i32_16x16x64_i8 v[18:21], v[158:161], v[190:193], v[70:73]
	v_mfma_i32_16x16x64_i8 v[70:73], v[162:165], v[194:197], v[18:21]
	s_barrier
	s_add_i32 vcc_lo, vcc_lo, 2
	s_add_u32 s96, s96, 0x100
	s_addc_u32 s97, s97, 0
	s_cmp_gt_u32 vcc_lo, 13
	s_mov_b64 s[0:1], s[8:9]
	s_cbranch_scc0 .LBB0_80
.Lpeelx80:
	s_setprio 0
	v_readlane_b32 s0, v254, 44
	v_readlane_b32 s1, v254, 45
	s_and_b64 vcc, exec, s[0:1]
	s_cbranch_vccz .LBB0_83
	s_barrier

; #define PG8_STAGE(bufoff, gbase, voff) do { _Pragma("unroll") for (int _i = 0; _i < 2; ++_i) \
;         __builtin_amdgcn_global_load_lds((const unsigned*)((const char*)(gbase) + (voff)[_i]), (PG8_LAS unsigned*)(lds + (bufoff) + ldsw + _i * 8192), 16, 0, 0); } while (0)
; #define PG8_LDA(dst, b, h) do { _Pragma("unroll") for (int m = 0; m < 4; ++m) _Pragma("unroll") for (int k = 0; k < 2; ++k) dst[m][k] = *(const PG8_LAS bf16x8*)(lds + PG8_SA(b, h) + aoff + m * 2048 + k * 1024); } while (0)
; #define PG8_LDB(dst, b, h) do { _Pragma("unroll") for (int n = 0; n < 2; ++n) _Pragma("unroll") for (int k = 0; k < 2; ++k) dst[n][k] = *(const PG8_LAS bf16x8*)(lds + PG8_SB(b, h) + boff + n * 2048 + k * 1024); } while (0)
; #define PG8_MMA(ai, bj, At, Bt) do { __builtin_amdgcn_s_setprio(1); _Pragma("unroll") for (int m = 0; m < 4; ++m) _Pragma("unroll") for (int n = 0; n < 2; ++n) _Pragma("unroll") for (int k = 0; k < 2; ++k) \
;         acc[ai][bj][m][n] = mma16<Epi::I8>(Bt[n][k], At[m][k], acc[ai][bj][m][n]); __builtin_amdgcn_s_setprio(0); } while (0)
; #define PG8_WAIT_V(n) asm volatile("s_waitcnt vmcnt(" #n ")" ::: "memory")
; #define PG8_WAIT_L(n) asm volatile("s_waitcnt lgkmcnt(" #n ")" ::: "memory")
; #define PG8_BAR __builtin_amdgcn_s_barrier()
; #define PG8_SCHED __builtin_amdgcn_sched_barrier(0)
; template <class Epi, class Sched, bool ALIGN_EPI = false, bool SP2 = false>
; __device__ __forceinline__ void gemm_phase(PG8_LAS unsigned char* lds, const Gemm g, const Sched& S, const Epi& E) {
;     ...
;             PG8_LDB(B0, 0, 0); PG8_LDB(B1, 0, 1); PG8_SCHED; PG8_LDA(At, 0, 0); PG8_STAGE(PG8_SA(1, 1), a1 + hstep, voffA);
;             PG8_WAIT_V(8); PG8_WAIT_L(0); PG8_BAR; PG8_MMA(0, 0, At, B0); PG8_MMA(0, 1, At, B1); PG8_BAR; PG8_SCHED;
;             PG8_LDA(At, 0, 1); PG8_STAGE(PG8_SB(0, 0), b2, voffB); PG8_STAGE(PG8_SB(0, 1), b2 + hstep, voffB); PG8_STAGE(PG8_SA(0, 0), a2, voffA);
;             PG8_WAIT_V(8); PG8_WAIT_L(0); PG8_BAR; PG8_MMA(1, 0, At, B0); PG8_MMA(1, 1, At, B1); PG8_BAR; PG8_SCHED;
.Lprio175:
	s_add_i32 vcc_lo, s8, 2
	s_add_u32 s4, s6, 0x80
	s_addc_u32 s5, s7, 0
	s_add_i32 vcc_hi, 0, 0x10000
	s_cmp_eq_u32 s13, s8
	s_cselect_b32 s9, s1, s5
	s_cselect_b32 s8, s0, s4
	s_cselect_b32 s5, s97, s85
	s_cselect_b32 s4, s96, s67
	s_add_i32 s84, 0, 0x14000
	v_add_u32_e32 v122, vcc_hi, v248
	v_add_u32_e32 v154, s84, v248
	ds_read_b128 v[98:101], v122
	ds_read_b128 v[102:105], v122 offset:1024
	ds_read_b128 v[114:117], v122 offset:2048
	ds_read_b128 v[122:125], v122 offset:3072
	ds_read_b128 v[130:133], v154
	ds_read_b128 v[138:141], v154 offset:1024
	ds_read_b128 v[146:149], v154 offset:2048
	ds_read_b128 v[154:157], v154 offset:3072
	v_lshl_add_u64 v[206:207], s[6:7], 0, v[200:201]
	s_add_i32 m0, s81, 0xc000
	ds_read_b128 v[162:165], v249
	ds_read_b128 v[166:169], v249 offset:1024
	ds_read_b128 v[170:173], v249 offset:2048
	ds_read_b128 v[174:177], v249 offset:3072
	ds_read_b128 v[178:181], v249 offset:4096
	ds_read_b128 v[182:185], v249 offset:5120
	ds_read_b128 v[186:189], v249 offset:6144
	ds_read_b128 v[190:193], v249 offset:7168
	global_load_lds_dwordx4 v[206:207], off
	v_lshl_add_u64 v[206:207], s[6:7], 0, v[210:211]
	s_add_i32 m0, s81, 0xe000
	s_nop 0
	global_load_lds_dwordx4 v[206:207], off
	s_waitcnt vmcnt(8)
	s_waitcnt lgkmcnt(0)
	s_barrier
	s_waitcnt lgkmcnt(0)
	v_mfma_f32_16x16x32_bf16 v[158:161], v[98:101], v[162:165], 0
	v_mfma_f32_16x16x32_bf16 v[150:153], v[114:117], v[162:165], 0
	v_mfma_f32_16x16x32_bf16 v[118:121], v[114:117], v[170:173], 0
	v_mfma_f32_16x16x32_bf16 v[126:129], v[98:101], v[170:173], 0
	v_mfma_f32_16x16x32_bf16 v[94:97], v[98:101], v[178:181], 0
	v_mfma_f32_16x16x32_bf16 v[90:93], v[114:117], v[178:181], 0
	v_mfma_f32_16x16x32_bf16 v[74:77], v[114:117], v[186:189], 0
	v_mfma_f32_16x16x32_bf16 v[78:81], v[98:101], v[186:189], 0
	v_mfma_f32_16x16x32_bf16 v[158:161], v[102:105], v[166:169], v[158:161]
	v_mfma_f32_16x16x32_bf16 v[150:153], v[122:125], v[166:169], v[150:153]
	v_mfma_f32_16x16x32_bf16 v[118:121], v[122:125], v[174:177], v[118:121]
	v_mfma_f32_16x16x32_bf16 v[126:129], v[102:105], v[174:177], v[126:129]
	v_mfma_f32_16x16x32_bf16 v[94:97], v[102:105], v[182:185], v[94:97]
	v_mfma_f32_16x16x32_bf16 v[90:93], v[122:125], v[182:185], v[90:93]
	v_mfma_f32_16x16x32_bf16 v[74:77], v[122:125], v[190:193], v[74:77]
	v_mfma_f32_16x16x32_bf16 v[78:81], v[102:105], v[190:193], v[78:81]
	v_mfma_f32_16x16x32_bf16 v[142:145], v[130:133], v[162:165], 0
	v_mfma_f32_16x16x32_bf16 v[134:137], v[146:149], v[162:165], 0
	v_mfma_f32_16x16x32_bf16 v[106:109], v[146:149], v[170:173], 0
	v_mfma_f32_16x16x32_bf16 v[110:113], v[130:133], v[170:173], 0
	v_mfma_f32_16x16x32_bf16 v[86:89], v[130:133], v[178:181], 0
	v_mfma_f32_16x16x32_bf16 v[82:85], v[146:149], v[178:181], 0
	v_mfma_f32_16x16x32_bf16 v[66:69], v[146:149], v[186:189], 0
	v_mfma_f32_16x16x32_bf16 v[70:73], v[130:133], v[186:189], 0
	v_mfma_f32_16x16x32_bf16 v[142:145], v[138:141], v[166:169], v[142:145]
	v_mfma_f32_16x16x32_bf16 v[134:137], v[154:157], v[166:169], v[134:137]
	v_mfma_f32_16x16x32_bf16 v[106:109], v[154:157], v[174:177], v[106:109]
	v_mfma_f32_16x16x32_bf16 v[110:113], v[138:141], v[174:177], v[110:113]
	v_mfma_f32_16x16x32_bf16 v[86:89], v[138:141], v[182:185], v[86:89]
	v_mfma_f32_16x16x32_bf16 v[82:85], v[154:157], v[182:185], v[82:85]
	v_mfma_f32_16x16x32_bf16 v[66:69], v[154:157], v[190:193], v[66:69]
	v_mfma_f32_16x16x32_bf16 v[70:73], v[138:141], v[190:193], v[70:73]
	s_barrier
	s_add_i32 vcc_hi, vcc_hi, s80
	v_lshl_add_u64 v[206:207], s[4:5], 0, v[0:1]
	s_mov_b32 m0, vcc_hi
	ds_read_b128 v[162:165], v249 offset:16384
	ds_read_b128 v[166:169], v249 offset:17408
	ds_read_b128 v[170:173], v249 offset:18432
	ds_read_b128 v[174:177], v249 offset:19456
	ds_read_b128 v[178:181], v249 offset:20480
	ds_read_b128 v[182:185], v249 offset:21504
	ds_read_b128 v[186:189], v249 offset:22528
	ds_read_b128 v[190:193], v249 offset:23552
	global_load_lds_dwordx4 v[206:207], off
	s_add_i32 m0, vcc_hi, 0x2000
	v_lshl_add_u64 v[212:213], s[4:5], 0, v[198:199]
	s_add_u32 s4, s4, s58
	s_addc_u32 s5, s5, 0
	s_add_i32 s84, s84, s80
	global_load_lds_dwordx4 v[212:213], off
	v_lshl_add_u64 v[214:215], s[4:5], 0, v[0:1]
	s_mov_b32 m0, s84
	v_lshl_add_u64 v[216:217], s[4:5], 0, v[198:199]
	global_load_lds_dwordx4 v[214:215], off
	s_add_i32 m0, s84, 0x2000
	v_lshl_add_u64 v[218:219], s[8:9], 0, v[194:195]
	global_load_lds_dwordx4 v[216:217], off
	s_mov_b32 m0, s81
	v_lshl_add_u64 v[220:221], s[8:9], 0, v[196:197]
	global_load_lds_dwordx4 v[218:219], off
	s_mov_b32 m0, s70
	s_nop 0
	global_load_lds_dwordx4 v[220:221], off
	s_waitcnt vmcnt(8)
	s_waitcnt lgkmcnt(0)
	s_barrier
; #define PG8_STAGE(bufoff, gbase, voff) do { _Pragma("unroll") for (int _i = 0; _i < 2; ++_i) \
;         __builtin_amdgcn_global_load_lds((const unsigned*)((const char*)(gbase) + (voff)[_i]), (PG8_LAS unsigned*)(lds + (bufoff) + ldsw + _i * 8192), 16, 0, 0); } while (0)
; #define PG8_LDA(dst, b, h) do { _Pragma("unroll") for (int m = 0; m < 4; ++m) _Pragma("unroll") for (int k = 0; k < 2; ++k) dst[m][k] = *(const PG8_LAS bf16x8*)(lds + PG8_SA(b, h) + aoff + m * 2048 + k * 1024); } while (0)
; #define PG8_LDB(dst, b, h) do { _Pragma("unroll") for (int n = 0; n < 2; ++n) _Pragma("unroll") for (int k = 0; k < 2; ++k) dst[n][k] = *(const PG8_LAS bf16x8*)(lds + PG8_SB(b, h) + boff + n * 2048 + k * 1024); } while (0)
; #define PG8_MMA(ai, bj, At, Bt) do { __builtin_amdgcn_s_setprio(1); _Pragma("unroll") for (int m = 0; m < 4; ++m) _Pragma("unroll") for (int n = 0; n < 2; ++n) _Pragma("unroll") for (int k = 0; k < 2; ++k) \
;         acc[ai][bj][m][n] = mma16<Epi::I8>(Bt[n][k], At[m][k], acc[ai][bj][m][n]); __builtin_amdgcn_s_setprio(0); } while (0)
; #define PG8_WAIT_V(n) asm volatile("s_waitcnt vmcnt(" #n ")" ::: "memory")
; #define PG8_WAIT_L(n) asm volatile("s_waitcnt lgkmcnt(" #n ")" ::: "memory")
; #define PG8_BAR __builtin_amdgcn_s_barrier()
; #define PG8_SCHED __builtin_amdgcn_sched_barrier(0)
; template <class Epi, class Sched, bool ALIGN_EPI = false, bool SP2 = false>
; __device__ __forceinline__ void gemm_phase(PG8_LAS unsigned char* lds, const Gemm g, const Sched& S, const Epi& E) {
;     ...
;             PG8_WAIT_V(8); PG8_WAIT_L(0); PG8_BAR; PG8_MMA(0, 0, At, B0); PG8_MMA(0, 1, At, B1); PG8_BAR; PG8_SCHED;
;             PG8_LDA(At, 0, 1); PG8_STAGE(PG8_SB(0, 0), b2, voffB); PG8_STAGE(PG8_SB(0, 1), b2 + hstep, voffB); PG8_STAGE(PG8_SA(0, 0), a2, voffA);
;             PG8_WAIT_V(8); PG8_WAIT_L(0); PG8_BAR; PG8_MMA(1, 0, At, B0); PG8_MMA(1, 1, At, B1); PG8_BAR; PG8_SCHED;
;             PG8_LDB(B0, 1, 0); PG8_LDB(B1, 1, 1); PG8_SCHED; PG8_LDA(At, 1, 0); PG8_STAGE(PG8_SA(0, 1), a2 + hstep, voffA);
;             PG8_WAIT_V(8); PG8_WAIT_L(0); PG8_BAR; PG8_MMA(0, 0, At, B0); PG8_MMA(0, 1, At, B1); PG8_BAR; PG8_SCHED;
	s_waitcnt lgkmcnt(0)
	v_mfma_f32_16x16x32_bf16 v[62:65], v[98:101], v[162:165], 0
	v_mfma_f32_16x16x32_bf16 v[58:61], v[114:117], v[162:165], 0
	v_mfma_f32_16x16x32_bf16 v[42:45], v[114:117], v[170:173], 0
	v_mfma_f32_16x16x32_bf16 v[46:49], v[98:101], v[170:173], 0
	v_mfma_f32_16x16x32_bf16 v[30:33], v[98:101], v[178:181], 0
	v_mfma_f32_16x16x32_bf16 v[26:29], v[114:117], v[178:181], 0
	v_mfma_f32_16x16x32_bf16 v[10:13], v[114:117], v[186:189], 0
	v_mfma_f32_16x16x32_bf16 v[14:17], v[98:101], v[186:189], 0
	v_mfma_f32_16x16x32_bf16 v[62:65], v[102:105], v[166:169], v[62:65]
	v_mfma_f32_16x16x32_bf16 v[58:61], v[122:125], v[166:169], v[58:61]
	v_mfma_f32_16x16x32_bf16 v[42:45], v[122:125], v[174:177], v[42:45]
	v_mfma_f32_16x16x32_bf16 v[46:49], v[102:105], v[174:177], v[46:49]
	v_mfma_f32_16x16x32_bf16 v[30:33], v[102:105], v[182:185], v[30:33]
	v_mfma_f32_16x16x32_bf16 v[26:29], v[122:125], v[182:185], v[26:29]
	v_mfma_f32_16x16x32_bf16 v[10:13], v[122:125], v[190:193], v[10:13]
	v_mfma_f32_16x16x32_bf16 v[14:17], v[102:105], v[190:193], v[14:17]
	v_mfma_f32_16x16x32_bf16 v[54:57], v[130:133], v[162:165], 0
	v_mfma_f32_16x16x32_bf16 v[50:53], v[146:149], v[162:165], 0
	v_mfma_f32_16x16x32_bf16 v[34:37], v[146:149], v[170:173], 0
	v_mfma_f32_16x16x32_bf16 v[38:41], v[130:133], v[170:173], 0
	v_mfma_f32_16x16x32_bf16 v[22:25], v[130:133], v[178:181], 0
	v_mfma_f32_16x16x32_bf16 v[18:21], v[146:149], v[178:181], 0
	v_mfma_f32_16x16x32_bf16 v[2:5], v[146:149], v[186:189], 0
	v_mfma_f32_16x16x32_bf16 v[6:9], v[130:133], v[186:189], 0
	v_mfma_f32_16x16x32_bf16 v[54:57], v[138:141], v[166:169], v[54:57]
	v_mfma_f32_16x16x32_bf16 v[50:53], v[154:157], v[166:169], v[50:53]
	v_mfma_f32_16x16x32_bf16 v[34:37], v[154:157], v[174:177], v[34:37]
	v_mfma_f32_16x16x32_bf16 v[38:41], v[138:141], v[174:177], v[38:41]
	v_mfma_f32_16x16x32_bf16 v[22:25], v[138:141], v[182:185], v[22:25]
	v_mfma_f32_16x16x32_bf16 v[18:21], v[154:157], v[182:185], v[18:21]
	v_mfma_f32_16x16x32_bf16 v[2:5], v[154:157], v[190:193], v[2:5]
	v_mfma_f32_16x16x32_bf16 v[6:9], v[138:141], v[190:193], v[6:9]
	s_barrier
	s_add_i32 s84, 0, 0x18000
	s_add_i32 vcc_hi, 0, 0x1c000
	v_add_u32_e32 v122, s84, v248
	v_add_u32_e32 v154, vcc_hi, v248
	ds_read_b128 v[98:101], v122
	ds_read_b128 v[102:105], v122 offset:1024
	ds_read_b128 v[114:117], v122 offset:2048
	ds_read_b128 v[122:125], v122 offset:3072
	ds_read_b128 v[130:133], v154
	ds_read_b128 v[138:141], v154 offset:1024
	ds_read_b128 v[146:149], v154 offset:2048
	ds_read_b128 v[154:157], v154 offset:3072
	s_add_u32 s4, s8, s58
	s_addc_u32 s5, s9, 0
	s_mov_b32 m0, s71
	v_lshl_add_u64 v[222:223], s[4:5], 0, v[194:195]
	ds_read_b128 v[162:165], v249 offset:32768
	ds_read_b128 v[166:169], v249 offset:33792
	ds_read_b128 v[170:173], v249 offset:34816
	ds_read_b128 v[174:177], v249 offset:35840
	ds_read_b128 v[178:181], v249 offset:36864
	ds_read_b128 v[182:185], v249 offset:37888
	ds_read_b128 v[186:189], v249 offset:38912
	ds_read_b128 v[190:193], v249 offset:39936
	global_load_lds_dwordx4 v[222:223], off
	v_lshl_add_u64 v[222:223], s[4:5], 0, v[196:197]
	s_mov_b32 m0, s12
	s_nop 0
	global_load_lds_dwordx4 v[222:223], off
	s_waitcnt vmcnt(8)
	s_waitcnt lgkmcnt(0)
	s_barrier
	s_waitcnt lgkmcnt(0)
	v_mfma_f32_16x16x32_bf16 v[158:161], v[98:101], v[162:165], v[158:161]
	v_mfma_f32_16x16x32_bf16 v[150:153], v[114:117], v[162:165], v[150:153]
	v_mfma_f32_16x16x32_bf16 v[118:121], v[114:117], v[170:173], v[118:121]
	v_mfma_f32_16x16x32_bf16 v[126:129], v[98:101], v[170:173], v[126:129]
	v_mfma_f32_16x16x32_bf16 v[94:97], v[98:101], v[178:181], v[94:97]
	v_mfma_f32_16x16x32_bf16 v[90:93], v[114:117], v[178:181], v[90:93]
	v_mfma_f32_16x16x32_bf16 v[74:77], v[114:117], v[186:189], v[74:77]
	v_mfma_f32_16x16x32_bf16 v[78:81], v[98:101], v[186:189], v[78:81]
	v_mfma_f32_16x16x32_bf16 v[158:161], v[102:105], v[166:169], v[158:161]
	v_mfma_f32_16x16x32_bf16 v[150:153], v[122:125], v[166:169], v[150:153]
	v_mfma_f32_16x16x32_bf16 v[118:121], v[122:125], v[174:177], v[118:121]
	v_mfma_f32_16x16x32_bf16 v[126:129], v[102:105], v[174:177], v[126:129]
	v_mfma_f32_16x16x32_bf16 v[94:97], v[102:105], v[182:185], v[94:97]
	v_mfma_f32_16x16x32_bf16 v[90:93], v[122:125], v[182:185], v[90:93]
	v_mfma_f32_16x16x32_bf16 v[74:77], v[122:125], v[190:193], v[74:77]
	v_mfma_f32_16x16x32_bf16 v[78:81], v[102:105], v[190:193], v[78:81]
	v_mfma_f32_16x16x32_bf16 v[142:145], v[130:133], v[162:165], v[142:145]
	v_mfma_f32_16x16x32_bf16 v[134:137], v[146:149], v[162:165], v[134:137]
	v_mfma_f32_16x16x32_bf16 v[106:109], v[146:149], v[170:173], v[106:109]
	v_mfma_f32_16x16x32_bf16 v[110:113], v[130:133], v[170:173], v[110:113]
	v_mfma_f32_16x16x32_bf16 v[86:89], v[130:133], v[178:181], v[86:89]
	v_mfma_f32_16x16x32_bf16 v[82:85], v[146:149], v[178:181], v[82:85]
	v_mfma_f32_16x16x32_bf16 v[66:69], v[146:149], v[186:189], v[66:69]
	v_mfma_f32_16x16x32_bf16 v[70:73], v[130:133], v[186:189], v[70:73]
	v_mfma_f32_16x16x32_bf16 v[142:145], v[138:141], v[166:169], v[142:145]
	v_mfma_f32_16x16x32_bf16 v[134:137], v[154:157], v[166:169], v[134:137]
	v_mfma_f32_16x16x32_bf16 v[106:109], v[154:157], v[174:177], v[106:109]
	v_mfma_f32_16x16x32_bf16 v[110:113], v[138:141], v[174:177], v[110:113]
	v_mfma_f32_16x16x32_bf16 v[86:89], v[138:141], v[182:185], v[86:89]
	v_mfma_f32_16x16x32_bf16 v[82:85], v[154:157], v[182:185], v[82:85]
	v_mfma_f32_16x16x32_bf16 v[66:69], v[154:157], v[190:193], v[66:69]
	v_mfma_f32_16x16x32_bf16 v[70:73], v[138:141], v[190:193], v[70:73]
	s_barrier
; #define PG8_STAGE(bufoff, gbase, voff) do { _Pragma("unroll") for (int _i = 0; _i < 2; ++_i) \
;         __builtin_amdgcn_global_load_lds((const unsigned*)((const char*)(gbase) + (voff)[_i]), (PG8_LAS unsigned*)(lds + (bufoff) + ldsw + _i * 8192), 16, 0, 0); } while (0)
; #define PG8_LDA(dst, b, h) do { _Pragma("unroll") for (int m = 0; m < 4; ++m) _Pragma("unroll") for (int k = 0; k < 2; ++k) dst[m][k] = *(const PG8_LAS bf16x8*)(lds + PG8_SA(b, h) + aoff + m * 2048 + k * 1024); } while (0)
; #define PG8_LDB(dst, b, h) do { _Pragma("unroll") for (int n = 0; n < 2; ++n) _Pragma("unroll") for (int k = 0; k < 2; ++k) dst[n][k] = *(const PG8_LAS bf16x8*)(lds + PG8_SB(b, h) + boff + n * 2048 + k * 1024); } while (0)
; template <class Epi, class Sched, bool ALIGN_EPI = false, bool SP2 = false>
; __device__ __forceinline__ void gemm_phase(PG8_LAS unsigned char* lds, const Gemm g, const Sched& S, const Epi& E) {
;     ...
;         for (int t = 0; t < nt; t += 2) {
;             const bool last = (t == nt - 2);
;             const char* a1 = cA + (size_t)(t + 1) * kstep;
;             const char* a2 = last ? nA : cA + (size_t)(t + 2) * kstep; const char* b2 = last ? nB : cB + (size_t)(t + 2) * kstep;
;             const char* a3 = a2 + kstep; const char* b3 = b2 + kstep;
;             if (last && has_next) S.a_ready(nxt);
;             if constexpr (SP2) {
;             PG8_LDB(B0, 0, 0); PG8_LDB(B1, 0, 1); PG8_SCHED; PG8_LDA(At, 0, 0); PG8_STAGE(PG8_SA(1, 1), a1 + hstep, voffA);
;             PG8_WAIT_V(8); PG8_WAIT_L(0); PG8_BAR; PG8_MMA(0, 0, At, B0); PG8_MMA(0, 1, At, B1); PG8_BAR; PG8_SCHED;
;             PG8_LDA(At, 0, 1); PG8_STAGE(PG8_SB(0, 0), b2, voffB); PG8_STAGE(PG8_SB(0, 1), b2 + hstep, voffB); PG8_STAGE(PG8_SA(0, 0), a2, voffA);
;             PG8_WAIT_V(8); PG8_WAIT_L(0); PG8_BAR; PG8_MMA(1, 0, At, B0); PG8_MMA(1, 1, At, B1); PG8_BAR; PG8_SCHED;
;             PG8_LDB(B0, 1, 0); PG8_LDB(B1, 1, 1); PG8_SCHED; PG8_LDA(At, 1, 0); PG8_STAGE(PG8_SA(0, 1), a2 + hstep, voffA);
;             PG8_WAIT_V(8); PG8_WAIT_L(0); PG8_BAR; PG8_MMA(0, 0, At, B0); PG8_MMA(0, 1, At, B1); PG8_BAR; PG8_SCHED;
;             PG8_LDA(At, 1, 1); PG8_STAGE(PG8_SB(1, 0), b3, voffB); PG8_STAGE(PG8_SB(1, 1), b3 + hstep, voffB); PG8_STAGE(PG8_SA(1, 0), a3, voffA);
;             PG8_WAIT_V(8); PG8_WAIT_L(0); PG8_BAR; PG8_MMA(1, 0, At, B0); PG8_MMA(1, 1, At, B1); PG8_BAR; PG8_SCHED;
	s_add_i32 s4, s84, s80
	v_lshl_add_u64 v[206:207], v[206:207], 0, s[92:93]
	s_mov_b32 m0, s4
	ds_read_b128 v[162:165], v249 offset:49152
	ds_read_b128 v[166:169], v249 offset:50176
	ds_read_b128 v[170:173], v249 offset:51200
	ds_read_b128 v[174:177], v249 offset:52224
	ds_read_b128 v[178:181], v249 offset:53248
	ds_read_b128 v[182:185], v249 offset:54272
	ds_read_b128 v[186:189], v249 offset:55296
	ds_read_b128 v[190:193], v249 offset:56320
	global_load_lds_dwordx4 v[206:207], off
	v_lshl_add_u64 v[206:207], v[212:213], 0, s[92:93]
	s_add_i32 m0, s4, 0x2000
	s_add_i32 s4, vcc_hi, s80
	global_load_lds_dwordx4 v[206:207], off
	v_lshl_add_u64 v[206:207], v[214:215], 0, s[92:93]
	s_mov_b32 m0, s4
	s_nop 0
	global_load_lds_dwordx4 v[206:207], off
	v_lshl_add_u64 v[206:207], v[216:217], 0, s[92:93]
	s_add_i32 m0, s4, 0x2000
	s_nop 0
	global_load_lds_dwordx4 v[206:207], off
	v_lshl_add_u64 v[206:207], v[218:219], 0, s[92:93]
	s_mov_b32 m0, s10
	s_nop 0
	global_load_lds_dwordx4 v[206:207], off
	v_lshl_add_u64 v[206:207], v[220:221], 0, s[92:93]
	s_mov_b32 m0, s11
	s_nop 0
	global_load_lds_dwordx4 v[206:207], off
	s_waitcnt vmcnt(8)
	s_waitcnt lgkmcnt(0)
	s_barrier
	s_waitcnt lgkmcnt(0)
	v_mfma_f32_16x16x32_bf16 v[62:65], v[98:101], v[162:165], v[62:65]
	v_mfma_f32_16x16x32_bf16 v[58:61], v[114:117], v[162:165], v[58:61]
	v_mfma_f32_16x16x32_bf16 v[42:45], v[114:117], v[170:173], v[42:45]
	v_mfma_f32_16x16x32_bf16 v[46:49], v[98:101], v[170:173], v[46:49]
	v_mfma_f32_16x16x32_bf16 v[30:33], v[98:101], v[178:181], v[30:33]
	v_mfma_f32_16x16x32_bf16 v[26:29], v[114:117], v[178:181], v[26:29]
	v_mfma_f32_16x16x32_bf16 v[10:13], v[114:117], v[186:189], v[10:13]
	v_mfma_f32_16x16x32_bf16 v[14:17], v[98:101], v[186:189], v[14:17]
	v_mfma_f32_16x16x32_bf16 v[62:65], v[102:105], v[166:169], v[62:65]
	v_mfma_f32_16x16x32_bf16 v[58:61], v[122:125], v[166:169], v[58:61]
	v_mfma_f32_16x16x32_bf16 v[42:45], v[122:125], v[174:177], v[42:45]
	v_mfma_f32_16x16x32_bf16 v[46:49], v[102:105], v[174:177], v[46:49]
	v_mfma_f32_16x16x32_bf16 v[30:33], v[102:105], v[182:185], v[30:33]
	v_mfma_f32_16x16x32_bf16 v[26:29], v[122:125], v[182:185], v[26:29]
	v_mfma_f32_16x16x32_bf16 v[10:13], v[122:125], v[190:193], v[10:13]
	v_mfma_f32_16x16x32_bf16 v[14:17], v[102:105], v[190:193], v[14:17]
	v_mfma_f32_16x16x32_bf16 v[54:57], v[130:133], v[162:165], v[54:57]
	v_mfma_f32_16x16x32_bf16 v[50:53], v[146:149], v[162:165], v[50:53]
	v_mfma_f32_16x16x32_bf16 v[34:37], v[146:149], v[170:173], v[34:37]
	v_mfma_f32_16x16x32_bf16 v[38:41], v[130:133], v[170:173], v[38:41]
	v_mfma_f32_16x16x32_bf16 v[22:25], v[130:133], v[178:181], v[22:25]
	v_mfma_f32_16x16x32_bf16 v[18:21], v[146:149], v[178:181], v[18:21]
	v_mfma_f32_16x16x32_bf16 v[2:5], v[146:149], v[186:189], v[2:5]
	v_mfma_f32_16x16x32_bf16 v[6:9], v[130:133], v[186:189], v[6:9]
	v_mfma_f32_16x16x32_bf16 v[54:57], v[138:141], v[166:169], v[54:57]
	v_mfma_f32_16x16x32_bf16 v[50:53], v[154:157], v[166:169], v[50:53]
	v_mfma_f32_16x16x32_bf16 v[34:37], v[154:157], v[174:177], v[34:37]
	v_mfma_f32_16x16x32_bf16 v[38:41], v[138:141], v[174:177], v[38:41]
	v_mfma_f32_16x16x32_bf16 v[22:25], v[138:141], v[182:185], v[22:25]
	v_mfma_f32_16x16x32_bf16 v[18:21], v[154:157], v[182:185], v[18:21]
	v_mfma_f32_16x16x32_bf16 v[2:5], v[154:157], v[190:193], v[2:5]
	v_mfma_f32_16x16x32_bf16 v[6:9], v[138:141], v[190:193], v[6:9]
	s_barrier
	s_add_u32 s6, s6, 0x100
	s_addc_u32 s7, s7, 0
	s_add_u32 s67, s67, 0x100
	s_addc_u32 s85, s85, 0
	s_cmp_ge_u32 vcc_lo, s69
	s_mov_b32 s8, vcc_lo
	s_cbranch_scc0 .LBB0_175
	s_branch .Lpeelx175
.LBB0_175:
	s_add_i32 vcc_lo, s8, 2
	s_add_u32 s4, s6, 0x80
	s_addc_u32 s5, s7, 0
	s_add_i32 vcc_hi, 0, 0x10000
	s_cmp_eq_u32 s13, s8
	s_cselect_b32 s9, s1, s5
	s_cselect_b32 s8, s0, s4
	s_cselect_b32 s5, s97, s85
	s_cselect_b32 s4, s96, s67
	s_add_i32 s84, 0, 0x14000
	v_add_u32_e32 v122, vcc_hi, v248
	v_add_u32_e32 v154, s84, v248
	ds_read_b128 v[98:101], v122
	ds_read_b128 v[102:105], v122 offset:1024
	ds_read_b128 v[114:117], v122 offset:2048
	ds_read_b128 v[122:125], v122 offset:3072
	ds_read_b128 v[130:133], v154
	ds_read_b128 v[138:141], v154 offset:1024
	ds_read_b128 v[146:149], v154 offset:2048
	ds_read_b128 v[154:157], v154 offset:3072
	v_lshl_add_u64 v[206:207], s[6:7], 0, v[200:201]
	s_add_i32 m0, s81, 0xc000
	ds_read_b128 v[162:165], v249
	ds_read_b128 v[166:169], v249 offset:1024
	ds_read_b128 v[170:173], v249 offset:2048
	ds_read_b128 v[174:177], v249 offset:3072
	ds_read_b128 v[178:181], v249 offset:4096
	ds_read_b128 v[182:185], v249 offset:5120
	ds_read_b128 v[186:189], v249 offset:6144
	ds_read_b128 v[190:193], v249 offset:7168
	global_load_lds_dwordx4 v[206:207], off
	v_lshl_add_u64 v[206:207], s[6:7], 0, v[210:211]
	s_add_i32 m0, s81, 0xe000
	s_nop 0
	global_load_lds_dwordx4 v[206:207], off
	s_waitcnt vmcnt(8)
	s_waitcnt lgkmcnt(0)
	s_barrier
; #define PG8_STAGE(bufoff, gbase, voff) do { _Pragma("unroll") for (int _i = 0; _i < 2; ++_i) \
;         __builtin_amdgcn_global_load_lds((const unsigned*)((const char*)(gbase) + (voff)[_i]), (PG8_LAS unsigned*)(lds + (bufoff) + ldsw + _i * 8192), 16, 0, 0); } while (0)
; #define PG8_LDA(dst, b, h) do { _Pragma("unroll") for (int m = 0; m < 4; ++m) _Pragma("unroll") for (int k = 0; k < 2; ++k) dst[m][k] = *(const PG8_LAS bf16x8*)(lds + PG8_SA(b, h) + aoff + m * 2048 + k * 1024); } while (0)
; #define PG8_LDB(dst, b, h) do { _Pragma("unroll") for (int n = 0; n < 2; ++n) _Pragma("unroll") for (int k = 0; k < 2; ++k) dst[n][k] = *(const PG8_LAS bf16x8*)(lds + PG8_SB(b, h) + boff + n * 2048 + k * 1024); } while (0)
; #define PG8_MMA(ai, bj, At, Bt) do { __builtin_amdgcn_s_setprio(1); _Pragma("unroll") for (int m = 0; m < 4; ++m) _Pragma("unroll") for (int n = 0; n < 2; ++n) _Pragma("unroll") for (int k = 0; k < 2; ++k) \
;         acc[ai][bj][m][n] = mma16<Epi::I8>(Bt[n][k], At[m][k], acc[ai][bj][m][n]); __builtin_amdgcn_s_setprio(0); } while (0)
; #define PG8_WAIT_V(n) asm volatile("s_waitcnt vmcnt(" #n ")" ::: "memory")
; #define PG8_WAIT_L(n) asm volatile("s_waitcnt lgkmcnt(" #n ")" ::: "memory")
; #define PG8_BAR __builtin_amdgcn_s_barrier()
; #define PG8_SCHED __builtin_amdgcn_sched_barrier(0)
; template <class Epi, class Sched, bool ALIGN_EPI = false, bool SP2 = false>
; __device__ __forceinline__ void gemm_phase(PG8_LAS unsigned char* lds, const Gemm g, const Sched& S, const Epi& E) {
;     ...
;             PG8_LDB(B0, 0, 0); PG8_LDB(B1, 0, 1); PG8_SCHED; PG8_LDA(At, 0, 0); PG8_STAGE(PG8_SA(1, 1), a1 + hstep, voffA);
;             PG8_WAIT_V(8); PG8_WAIT_L(0); PG8_BAR; PG8_MMA(0, 0, At, B0); PG8_MMA(0, 1, At, B1); PG8_BAR; PG8_SCHED;
;             PG8_LDA(At, 0, 1); PG8_STAGE(PG8_SB(0, 0), b2, voffB); PG8_STAGE(PG8_SB(0, 1), b2 + hstep, voffB); PG8_STAGE(PG8_SA(0, 0), a2, voffA);
;             PG8_WAIT_V(8); PG8_WAIT_L(0); PG8_BAR; PG8_MMA(1, 0, At, B0); PG8_MMA(1, 1, At, B1); PG8_BAR; PG8_SCHED;
	s_waitcnt lgkmcnt(0)
	v_mfma_f32_16x16x32_bf16 v[158:161], v[98:101], v[162:165], v[158:161]
	v_mfma_f32_16x16x32_bf16 v[150:153], v[114:117], v[162:165], v[150:153]
	v_mfma_f32_16x16x32_bf16 v[118:121], v[114:117], v[170:173], v[118:121]
	v_mfma_f32_16x16x32_bf16 v[126:129], v[98:101], v[170:173], v[126:129]
	v_mfma_f32_16x16x32_bf16 v[94:97], v[98:101], v[178:181], v[94:97]
	v_mfma_f32_16x16x32_bf16 v[90:93], v[114:117], v[178:181], v[90:93]
	v_mfma_f32_16x16x32_bf16 v[74:77], v[114:117], v[186:189], v[74:77]
	v_mfma_f32_16x16x32_bf16 v[78:81], v[98:101], v[186:189], v[78:81]
	v_mfma_f32_16x16x32_bf16 v[158:161], v[102:105], v[166:169], v[158:161]
	v_mfma_f32_16x16x32_bf16 v[150:153], v[122:125], v[166:169], v[150:153]
	v_mfma_f32_16x16x32_bf16 v[118:121], v[122:125], v[174:177], v[118:121]
	v_mfma_f32_16x16x32_bf16 v[126:129], v[102:105], v[174:177], v[126:129]
	v_mfma_f32_16x16x32_bf16 v[94:97], v[102:105], v[182:185], v[94:97]
	v_mfma_f32_16x16x32_bf16 v[90:93], v[122:125], v[182:185], v[90:93]
	v_mfma_f32_16x16x32_bf16 v[74:77], v[122:125], v[190:193], v[74:77]
	v_mfma_f32_16x16x32_bf16 v[78:81], v[102:105], v[190:193], v[78:81]
	v_mfma_f32_16x16x32_bf16 v[142:145], v[130:133], v[162:165], v[142:145]
	v_mfma_f32_16x16x32_bf16 v[134:137], v[146:149], v[162:165], v[134:137]
	v_mfma_f32_16x16x32_bf16 v[106:109], v[146:149], v[170:173], v[106:109]
	v_mfma_f32_16x16x32_bf16 v[110:113], v[130:133], v[170:173], v[110:113]
	v_mfma_f32_16x16x32_bf16 v[86:89], v[130:133], v[178:181], v[86:89]
	v_mfma_f32_16x16x32_bf16 v[82:85], v[146:149], v[178:181], v[82:85]
	v_mfma_f32_16x16x32_bf16 v[66:69], v[146:149], v[186:189], v[66:69]
	v_mfma_f32_16x16x32_bf16 v[70:73], v[130:133], v[186:189], v[70:73]
	v_mfma_f32_16x16x32_bf16 v[142:145], v[138:141], v[166:169], v[142:145]
	v_mfma_f32_16x16x32_bf16 v[134:137], v[154:157], v[166:169], v[134:137]
	v_mfma_f32_16x16x32_bf16 v[106:109], v[154:157], v[174:177], v[106:109]
	v_mfma_f32_16x16x32_bf16 v[110:113], v[138:141], v[174:177], v[110:113]
	v_mfma_f32_16x16x32_bf16 v[86:89], v[138:141], v[182:185], v[86:89]
	v_mfma_f32_16x16x32_bf16 v[82:85], v[154:157], v[182:185], v[82:85]
	v_mfma_f32_16x16x32_bf16 v[66:69], v[154:157], v[190:193], v[66:69]
	v_mfma_f32_16x16x32_bf16 v[70:73], v[138:141], v[190:193], v[70:73]
	s_barrier
	s_add_i32 vcc_hi, vcc_hi, s80
	v_lshl_add_u64 v[206:207], s[4:5], 0, v[0:1]
	s_mov_b32 m0, vcc_hi
	ds_read_b128 v[162:165], v249 offset:16384
	ds_read_b128 v[166:169], v249 offset:17408
	ds_read_b128 v[170:173], v249 offset:18432
	ds_read_b128 v[174:177], v249 offset:19456
	ds_read_b128 v[178:181], v249 offset:20480
	ds_read_b128 v[182:185], v249 offset:21504
	ds_read_b128 v[186:189], v249 offset:22528
	ds_read_b128 v[190:193], v249 offset:23552
	global_load_lds_dwordx4 v[206:207], off
	s_add_i32 m0, vcc_hi, 0x2000
	v_lshl_add_u64 v[212:213], s[4:5], 0, v[198:199]
	s_add_u32 s4, s4, s58
	s_addc_u32 s5, s5, 0
	s_add_i32 s84, s84, s80
	global_load_lds_dwordx4 v[212:213], off
	v_lshl_add_u64 v[214:215], s[4:5], 0, v[0:1]
	s_mov_b32 m0, s84
	v_lshl_add_u64 v[216:217], s[4:5], 0, v[198:199]
	global_load_lds_dwordx4 v[214:215], off
	s_add_i32 m0, s84, 0x2000
	v_lshl_add_u64 v[218:219], s[8:9], 0, v[194:195]
	global_load_lds_dwordx4 v[216:217], off
	s_mov_b32 m0, s81
	v_lshl_add_u64 v[220:221], s[8:9], 0, v[196:197]
	global_load_lds_dwordx4 v[218:219], off
	s_mov_b32 m0, s70
	s_nop 0
	global_load_lds_dwordx4 v[220:221], off
	s_waitcnt vmcnt(8)
	s_waitcnt lgkmcnt(0)
	s_barrier
	s_waitcnt lgkmcnt(0)
	v_mfma_f32_16x16x32_bf16 v[62:65], v[98:101], v[162:165], v[62:65]
	v_mfma_f32_16x16x32_bf16 v[58:61], v[114:117], v[162:165], v[58:61]
	v_mfma_f32_16x16x32_bf16 v[42:45], v[114:117], v[170:173], v[42:45]
	v_mfma_f32_16x16x32_bf16 v[46:49], v[98:101], v[170:173], v[46:49]
	v_mfma_f32_16x16x32_bf16 v[30:33], v[98:101], v[178:181], v[30:33]
	v_mfma_f32_16x16x32_bf16 v[26:29], v[114:117], v[178:181], v[26:29]
	v_mfma_f32_16x16x32_bf16 v[10:13], v[114:117], v[186:189], v[10:13]
	v_mfma_f32_16x16x32_bf16 v[14:17], v[98:101], v[186:189], v[14:17]
	v_mfma_f32_16x16x32_bf16 v[62:65], v[102:105], v[166:169], v[62:65]
	v_mfma_f32_16x16x32_bf16 v[58:61], v[122:125], v[166:169], v[58:61]
	v_mfma_f32_16x16x32_bf16 v[42:45], v[122:125], v[174:177], v[42:45]
	v_mfma_f32_16x16x32_bf16 v[46:49], v[102:105], v[174:177], v[46:49]
	v_mfma_f32_16x16x32_bf16 v[30:33], v[102:105], v[182:185], v[30:33]
	v_mfma_f32_16x16x32_bf16 v[26:29], v[122:125], v[182:185], v[26:29]
	v_mfma_f32_16x16x32_bf16 v[10:13], v[122:125], v[190:193], v[10:13]
	v_mfma_f32_16x16x32_bf16 v[14:17], v[102:105], v[190:193], v[14:17]
	v_mfma_f32_16x16x32_bf16 v[54:57], v[130:133], v[162:165], v[54:57]
	v_mfma_f32_16x16x32_bf16 v[50:53], v[146:149], v[162:165], v[50:53]
	v_mfma_f32_16x16x32_bf16 v[34:37], v[146:149], v[170:173], v[34:37]
	v_mfma_f32_16x16x32_bf16 v[38:41], v[130:133], v[170:173], v[38:41]
	v_mfma_f32_16x16x32_bf16 v[22:25], v[130:133], v[178:181], v[22:25]
	v_mfma_f32_16x16x32_bf16 v[18:21], v[146:149], v[178:181], v[18:21]
	v_mfma_f32_16x16x32_bf16 v[2:5], v[146:149], v[186:189], v[2:5]
	v_mfma_f32_16x16x32_bf16 v[6:9], v[130:133], v[186:189], v[6:9]
	v_mfma_f32_16x16x32_bf16 v[54:57], v[138:141], v[166:169], v[54:57]
	v_mfma_f32_16x16x32_bf16 v[50:53], v[154:157], v[166:169], v[50:53]
	v_mfma_f32_16x16x32_bf16 v[34:37], v[154:157], v[174:177], v[34:37]
	v_mfma_f32_16x16x32_bf16 v[38:41], v[138:141], v[174:177], v[38:41]
	v_mfma_f32_16x16x32_bf16 v[22:25], v[138:141], v[182:185], v[22:25]
	v_mfma_f32_16x16x32_bf16 v[18:21], v[154:157], v[182:185], v[18:21]
	v_mfma_f32_16x16x32_bf16 v[2:5], v[154:157], v[190:193], v[2:5]
	v_mfma_f32_16x16x32_bf16 v[6:9], v[138:141], v[190:193], v[6:9]
	s_barrier
; #define PG8_STAGE(bufoff, gbase, voff) do { _Pragma("unroll") for (int _i = 0; _i < 2; ++_i) \
;         __builtin_amdgcn_global_load_lds((const unsigned*)((const char*)(gbase) + (voff)[_i]), (PG8_LAS unsigned*)(lds + (bufoff) + ldsw + _i * 8192), 16, 0, 0); } while (0)
; #define PG8_LDA(dst, b, h) do { _Pragma("unroll") for (int m = 0; m < 4; ++m) _Pragma("unroll") for (int k = 0; k < 2; ++k) dst[m][k] = *(const PG8_LAS bf16x8*)(lds + PG8_SA(b, h) + aoff + m * 2048 + k * 1024); } while (0)
; #define PG8_LDB(dst, b, h) do { _Pragma("unroll") for (int n = 0; n < 2; ++n) _Pragma("unroll") for (int k = 0; k < 2; ++k) dst[n][k] = *(const PG8_LAS bf16x8*)(lds + PG8_SB(b, h) + boff + n * 2048 + k * 1024); } while (0)
; #define PG8_MMA(ai, bj, At, Bt) do { __builtin_amdgcn_s_setprio(1); _Pragma("unroll") for (int m = 0; m < 4; ++m) _Pragma("unroll") for (int n = 0; n < 2; ++n) _Pragma("unroll") for (int k = 0; k < 2; ++k) \
;         acc[ai][bj][m][n] = mma16<Epi::I8>(Bt[n][k], At[m][k], acc[ai][bj][m][n]); __builtin_amdgcn_s_setprio(0); } while (0)
; #define PG8_WAIT_V(n) asm volatile("s_waitcnt vmcnt(" #n ")" ::: "memory")
; #define PG8_WAIT_L(n) asm volatile("s_waitcnt lgkmcnt(" #n ")" ::: "memory")
; #define PG8_BAR __builtin_amdgcn_s_barrier()
; #define PG8_SCHED __builtin_amdgcn_sched_barrier(0)
; template <class Epi, class Sched, bool ALIGN_EPI = false, bool SP2 = false>
; __device__ __forceinline__ void gemm_phase(PG8_LAS unsigned char* lds, const Gemm g, const Sched& S, const Epi& E) {
;     ...
;         for (int t = 0; t < nt; t += 2) {
;             const bool last = (t == nt - 2);
;             const char* a1 = cA + (size_t)(t + 1) * kstep;
;             const char* a2 = last ? nA : cA + (size_t)(t + 2) * kstep; const char* b2 = last ? nB : cB + (size_t)(t + 2) * kstep;
;     ...
;             PG8_LDB(B0, 1, 0); PG8_LDB(B1, 1, 1); PG8_SCHED; PG8_LDA(At, 1, 0); PG8_STAGE(PG8_SA(0, 1), a2 + hstep, voffA);
;             PG8_WAIT_V(8); PG8_WAIT_L(0); PG8_BAR; PG8_MMA(0, 0, At, B0); PG8_MMA(0, 1, At, B1); PG8_BAR; PG8_SCHED;
;             PG8_LDA(At, 1, 1); PG8_STAGE(PG8_SB(1, 0), b3, voffB); PG8_STAGE(PG8_SB(1, 1), b3 + hstep, voffB); PG8_STAGE(PG8_SA(1, 0), a3, voffA);
;             PG8_WAIT_V(8); PG8_WAIT_L(0); PG8_BAR; PG8_MMA(1, 0, At, B0); PG8_MMA(1, 1, At, B1); PG8_BAR; PG8_SCHED;
	s_add_i32 s84, 0, 0x18000
	s_add_i32 vcc_hi, 0, 0x1c000
	v_add_u32_e32 v122, s84, v248
	v_add_u32_e32 v154, vcc_hi, v248
	ds_read_b128 v[98:101], v122
	ds_read_b128 v[102:105], v122 offset:1024
	ds_read_b128 v[114:117], v122 offset:2048
	ds_read_b128 v[122:125], v122 offset:3072
	ds_read_b128 v[130:133], v154
	ds_read_b128 v[138:141], v154 offset:1024
	ds_read_b128 v[146:149], v154 offset:2048
	ds_read_b128 v[154:157], v154 offset:3072
	s_add_u32 s4, s8, s58
	s_addc_u32 s5, s9, 0
	s_mov_b32 m0, s71
	v_lshl_add_u64 v[222:223], s[4:5], 0, v[194:195]
	ds_read_b128 v[162:165], v249 offset:32768
	ds_read_b128 v[166:169], v249 offset:33792
	ds_read_b128 v[170:173], v249 offset:34816
	ds_read_b128 v[174:177], v249 offset:35840
	ds_read_b128 v[178:181], v249 offset:36864
	ds_read_b128 v[182:185], v249 offset:37888
	ds_read_b128 v[186:189], v249 offset:38912
	ds_read_b128 v[190:193], v249 offset:39936
	global_load_lds_dwordx4 v[222:223], off
	v_lshl_add_u64 v[222:223], s[4:5], 0, v[196:197]
	s_mov_b32 m0, s12
	s_nop 0
	global_load_lds_dwordx4 v[222:223], off
	s_waitcnt vmcnt(8)
	s_waitcnt lgkmcnt(0)
	s_barrier
	s_waitcnt lgkmcnt(0)
	v_mfma_f32_16x16x32_bf16 v[158:161], v[98:101], v[162:165], v[158:161]
	v_mfma_f32_16x16x32_bf16 v[150:153], v[114:117], v[162:165], v[150:153]
	v_mfma_f32_16x16x32_bf16 v[118:121], v[114:117], v[170:173], v[118:121]
	v_mfma_f32_16x16x32_bf16 v[126:129], v[98:101], v[170:173], v[126:129]
	v_mfma_f32_16x16x32_bf16 v[94:97], v[98:101], v[178:181], v[94:97]
	v_mfma_f32_16x16x32_bf16 v[90:93], v[114:117], v[178:181], v[90:93]
	v_mfma_f32_16x16x32_bf16 v[74:77], v[114:117], v[186:189], v[74:77]
	v_mfma_f32_16x16x32_bf16 v[78:81], v[98:101], v[186:189], v[78:81]
	v_mfma_f32_16x16x32_bf16 v[158:161], v[102:105], v[166:169], v[158:161]
	v_mfma_f32_16x16x32_bf16 v[150:153], v[122:125], v[166:169], v[150:153]
	v_mfma_f32_16x16x32_bf16 v[118:121], v[122:125], v[174:177], v[118:121]
	v_mfma_f32_16x16x32_bf16 v[126:129], v[102:105], v[174:177], v[126:129]
	v_mfma_f32_16x16x32_bf16 v[94:97], v[102:105], v[182:185], v[94:97]
	v_mfma_f32_16x16x32_bf16 v[90:93], v[122:125], v[182:185], v[90:93]
	v_mfma_f32_16x16x32_bf16 v[74:77], v[122:125], v[190:193], v[74:77]
	v_mfma_f32_16x16x32_bf16 v[78:81], v[102:105], v[190:193], v[78:81]
	v_mfma_f32_16x16x32_bf16 v[142:145], v[130:133], v[162:165], v[142:145]
	v_mfma_f32_16x16x32_bf16 v[134:137], v[146:149], v[162:165], v[134:137]
	v_mfma_f32_16x16x32_bf16 v[106:109], v[146:149], v[170:173], v[106:109]
	v_mfma_f32_16x16x32_bf16 v[110:113], v[130:133], v[170:173], v[110:113]
	v_mfma_f32_16x16x32_bf16 v[86:89], v[130:133], v[178:181], v[86:89]
	v_mfma_f32_16x16x32_bf16 v[82:85], v[146:149], v[178:181], v[82:85]
	v_mfma_f32_16x16x32_bf16 v[66:69], v[146:149], v[186:189], v[66:69]
	v_mfma_f32_16x16x32_bf16 v[70:73], v[130:133], v[186:189], v[70:73]
	v_mfma_f32_16x16x32_bf16 v[142:145], v[138:141], v[166:169], v[142:145]
	v_mfma_f32_16x16x32_bf16 v[134:137], v[154:157], v[166:169], v[134:137]
	v_mfma_f32_16x16x32_bf16 v[106:109], v[154:157], v[174:177], v[106:109]
	v_mfma_f32_16x16x32_bf16 v[110:113], v[138:141], v[174:177], v[110:113]
	v_mfma_f32_16x16x32_bf16 v[86:89], v[138:141], v[182:185], v[86:89]
	v_mfma_f32_16x16x32_bf16 v[82:85], v[154:157], v[182:185], v[82:85]
	v_mfma_f32_16x16x32_bf16 v[66:69], v[154:157], v[190:193], v[66:69]
	v_mfma_f32_16x16x32_bf16 v[70:73], v[138:141], v[190:193], v[70:73]
	s_barrier
	s_add_i32 s4, s84, s80
	v_lshl_add_u64 v[206:207], v[206:207], 0, s[92:93]
	s_mov_b32 m0, s4
	ds_read_b128 v[162:165], v249 offset:49152
	ds_read_b128 v[166:169], v249 offset:50176
	ds_read_b128 v[170:173], v249 offset:51200
	ds_read_b128 v[174:177], v249 offset:52224
	ds_read_b128 v[178:181], v249 offset:53248
	ds_read_b128 v[182:185], v249 offset:54272
	ds_read_b128 v[186:189], v249 offset:55296
	ds_read_b128 v[190:193], v249 offset:56320
	global_load_lds_dwordx4 v[206:207], off
	v_lshl_add_u64 v[206:207], v[212:213], 0, s[92:93]
	s_add_i32 m0, s4, 0x2000
	s_add_i32 s4, vcc_hi, s80
	global_load_lds_dwordx4 v[206:207], off
	v_lshl_add_u64 v[206:207], v[214:215], 0, s[92:93]
	s_mov_b32 m0, s4
	s_nop 0
	global_load_lds_dwordx4 v[206:207], off
	v_lshl_add_u64 v[206:207], v[216:217], 0, s[92:93]
	s_add_i32 m0, s4, 0x2000
	s_nop 0
	global_load_lds_dwordx4 v[206:207], off
	v_lshl_add_u64 v[206:207], v[218:219], 0, s[92:93]
	s_mov_b32 m0, s10
	s_nop 0
	global_load_lds_dwordx4 v[206:207], off
	v_lshl_add_u64 v[206:207], v[220:221], 0, s[92:93]
	s_mov_b32 m0, s11
	s_nop 0
	global_load_lds_dwordx4 v[206:207], off
	s_waitcnt vmcnt(8)
	s_waitcnt lgkmcnt(0)
	s_barrier
	s_waitcnt lgkmcnt(0)
	v_mfma_f32_16x16x32_bf16 v[62:65], v[98:101], v[162:165], v[62:65]
	v_mfma_f32_16x16x32_bf16 v[58:61], v[114:117], v[162:165], v[58:61]
	v_mfma_f32_16x16x32_bf16 v[42:45], v[114:117], v[170:173], v[42:45]
	v_mfma_f32_16x16x32_bf16 v[46:49], v[98:101], v[170:173], v[46:49]
	v_mfma_f32_16x16x32_bf16 v[30:33], v[98:101], v[178:181], v[30:33]
	v_mfma_f32_16x16x32_bf16 v[26:29], v[114:117], v[178:181], v[26:29]
	v_mfma_f32_16x16x32_bf16 v[10:13], v[114:117], v[186:189], v[10:13]
	v_mfma_f32_16x16x32_bf16 v[14:17], v[98:101], v[186:189], v[14:17]
	v_mfma_f32_16x16x32_bf16 v[62:65], v[102:105], v[166:169], v[62:65]
	v_mfma_f32_16x16x32_bf16 v[58:61], v[122:125], v[166:169], v[58:61]
	v_mfma_f32_16x16x32_bf16 v[42:45], v[122:125], v[174:177], v[42:45]
	v_mfma_f32_16x16x32_bf16 v[46:49], v[102:105], v[174:177], v[46:49]
	v_mfma_f32_16x16x32_bf16 v[30:33], v[102:105], v[182:185], v[30:33]
	v_mfma_f32_16x16x32_bf16 v[26:29], v[122:125], v[182:185], v[26:29]
	v_mfma_f32_16x16x32_bf16 v[10:13], v[122:125], v[190:193], v[10:13]
	v_mfma_f32_16x16x32_bf16 v[14:17], v[102:105], v[190:193], v[14:17]
	v_mfma_f32_16x16x32_bf16 v[54:57], v[130:133], v[162:165], v[54:57]
	v_mfma_f32_16x16x32_bf16 v[50:53], v[146:149], v[162:165], v[50:53]
	v_mfma_f32_16x16x32_bf16 v[34:37], v[146:149], v[170:173], v[34:37]
	v_mfma_f32_16x16x32_bf16 v[38:41], v[130:133], v[170:173], v[38:41]
	v_mfma_f32_16x16x32_bf16 v[22:25], v[130:133], v[178:181], v[22:25]
	v_mfma_f32_16x16x32_bf16 v[18:21], v[146:149], v[178:181], v[18:21]
	v_mfma_f32_16x16x32_bf16 v[2:5], v[146:149], v[186:189], v[2:5]
	v_mfma_f32_16x16x32_bf16 v[6:9], v[130:133], v[186:189], v[6:9]
	v_mfma_f32_16x16x32_bf16 v[54:57], v[138:141], v[166:169], v[54:57]
	v_mfma_f32_16x16x32_bf16 v[50:53], v[154:157], v[166:169], v[50:53]
	v_mfma_f32_16x16x32_bf16 v[34:37], v[154:157], v[174:177], v[34:37]
	v_mfma_f32_16x16x32_bf16 v[38:41], v[138:141], v[174:177], v[38:41]
	v_mfma_f32_16x16x32_bf16 v[22:25], v[138:141], v[182:185], v[22:25]
	v_mfma_f32_16x16x32_bf16 v[18:21], v[154:157], v[182:185], v[18:21]
	v_mfma_f32_16x16x32_bf16 v[2:5], v[154:157], v[190:193], v[2:5]
	v_mfma_f32_16x16x32_bf16 v[6:9], v[138:141], v[190:193], v[6:9]
	s_barrier
	s_add_u32 s6, s6, 0x100
	s_addc_u32 s7, s7, 0
	s_add_u32 s67, s67, 0x100
	s_addc_u32 s85, s85, 0
	s_cmp_ge_u32 vcc_lo, s69
	s_mov_b32 s8, vcc_lo
	s_cbranch_scc0 .LBB0_175
; #define PG8_BAR __builtin_amdgcn_s_barrier()
; template <class Epi, class Sched, bool ALIGN_EPI = false, bool SP2 = false>
; __device__ __forceinline__ void gemm_phase(PG8_LAS unsigned char* lds, const Gemm g, const Sched& S, const Epi& E) {
;     ...
;         if constexpr (ALIGN_EPI) { if (wr == 0) PG8_BAR; }
;         if constexpr (!Epi::AFTER_DRAIN) { E(acc, cur, wr, wc, fr, fq); S.done(cur); }
.Lpeelx175:
	s_setprio 0
	v_mov_b32_e32 v232, 0x8800
	v_mov_b32_e32 v231, 0x2000
	v_mov_b32_e32 v202, 1
	s_and_b64 vcc, exec, s[46:47]
	s_cbranch_vccz .LBB0_178
	s_barrier

; #define PG8_STAGE(bufoff, gbase, voff) do { _Pragma("unroll") for (int _i = 0; _i < 2; ++_i) \
;         __builtin_amdgcn_global_load_lds((const unsigned*)((const char*)(gbase) + (voff)[_i]), (PG8_LAS unsigned*)(lds + (bufoff) + ldsw + _i * 8192), 16, 0, 0); } while (0)
; #define PG8_LDA(dst, b, h) do { _Pragma("unroll") for (int m = 0; m < 4; ++m) _Pragma("unroll") for (int k = 0; k < 2; ++k) dst[m][k] = *(const PG8_LAS bf16x8*)(lds + PG8_SA(b, h) + aoff + m * 2048 + k * 1024); } while (0)
; #define PG8_LDB(dst, b, h) do { _Pragma("unroll") for (int n = 0; n < 2; ++n) _Pragma("unroll") for (int k = 0; k < 2; ++k) dst[n][k] = *(const PG8_LAS bf16x8*)(lds + PG8_SB(b, h) + boff + n * 2048 + k * 1024); } while (0)
; #define PG8_WAIT_V(n) asm volatile("s_waitcnt vmcnt(" #n ")" ::: "memory")
; #define PG8_WAIT_L(n) asm volatile("s_waitcnt lgkmcnt(" #n ")" ::: "memory")
; #define PG8_BAR __builtin_amdgcn_s_barrier()
; #define PG8_SCHED __builtin_amdgcn_sched_barrier(0)
; template <class Epi, class Sched, bool ALIGN_EPI = false, bool SP2 = false>
; __device__ __forceinline__ void gemm_phase(PG8_LAS unsigned char* lds, const Gemm g, const Sched& S, const Epi& E) {
;     ...
; #pragma unroll
;     for (int a = 0; a < 2; ++a)
; #pragma unroll
;         for (int b = 0; b < 2; ++b)
; #pragma unroll
;             for (int m = 0; m < 4; ++m)
; #pragma unroll
;                 for (int n = 0; n < 2; ++n) acc[a][b][m][n] = (f32x4){0.f, 0.f, 0.f, 0.f};
;     ...
;             const bool last = (t == nt - 2);
;             const char* a1 = cA + (size_t)(t + 1) * kstep;
;             const char* a2 = last ? nA : cA + (size_t)(t + 2) * kstep; const char* b2 = last ? nB : cB + (size_t)(t + 2) * kstep;
;             const char* a3 = a2 + kstep; const char* b3 = b2 + kstep;
;             if (last && has_next) S.a_ready(nxt);
;             if constexpr (SP2) {
;             PG8_LDB(B0, 0, 0); PG8_LDB(B1, 0, 1); PG8_SCHED; PG8_LDA(At, 0, 0); PG8_STAGE(PG8_SA(1, 1), a1 + hstep, voffA);
;             PG8_WAIT_V(8); PG8_WAIT_L(0); PG8_BAR; PG8_MMA(0, 0, At, B0); PG8_MMA(0, 1, At, B1); PG8_BAR; PG8_SCHED;
;             PG8_LDA(At, 0, 1); PG8_STAGE(PG8_SB(0, 0), b2, voffB); PG8_STAGE(PG8_SB(0, 1), b2 + hstep, voffB); PG8_STAGE(PG8_SA(0, 0), a2, voffA);
;             PG8_WAIT_V(8); PG8_WAIT_L(0); PG8_BAR; PG8_MMA(1, 0, At, B0); PG8_MMA(1, 1, At, B1); PG8_BAR; PG8_SCHED;
.Lprio291:
	s_add_u32 s84, s8, 0x100
	s_addc_u32 s85, s9, 0
	s_add_i32 s66, 0, 0x10000
	s_cmp_eq_u32 s10, 12
	s_cselect_b32 vcc_hi, s5, s85
	s_cselect_b32 vcc_lo, s7, s84
	s_cselect_b32 s97, s11, s68
	s_cselect_b32 s96, s67, s69
	s_add_i32 s70, 0, 0x14000
	v_add_u32_e32 v110, s66, v175
	v_add_u32_e32 v168, s70, v175
	s_waitcnt vmcnt(0)
	ds_read_b128 v[66:69], v110
	ds_read_b128 v[70:73], v110 offset:1024
	ds_read_b128 v[106:109], v110 offset:2048
	ds_read_b128 v[110:113], v110 offset:3072
	ds_read_b128 v[114:117], v168
	ds_read_b128 v[118:121], v168 offset:1024
	ds_read_b128 v[126:129], v168 offset:2048
	ds_read_b128 v[178:181], v168 offset:3072
	v_lshl_add_u64 v[168:169], s[8:9], 0, v[164:165]
	s_add_i32 m0, s1, 0xc000
	ds_read_b128 v[182:185], v177
	ds_read_b128 v[186:189], v177 offset:1024
	ds_read_b128 v[190:193], v177 offset:2048
	ds_read_b128 v[194:197], v177 offset:3072
	ds_read_b128 v[198:201], v177 offset:4096
	ds_read_b128 v[210:213], v177 offset:5120
	ds_read_b128 v[214:217], v177 offset:6144
	ds_read_b128 v[218:221], v177 offset:7168
	global_load_lds_dwordx4 v[168:169], off
	v_lshl_add_u64 v[168:169], s[8:9], 0, v[166:167]
	s_add_i32 m0, s1, 0xe000
	s_nop 0
	global_load_lds_dwordx4 v[168:169], off
	s_waitcnt vmcnt(8)
	s_waitcnt lgkmcnt(0)
	s_barrier
	s_waitcnt lgkmcnt(0)
	v_mfma_i32_16x16x64_i8 v[154:157], v[66:69], v[182:185], 0
	v_mfma_i32_16x16x64_i8 v[146:149], v[106:109], v[182:185], 0
	v_mfma_i32_16x16x64_i8 v[138:141], v[106:109], v[190:193], 0
	v_mfma_i32_16x16x64_i8 v[150:153], v[66:69], v[190:193], 0
	v_mfma_i32_16x16x64_i8 v[142:145], v[66:69], v[198:201], 0
	v_mfma_i32_16x16x64_i8 v[130:133], v[106:109], v[198:201], 0
	v_mfma_i32_16x16x64_i8 v[122:125], v[106:109], v[214:217], 0
	v_mfma_i32_16x16x64_i8 v[134:137], v[66:69], v[214:217], 0
	v_mfma_i32_16x16x64_i8 v[154:157], v[70:73], v[186:189], v[154:157]
	v_mfma_i32_16x16x64_i8 v[146:149], v[110:113], v[186:189], v[146:149]
	v_mfma_i32_16x16x64_i8 v[138:141], v[110:113], v[194:197], v[138:141]
	v_mfma_i32_16x16x64_i8 v[150:153], v[70:73], v[194:197], v[150:153]
	v_mfma_i32_16x16x64_i8 v[142:145], v[70:73], v[210:213], v[142:145]
	v_mfma_i32_16x16x64_i8 v[130:133], v[110:113], v[210:213], v[130:133]
	v_mfma_i32_16x16x64_i8 v[122:125], v[110:113], v[218:221], v[122:125]
	v_mfma_i32_16x16x64_i8 v[134:137], v[70:73], v[218:221], v[134:137]
	v_mfma_i32_16x16x64_i8 v[102:105], v[114:117], v[182:185], 0
	v_mfma_i32_16x16x64_i8 v[94:97], v[126:129], v[182:185], 0
	v_mfma_i32_16x16x64_i8 v[86:89], v[126:129], v[190:193], 0
	v_mfma_i32_16x16x64_i8 v[98:101], v[114:117], v[190:193], 0
	v_mfma_i32_16x16x64_i8 v[90:93], v[114:117], v[198:201], 0
	v_mfma_i32_16x16x64_i8 v[78:81], v[126:129], v[198:201], 0
	v_mfma_i32_16x16x64_i8 v[74:77], v[126:129], v[214:217], 0
	v_mfma_i32_16x16x64_i8 v[82:85], v[114:117], v[214:217], 0
	v_mfma_i32_16x16x64_i8 v[102:105], v[118:121], v[186:189], v[102:105]
	v_mfma_i32_16x16x64_i8 v[94:97], v[178:181], v[186:189], v[94:97]
	v_mfma_i32_16x16x64_i8 v[86:89], v[178:181], v[194:197], v[86:89]
	v_mfma_i32_16x16x64_i8 v[98:101], v[118:121], v[194:197], v[98:101]
	v_mfma_i32_16x16x64_i8 v[90:93], v[118:121], v[210:213], v[90:93]
	v_mfma_i32_16x16x64_i8 v[78:81], v[178:181], v[210:213], v[78:81]
	v_mfma_i32_16x16x64_i8 v[74:77], v[178:181], v[218:221], v[74:77]
	v_mfma_i32_16x16x64_i8 v[82:85], v[118:121], v[218:221], v[82:85]
	s_barrier
	s_add_i32 s8, s66, s81
	v_lshl_add_u64 v[168:169], s[96:97], 0, v[0:1]
	s_mov_b32 m0, s8
	ds_read_b128 v[182:185], v177 offset:16384
	ds_read_b128 v[186:189], v177 offset:17408
	ds_read_b128 v[190:193], v177 offset:18432
	ds_read_b128 v[194:197], v177 offset:19456
	ds_read_b128 v[198:201], v177 offset:20480
	ds_read_b128 v[210:213], v177 offset:21504
	ds_read_b128 v[214:217], v177 offset:22528
	ds_read_b128 v[218:221], v177 offset:23552
	global_load_lds_dwordx4 v[168:169], off
	s_add_i32 m0, s8, 0x2000
	s_add_u32 s8, s96, 0x40000
	v_lshl_add_u64 v[206:207], s[96:97], 0, v[158:159]
	s_addc_u32 s9, s97, 0
	s_add_i32 s66, s70, s81
	global_load_lds_dwordx4 v[206:207], off
	v_lshl_add_u64 v[222:223], s[8:9], 0, v[0:1]
	s_mov_b32 m0, s66
	v_lshl_add_u64 v[224:225], vcc, 0, v[160:161]
	global_load_lds_dwordx4 v[222:223], off
	v_lshl_add_u64 v[222:223], s[8:9], 0, v[158:159]
	s_add_i32 m0, s66, 0x2000
	s_nop 0
	global_load_lds_dwordx4 v[222:223], off
	v_lshl_add_u64 v[222:223], vcc, 0, v[162:163]
	s_mov_b32 m0, s1
	s_nop 0
	global_load_lds_dwordx4 v[222:223], off
	s_mov_b32 m0, s58
	s_nop 0
	global_load_lds_dwordx4 v[224:225], off
	s_waitcnt vmcnt(8)
	s_waitcnt lgkmcnt(0)
	s_barrier
	s_waitcnt lgkmcnt(0)
	v_mfma_i32_16x16x64_i8 v[62:65], v[66:69], v[182:185], 0
	v_mfma_i32_16x16x64_i8 v[54:57], v[106:109], v[182:185], 0
	v_mfma_i32_16x16x64_i8 v[46:49], v[106:109], v[190:193], 0
	v_mfma_i32_16x16x64_i8 v[58:61], v[66:69], v[190:193], 0
	v_mfma_i32_16x16x64_i8 v[50:53], v[66:69], v[198:201], 0
	v_mfma_i32_16x16x64_i8 v[38:41], v[106:109], v[198:201], 0
	v_mfma_i32_16x16x64_i8 v[34:37], v[106:109], v[214:217], 0
	v_mfma_i32_16x16x64_i8 v[42:45], v[66:69], v[214:217], 0
	v_mfma_i32_16x16x64_i8 v[62:65], v[70:73], v[186:189], v[62:65]
	v_mfma_i32_16x16x64_i8 v[54:57], v[110:113], v[186:189], v[54:57]
	v_mfma_i32_16x16x64_i8 v[46:49], v[110:113], v[194:197], v[46:49]
	v_mfma_i32_16x16x64_i8 v[58:61], v[70:73], v[194:197], v[58:61]
	v_mfma_i32_16x16x64_i8 v[50:53], v[70:73], v[210:213], v[50:53]
	v_mfma_i32_16x16x64_i8 v[38:41], v[110:113], v[210:213], v[38:41]
	v_mfma_i32_16x16x64_i8 v[34:37], v[110:113], v[218:221], v[34:37]
	v_mfma_i32_16x16x64_i8 v[42:45], v[70:73], v[218:221], v[42:45]
	v_mfma_i32_16x16x64_i8 v[30:33], v[114:117], v[182:185], 0
	v_mfma_i32_16x16x64_i8 v[22:25], v[126:129], v[182:185], 0
	v_mfma_i32_16x16x64_i8 v[14:17], v[126:129], v[190:193], 0
	v_mfma_i32_16x16x64_i8 v[26:29], v[114:117], v[190:193], 0
	v_mfma_i32_16x16x64_i8 v[18:21], v[114:117], v[198:201], 0
	v_mfma_i32_16x16x64_i8 v[6:9], v[126:129], v[198:201], 0
	v_mfma_i32_16x16x64_i8 v[2:5], v[126:129], v[214:217], 0
	v_mfma_i32_16x16x64_i8 v[10:13], v[114:117], v[214:217], 0
	v_mfma_i32_16x16x64_i8 v[30:33], v[118:121], v[186:189], v[30:33]
	v_mfma_i32_16x16x64_i8 v[22:25], v[178:181], v[186:189], v[22:25]
	v_mfma_i32_16x16x64_i8 v[14:17], v[178:181], v[194:197], v[14:17]
	v_mfma_i32_16x16x64_i8 v[26:29], v[118:121], v[194:197], v[26:29]
	v_mfma_i32_16x16x64_i8 v[18:21], v[118:121], v[210:213], v[18:21]
	v_mfma_i32_16x16x64_i8 v[6:9], v[178:181], v[210:213], v[6:9]
	v_mfma_i32_16x16x64_i8 v[2:5], v[178:181], v[218:221], v[2:5]
	v_mfma_i32_16x16x64_i8 v[10:13], v[118:121], v[218:221], v[10:13]
	s_barrier
; #define PG8_STAGE(bufoff, gbase, voff) do { _Pragma("unroll") for (int _i = 0; _i < 2; ++_i) \
;         __builtin_amdgcn_global_load_lds((const unsigned*)((const char*)(gbase) + (voff)[_i]), (PG8_LAS unsigned*)(lds + (bufoff) + ldsw + _i * 8192), 16, 0, 0); } while (0)
; #define PG8_LDA(dst, b, h) do { _Pragma("unroll") for (int m = 0; m < 4; ++m) _Pragma("unroll") for (int k = 0; k < 2; ++k) dst[m][k] = *(const PG8_LAS bf16x8*)(lds + PG8_SA(b, h) + aoff + m * 2048 + k * 1024); } while (0)
; #define PG8_LDB(dst, b, h) do { _Pragma("unroll") for (int n = 0; n < 2; ++n) _Pragma("unroll") for (int k = 0; k < 2; ++k) dst[n][k] = *(const PG8_LAS bf16x8*)(lds + PG8_SB(b, h) + boff + n * 2048 + k * 1024); } while (0)
; #define PG8_MMA(ai, bj, At, Bt) do { __builtin_amdgcn_s_setprio(1); _Pragma("unroll") for (int m = 0; m < 4; ++m) _Pragma("unroll") for (int n = 0; n < 2; ++n) _Pragma("unroll") for (int k = 0; k < 2; ++k) \
;         acc[ai][bj][m][n] = mma16<Epi::I8>(Bt[n][k], At[m][k], acc[ai][bj][m][n]); __builtin_amdgcn_s_setprio(0); } while (0)
; #define PG8_WAIT_V(n) asm volatile("s_waitcnt vmcnt(" #n ")" ::: "memory")
; #define PG8_WAIT_L(n) asm volatile("s_waitcnt lgkmcnt(" #n ")" ::: "memory")
; #define PG8_BAR __builtin_amdgcn_s_barrier()
; #define PG8_SCHED __builtin_amdgcn_sched_barrier(0)
; template <class Epi, class Sched, bool ALIGN_EPI = false, bool SP2 = false>
; __device__ __forceinline__ void gemm_phase(PG8_LAS unsigned char* lds, const Gemm g, const Sched& S, const Epi& E) {
;     ...
;         for (int t = 0; t < nt; t += 2) {
;     ...
;             PG8_LDB(B0, 1, 0); PG8_LDB(B1, 1, 1); PG8_SCHED; PG8_LDA(At, 1, 0); PG8_STAGE(PG8_SA(0, 1), a2 + hstep, voffA);
;             PG8_WAIT_V(8); PG8_WAIT_L(0); PG8_BAR; PG8_MMA(0, 0, At, B0); PG8_MMA(0, 1, At, B1); PG8_BAR; PG8_SCHED;
;             PG8_LDA(At, 1, 1); PG8_STAGE(PG8_SB(1, 0), b3, voffB); PG8_STAGE(PG8_SB(1, 1), b3 + hstep, voffB); PG8_STAGE(PG8_SA(1, 0), a3, voffA);
;             PG8_WAIT_V(8); PG8_WAIT_L(0); PG8_BAR; PG8_MMA(1, 0, At, B0); PG8_MMA(1, 1, At, B1); PG8_BAR; PG8_SCHED;
	s_add_i32 s66, 0, 0x18000
	s_add_i32 s70, 0, 0x1c000
	v_add_u32_e32 v110, s66, v175
	v_add_u32_e32 v170, s70, v175
	ds_read_b128 v[66:69], v110
	ds_read_b128 v[70:73], v110 offset:1024
	ds_read_b128 v[106:109], v110 offset:2048
	ds_read_b128 v[110:113], v110 offset:3072
	ds_read_b128 v[114:117], v170
	ds_read_b128 v[118:121], v170 offset:1024
	ds_read_b128 v[126:129], v170 offset:2048
	ds_read_b128 v[178:181], v170 offset:3072
	s_add_u32 s8, vcc_lo, 0x40000
	s_addc_u32 s9, vcc_hi, 0
	s_mov_b32 m0, s80
	v_lshl_add_u64 v[226:227], s[8:9], 0, v[162:163]
	ds_read_b128 v[182:185], v177 offset:32768
	ds_read_b128 v[186:189], v177 offset:33792
	ds_read_b128 v[190:193], v177 offset:34816
	ds_read_b128 v[194:197], v177 offset:35840
	ds_read_b128 v[198:201], v177 offset:36864
	ds_read_b128 v[210:213], v177 offset:37888
	ds_read_b128 v[214:217], v177 offset:38912
	ds_read_b128 v[218:221], v177 offset:39936
	global_load_lds_dwordx4 v[226:227], off
	v_lshl_add_u64 v[226:227], s[8:9], 0, v[160:161]
	s_mov_b32 m0, s0
	s_nop 0
	global_load_lds_dwordx4 v[226:227], off
	s_waitcnt vmcnt(8)
	s_waitcnt lgkmcnt(0)
	s_barrier
	s_waitcnt lgkmcnt(0)
	v_mfma_i32_16x16x64_i8 v[154:157], v[66:69], v[182:185], v[154:157]
	v_mfma_i32_16x16x64_i8 v[146:149], v[106:109], v[182:185], v[146:149]
	v_mfma_i32_16x16x64_i8 v[138:141], v[106:109], v[190:193], v[138:141]
	v_mfma_i32_16x16x64_i8 v[150:153], v[66:69], v[190:193], v[150:153]
	v_mfma_i32_16x16x64_i8 v[142:145], v[66:69], v[198:201], v[142:145]
	v_mfma_i32_16x16x64_i8 v[130:133], v[106:109], v[198:201], v[130:133]
	v_mfma_i32_16x16x64_i8 v[122:125], v[106:109], v[214:217], v[122:125]
	v_mfma_i32_16x16x64_i8 v[134:137], v[66:69], v[214:217], v[134:137]
	v_mfma_i32_16x16x64_i8 v[154:157], v[70:73], v[186:189], v[154:157]
	v_mfma_i32_16x16x64_i8 v[146:149], v[110:113], v[186:189], v[146:149]
	v_mfma_i32_16x16x64_i8 v[138:141], v[110:113], v[194:197], v[138:141]
	v_mfma_i32_16x16x64_i8 v[150:153], v[70:73], v[194:197], v[150:153]
	v_mfma_i32_16x16x64_i8 v[142:145], v[70:73], v[210:213], v[142:145]
	v_mfma_i32_16x16x64_i8 v[130:133], v[110:113], v[210:213], v[130:133]
	v_mfma_i32_16x16x64_i8 v[122:125], v[110:113], v[218:221], v[122:125]
	v_mfma_i32_16x16x64_i8 v[134:137], v[70:73], v[218:221], v[134:137]
	v_mfma_i32_16x16x64_i8 v[102:105], v[114:117], v[182:185], v[102:105]
	v_mfma_i32_16x16x64_i8 v[94:97], v[126:129], v[182:185], v[94:97]
	v_mfma_i32_16x16x64_i8 v[86:89], v[126:129], v[190:193], v[86:89]
	v_mfma_i32_16x16x64_i8 v[98:101], v[114:117], v[190:193], v[98:101]
	v_mfma_i32_16x16x64_i8 v[90:93], v[114:117], v[198:201], v[90:93]
	v_mfma_i32_16x16x64_i8 v[78:81], v[126:129], v[198:201], v[78:81]
	v_mfma_i32_16x16x64_i8 v[74:77], v[126:129], v[214:217], v[74:77]
	v_mfma_i32_16x16x64_i8 v[82:85], v[114:117], v[214:217], v[82:85]
	v_mfma_i32_16x16x64_i8 v[102:105], v[118:121], v[186:189], v[102:105]
	v_mfma_i32_16x16x64_i8 v[94:97], v[178:181], v[186:189], v[94:97]
	v_mfma_i32_16x16x64_i8 v[86:89], v[178:181], v[194:197], v[86:89]
	v_mfma_i32_16x16x64_i8 v[98:101], v[118:121], v[194:197], v[98:101]
	v_mfma_i32_16x16x64_i8 v[90:93], v[118:121], v[210:213], v[90:93]
	v_mfma_i32_16x16x64_i8 v[78:81], v[178:181], v[210:213], v[78:81]
	v_mfma_i32_16x16x64_i8 v[74:77], v[178:181], v[218:221], v[74:77]
	v_mfma_i32_16x16x64_i8 v[82:85], v[118:121], v[218:221], v[82:85]
	s_barrier
	s_add_i32 s8, s66, s81
	v_lshl_add_u64 v[168:169], v[168:169], 0, s[92:93]
	s_mov_b32 m0, s8
	ds_read_b128 v[182:185], v177 offset:49152
	ds_read_b128 v[186:189], v177 offset:50176
	ds_read_b128 v[190:193], v177 offset:51200
	ds_read_b128 v[194:197], v177 offset:52224
	ds_read_b128 v[198:201], v177 offset:53248
	ds_read_b128 v[210:213], v177 offset:54272
	ds_read_b128 v[214:217], v177 offset:55296
	ds_read_b128 v[218:221], v177 offset:56320
	global_load_lds_dwordx4 v[168:169], off
	s_add_i32 m0, s8, 0x2000
	s_add_u32 s8, s96, 0x40080
	v_lshl_add_u64 v[168:169], v[206:207], 0, s[92:93]
	s_addc_u32 s9, s97, 0
	s_add_i32 s66, s70, s81
	global_load_lds_dwordx4 v[168:169], off
	v_lshl_add_u64 v[168:169], s[8:9], 0, v[0:1]
	s_mov_b32 m0, s66
	s_nop 0
	global_load_lds_dwordx4 v[168:169], off
	v_lshl_add_u64 v[168:169], s[8:9], 0, v[158:159]
	s_add_i32 m0, s66, 0x2000
	s_nop 0
	global_load_lds_dwordx4 v[168:169], off
	v_lshl_add_u64 v[168:169], v[222:223], 0, s[92:93]
	s_mov_b32 m0, s13
	s_nop 0
	global_load_lds_dwordx4 v[168:169], off
	v_lshl_add_u64 v[168:169], v[224:225], 0, s[92:93]
	s_mov_b32 m0, s12
	s_nop 0
	global_load_lds_dwordx4 v[168:169], off
	s_waitcnt vmcnt(8)
	s_waitcnt lgkmcnt(0)
	s_barrier
	s_waitcnt lgkmcnt(0)
	v_mfma_i32_16x16x64_i8 v[62:65], v[66:69], v[182:185], v[62:65]
	v_mfma_i32_16x16x64_i8 v[54:57], v[106:109], v[182:185], v[54:57]
	v_mfma_i32_16x16x64_i8 v[46:49], v[106:109], v[190:193], v[46:49]
	v_mfma_i32_16x16x64_i8 v[58:61], v[66:69], v[190:193], v[58:61]
	v_mfma_i32_16x16x64_i8 v[50:53], v[66:69], v[198:201], v[50:53]
	v_mfma_i32_16x16x64_i8 v[38:41], v[106:109], v[198:201], v[38:41]
	v_mfma_i32_16x16x64_i8 v[34:37], v[106:109], v[214:217], v[34:37]
	v_mfma_i32_16x16x64_i8 v[42:45], v[66:69], v[214:217], v[42:45]
	v_mfma_i32_16x16x64_i8 v[62:65], v[70:73], v[186:189], v[62:65]
	v_mfma_i32_16x16x64_i8 v[54:57], v[110:113], v[186:189], v[54:57]
	v_mfma_i32_16x16x64_i8 v[46:49], v[110:113], v[194:197], v[46:49]
	v_mfma_i32_16x16x64_i8 v[58:61], v[70:73], v[194:197], v[58:61]
	v_mfma_i32_16x16x64_i8 v[50:53], v[70:73], v[210:213], v[50:53]
	v_mfma_i32_16x16x64_i8 v[38:41], v[110:113], v[210:213], v[38:41]
	v_mfma_i32_16x16x64_i8 v[34:37], v[110:113], v[218:221], v[34:37]
	v_mfma_i32_16x16x64_i8 v[42:45], v[70:73], v[218:221], v[42:45]
	v_mfma_i32_16x16x64_i8 v[30:33], v[114:117], v[182:185], v[30:33]
	v_mfma_i32_16x16x64_i8 v[22:25], v[126:129], v[182:185], v[22:25]
	v_mfma_i32_16x16x64_i8 v[14:17], v[126:129], v[190:193], v[14:17]
	v_mfma_i32_16x16x64_i8 v[26:29], v[114:117], v[190:193], v[26:29]
	v_mfma_i32_16x16x64_i8 v[18:21], v[114:117], v[198:201], v[18:21]
	v_mfma_i32_16x16x64_i8 v[6:9], v[126:129], v[198:201], v[6:9]
	v_mfma_i32_16x16x64_i8 v[2:5], v[126:129], v[214:217], v[2:5]
	v_mfma_i32_16x16x64_i8 v[10:13], v[114:117], v[214:217], v[10:13]
	v_mfma_i32_16x16x64_i8 v[30:33], v[118:121], v[186:189], v[30:33]
	v_mfma_i32_16x16x64_i8 v[22:25], v[178:181], v[186:189], v[22:25]
	v_mfma_i32_16x16x64_i8 v[14:17], v[178:181], v[194:197], v[14:17]
	v_mfma_i32_16x16x64_i8 v[26:29], v[118:121], v[194:197], v[26:29]
	v_mfma_i32_16x16x64_i8 v[18:21], v[118:121], v[210:213], v[18:21]
	v_mfma_i32_16x16x64_i8 v[6:9], v[178:181], v[210:213], v[6:9]
	v_mfma_i32_16x16x64_i8 v[2:5], v[178:181], v[218:221], v[2:5]
	v_mfma_i32_16x16x64_i8 v[10:13], v[118:121], v[218:221], v[10:13]
	s_barrier
	s_add_i32 s10, s10, 2
	s_add_u32 s69, s69, 0x100
	s_addc_u32 s68, s68, 0
	s_cmp_gt_u32 s10, 13
	s_mov_b64 s[8:9], s[84:85]
	s_cbranch_scc0 .LBB0_291
	s_branch .Lpeelx291
; #define PG8_STAGE(bufoff, gbase, voff) do { _Pragma("unroll") for (int _i = 0; _i < 2; ++_i) \
;         __builtin_amdgcn_global_load_lds((const unsigned*)((const char*)(gbase) + (voff)[_i]), (PG8_LAS unsigned*)(lds + (bufoff) + ldsw + _i * 8192), 16, 0, 0); } while (0)
; #define PG8_LDA(dst, b, h) do { _Pragma("unroll") for (int m = 0; m < 4; ++m) _Pragma("unroll") for (int k = 0; k < 2; ++k) dst[m][k] = *(const PG8_LAS bf16x8*)(lds + PG8_SA(b, h) + aoff + m * 2048 + k * 1024); } while (0)
; #define PG8_LDB(dst, b, h) do { _Pragma("unroll") for (int n = 0; n < 2; ++n) _Pragma("unroll") for (int k = 0; k < 2; ++k) dst[n][k] = *(const PG8_LAS bf16x8*)(lds + PG8_SB(b, h) + boff + n * 2048 + k * 1024); } while (0)
; #define PG8_MMA(ai, bj, At, Bt) do { __builtin_amdgcn_s_setprio(1); _Pragma("unroll") for (int m = 0; m < 4; ++m) _Pragma("unroll") for (int n = 0; n < 2; ++n) _Pragma("unroll") for (int k = 0; k < 2; ++k) \
;         acc[ai][bj][m][n] = mma16<Epi::I8>(Bt[n][k], At[m][k], acc[ai][bj][m][n]); __builtin_amdgcn_s_setprio(0); } while (0)
; #define PG8_WAIT_V(n) asm volatile("s_waitcnt vmcnt(" #n ")" ::: "memory")
; #define PG8_WAIT_L(n) asm volatile("s_waitcnt lgkmcnt(" #n ")" ::: "memory")
; #define PG8_BAR __builtin_amdgcn_s_barrier()
; #define PG8_SCHED __builtin_amdgcn_sched_barrier(0)
; template <class Epi, class Sched, bool ALIGN_EPI = false, bool SP2 = false>
; __device__ __forceinline__ void gemm_phase(PG8_LAS unsigned char* lds, const Gemm g, const Sched& S, const Epi& E) {
;     ...
;             PG8_LDB(B0, 0, 0); PG8_LDB(B1, 0, 1); PG8_SCHED; PG8_LDA(At, 0, 0); PG8_STAGE(PG8_SA(1, 1), a1 + hstep, voffA);
;             PG8_WAIT_V(8); PG8_WAIT_L(0); PG8_BAR; PG8_MMA(0, 0, At, B0); PG8_MMA(0, 1, At, B1); PG8_BAR; PG8_SCHED;
;             PG8_LDA(At, 0, 1); PG8_STAGE(PG8_SB(0, 0), b2, voffB); PG8_STAGE(PG8_SB(0, 1), b2 + hstep, voffB); PG8_STAGE(PG8_SA(0, 0), a2, voffA);
;             PG8_WAIT_V(8); PG8_WAIT_L(0); PG8_BAR; PG8_MMA(1, 0, At, B0); PG8_MMA(1, 1, At, B1); PG8_BAR; PG8_SCHED;
.LBB0_291:
	s_add_u32 s84, s8, 0x100
	s_addc_u32 s85, s9, 0
	s_add_i32 s66, 0, 0x10000
	s_cmp_eq_u32 s10, 12
	s_cselect_b32 vcc_hi, s5, s85
	s_cselect_b32 vcc_lo, s7, s84
	s_cselect_b32 s97, s11, s68
	s_cselect_b32 s96, s67, s69
	s_add_i32 s70, 0, 0x14000
	v_add_u32_e32 v110, s66, v175
	v_add_u32_e32 v168, s70, v175
	s_waitcnt vmcnt(0)
	ds_read_b128 v[66:69], v110
	ds_read_b128 v[70:73], v110 offset:1024
	ds_read_b128 v[106:109], v110 offset:2048
	ds_read_b128 v[110:113], v110 offset:3072
	ds_read_b128 v[114:117], v168
	ds_read_b128 v[118:121], v168 offset:1024
	ds_read_b128 v[126:129], v168 offset:2048
	ds_read_b128 v[178:181], v168 offset:3072
	v_lshl_add_u64 v[168:169], s[8:9], 0, v[164:165]
	s_add_i32 m0, s1, 0xc000
	ds_read_b128 v[182:185], v177
	ds_read_b128 v[186:189], v177 offset:1024
	ds_read_b128 v[190:193], v177 offset:2048
	ds_read_b128 v[194:197], v177 offset:3072
	ds_read_b128 v[198:201], v177 offset:4096
	ds_read_b128 v[210:213], v177 offset:5120
	ds_read_b128 v[214:217], v177 offset:6144
	ds_read_b128 v[218:221], v177 offset:7168
	global_load_lds_dwordx4 v[168:169], off
	v_lshl_add_u64 v[168:169], s[8:9], 0, v[166:167]
	s_add_i32 m0, s1, 0xe000
	s_nop 0
	global_load_lds_dwordx4 v[168:169], off
	s_waitcnt vmcnt(8)
	s_waitcnt lgkmcnt(0)
	s_barrier
	s_waitcnt lgkmcnt(0)
	v_mfma_i32_16x16x64_i8 v[154:157], v[66:69], v[182:185], v[154:157]
	v_mfma_i32_16x16x64_i8 v[146:149], v[106:109], v[182:185], v[146:149]
	v_mfma_i32_16x16x64_i8 v[138:141], v[106:109], v[190:193], v[138:141]
	v_mfma_i32_16x16x64_i8 v[150:153], v[66:69], v[190:193], v[150:153]
	v_mfma_i32_16x16x64_i8 v[142:145], v[66:69], v[198:201], v[142:145]
	v_mfma_i32_16x16x64_i8 v[130:133], v[106:109], v[198:201], v[130:133]
	v_mfma_i32_16x16x64_i8 v[122:125], v[106:109], v[214:217], v[122:125]
	v_mfma_i32_16x16x64_i8 v[134:137], v[66:69], v[214:217], v[134:137]
	v_mfma_i32_16x16x64_i8 v[154:157], v[70:73], v[186:189], v[154:157]
	v_mfma_i32_16x16x64_i8 v[146:149], v[110:113], v[186:189], v[146:149]
	v_mfma_i32_16x16x64_i8 v[138:141], v[110:113], v[194:197], v[138:141]
	v_mfma_i32_16x16x64_i8 v[150:153], v[70:73], v[194:197], v[150:153]
	v_mfma_i32_16x16x64_i8 v[142:145], v[70:73], v[210:213], v[142:145]
	v_mfma_i32_16x16x64_i8 v[130:133], v[110:113], v[210:213], v[130:133]
	v_mfma_i32_16x16x64_i8 v[122:125], v[110:113], v[218:221], v[122:125]
	v_mfma_i32_16x16x64_i8 v[134:137], v[70:73], v[218:221], v[134:137]
	v_mfma_i32_16x16x64_i8 v[102:105], v[114:117], v[182:185], v[102:105]
	v_mfma_i32_16x16x64_i8 v[94:97], v[126:129], v[182:185], v[94:97]
	v_mfma_i32_16x16x64_i8 v[86:89], v[126:129], v[190:193], v[86:89]
	v_mfma_i32_16x16x64_i8 v[98:101], v[114:117], v[190:193], v[98:101]
	v_mfma_i32_16x16x64_i8 v[90:93], v[114:117], v[198:201], v[90:93]
	v_mfma_i32_16x16x64_i8 v[78:81], v[126:129], v[198:201], v[78:81]
	v_mfma_i32_16x16x64_i8 v[74:77], v[126:129], v[214:217], v[74:77]
	v_mfma_i32_16x16x64_i8 v[82:85], v[114:117], v[214:217], v[82:85]
	v_mfma_i32_16x16x64_i8 v[102:105], v[118:121], v[186:189], v[102:105]
	v_mfma_i32_16x16x64_i8 v[94:97], v[178:181], v[186:189], v[94:97]
	v_mfma_i32_16x16x64_i8 v[86:89], v[178:181], v[194:197], v[86:89]
	v_mfma_i32_16x16x64_i8 v[98:101], v[118:121], v[194:197], v[98:101]
	v_mfma_i32_16x16x64_i8 v[90:93], v[118:121], v[210:213], v[90:93]
	v_mfma_i32_16x16x64_i8 v[78:81], v[178:181], v[210:213], v[78:81]
	v_mfma_i32_16x16x64_i8 v[74:77], v[178:181], v[218:221], v[74:77]
	v_mfma_i32_16x16x64_i8 v[82:85], v[118:121], v[218:221], v[82:85]
	s_barrier
	s_add_i32 s8, s66, s81
	v_lshl_add_u64 v[168:169], s[96:97], 0, v[0:1]
	s_mov_b32 m0, s8
	ds_read_b128 v[182:185], v177 offset:16384
	ds_read_b128 v[186:189], v177 offset:17408
	ds_read_b128 v[190:193], v177 offset:18432
	ds_read_b128 v[194:197], v177 offset:19456
	ds_read_b128 v[198:201], v177 offset:20480
	ds_read_b128 v[210:213], v177 offset:21504
	ds_read_b128 v[214:217], v177 offset:22528
	ds_read_b128 v[218:221], v177 offset:23552
	global_load_lds_dwordx4 v[168:169], off
	s_add_i32 m0, s8, 0x2000
	s_add_u32 s8, s96, 0x40000
	v_lshl_add_u64 v[206:207], s[96:97], 0, v[158:159]
	s_addc_u32 s9, s97, 0
	s_add_i32 s66, s70, s81
	global_load_lds_dwordx4 v[206:207], off
	v_lshl_add_u64 v[222:223], s[8:9], 0, v[0:1]
	s_mov_b32 m0, s66
	v_lshl_add_u64 v[224:225], vcc, 0, v[160:161]
	global_load_lds_dwordx4 v[222:223], off
	v_lshl_add_u64 v[222:223], s[8:9], 0, v[158:159]
	s_add_i32 m0, s66, 0x2000
	s_nop 0
	global_load_lds_dwordx4 v[222:223], off
	v_lshl_add_u64 v[222:223], vcc, 0, v[162:163]
	s_mov_b32 m0, s1
	s_nop 0
	global_load_lds_dwordx4 v[222:223], off
	s_mov_b32 m0, s58
	s_nop 0
	global_load_lds_dwordx4 v[224:225], off
	s_waitcnt vmcnt(8)
	s_waitcnt lgkmcnt(0)
	s_barrier
; #define PG8_STAGE(bufoff, gbase, voff) do { _Pragma("unroll") for (int _i = 0; _i < 2; ++_i) \
;         __builtin_amdgcn_global_load_lds((const unsigned*)((const char*)(gbase) + (voff)[_i]), (PG8_LAS unsigned*)(lds + (bufoff) + ldsw + _i * 8192), 16, 0, 0); } while (0)
; #define PG8_LDA(dst, b, h) do { _Pragma("unroll") for (int m = 0; m < 4; ++m) _Pragma("unroll") for (int k = 0; k < 2; ++k) dst[m][k] = *(const PG8_LAS bf16x8*)(lds + PG8_SA(b, h) + aoff + m * 2048 + k * 1024); } while (0)
; #define PG8_LDB(dst, b, h) do { _Pragma("unroll") for (int n = 0; n < 2; ++n) _Pragma("unroll") for (int k = 0; k < 2; ++k) dst[n][k] = *(const PG8_LAS bf16x8*)(lds + PG8_SB(b, h) + boff + n * 2048 + k * 1024); } while (0)
; #define PG8_MMA(ai, bj, At, Bt) do { __builtin_amdgcn_s_setprio(1); _Pragma("unroll") for (int m = 0; m < 4; ++m) _Pragma("unroll") for (int n = 0; n < 2; ++n) _Pragma("unroll") for (int k = 0; k < 2; ++k) \
;         acc[ai][bj][m][n] = mma16<Epi::I8>(Bt[n][k], At[m][k], acc[ai][bj][m][n]); __builtin_amdgcn_s_setprio(0); } while (0)
; #define PG8_WAIT_V(n) asm volatile("s_waitcnt vmcnt(" #n ")" ::: "memory")
; #define PG8_WAIT_L(n) asm volatile("s_waitcnt lgkmcnt(" #n ")" ::: "memory")
; #define PG8_BAR __builtin_amdgcn_s_barrier()
; #define PG8_SCHED __builtin_amdgcn_sched_barrier(0)
; template <class Epi, class Sched, bool ALIGN_EPI = false, bool SP2 = false>
; __device__ __forceinline__ void gemm_phase(PG8_LAS unsigned char* lds, const Gemm g, const Sched& S, const Epi& E) {
;     ...
;             PG8_WAIT_V(8); PG8_WAIT_L(0); PG8_BAR; PG8_MMA(1, 0, At, B0); PG8_MMA(1, 1, At, B1); PG8_BAR; PG8_SCHED;
;             PG8_LDB(B0, 1, 0); PG8_LDB(B1, 1, 1); PG8_SCHED; PG8_LDA(At, 1, 0); PG8_STAGE(PG8_SA(0, 1), a2 + hstep, voffA);
;             PG8_WAIT_V(8); PG8_WAIT_L(0); PG8_BAR; PG8_MMA(0, 0, At, B0); PG8_MMA(0, 1, At, B1); PG8_BAR; PG8_SCHED;
	s_waitcnt lgkmcnt(0)
	v_mfma_i32_16x16x64_i8 v[62:65], v[66:69], v[182:185], v[62:65]
	v_mfma_i32_16x16x64_i8 v[54:57], v[106:109], v[182:185], v[54:57]
	v_mfma_i32_16x16x64_i8 v[46:49], v[106:109], v[190:193], v[46:49]
	v_mfma_i32_16x16x64_i8 v[58:61], v[66:69], v[190:193], v[58:61]
	v_mfma_i32_16x16x64_i8 v[50:53], v[66:69], v[198:201], v[50:53]
	v_mfma_i32_16x16x64_i8 v[38:41], v[106:109], v[198:201], v[38:41]
	v_mfma_i32_16x16x64_i8 v[34:37], v[106:109], v[214:217], v[34:37]
	v_mfma_i32_16x16x64_i8 v[42:45], v[66:69], v[214:217], v[42:45]
	v_mfma_i32_16x16x64_i8 v[62:65], v[70:73], v[186:189], v[62:65]
	v_mfma_i32_16x16x64_i8 v[54:57], v[110:113], v[186:189], v[54:57]
	v_mfma_i32_16x16x64_i8 v[46:49], v[110:113], v[194:197], v[46:49]
	v_mfma_i32_16x16x64_i8 v[58:61], v[70:73], v[194:197], v[58:61]
	v_mfma_i32_16x16x64_i8 v[50:53], v[70:73], v[210:213], v[50:53]
	v_mfma_i32_16x16x64_i8 v[38:41], v[110:113], v[210:213], v[38:41]
	v_mfma_i32_16x16x64_i8 v[34:37], v[110:113], v[218:221], v[34:37]
	v_mfma_i32_16x16x64_i8 v[42:45], v[70:73], v[218:221], v[42:45]
	v_mfma_i32_16x16x64_i8 v[30:33], v[114:117], v[182:185], v[30:33]
	v_mfma_i32_16x16x64_i8 v[22:25], v[126:129], v[182:185], v[22:25]
	v_mfma_i32_16x16x64_i8 v[14:17], v[126:129], v[190:193], v[14:17]
	v_mfma_i32_16x16x64_i8 v[26:29], v[114:117], v[190:193], v[26:29]
	v_mfma_i32_16x16x64_i8 v[18:21], v[114:117], v[198:201], v[18:21]
	v_mfma_i32_16x16x64_i8 v[6:9], v[126:129], v[198:201], v[6:9]
	v_mfma_i32_16x16x64_i8 v[2:5], v[126:129], v[214:217], v[2:5]
	v_mfma_i32_16x16x64_i8 v[10:13], v[114:117], v[214:217], v[10:13]
	v_mfma_i32_16x16x64_i8 v[30:33], v[118:121], v[186:189], v[30:33]
	v_mfma_i32_16x16x64_i8 v[22:25], v[178:181], v[186:189], v[22:25]
	v_mfma_i32_16x16x64_i8 v[14:17], v[178:181], v[194:197], v[14:17]
	v_mfma_i32_16x16x64_i8 v[26:29], v[118:121], v[194:197], v[26:29]
	v_mfma_i32_16x16x64_i8 v[18:21], v[118:121], v[210:213], v[18:21]
	v_mfma_i32_16x16x64_i8 v[6:9], v[178:181], v[210:213], v[6:9]
	v_mfma_i32_16x16x64_i8 v[2:5], v[178:181], v[218:221], v[2:5]
	v_mfma_i32_16x16x64_i8 v[10:13], v[118:121], v[218:221], v[10:13]
	s_barrier
	s_add_i32 s66, 0, 0x18000
	s_add_i32 s70, 0, 0x1c000
	v_add_u32_e32 v110, s66, v175
	v_add_u32_e32 v170, s70, v175
	ds_read_b128 v[66:69], v110
	ds_read_b128 v[70:73], v110 offset:1024
	ds_read_b128 v[106:109], v110 offset:2048
	ds_read_b128 v[110:113], v110 offset:3072
	ds_read_b128 v[114:117], v170
	ds_read_b128 v[118:121], v170 offset:1024
	ds_read_b128 v[126:129], v170 offset:2048
	ds_read_b128 v[178:181], v170 offset:3072
	s_add_u32 s8, vcc_lo, 0x40000
	s_addc_u32 s9, vcc_hi, 0
	s_mov_b32 m0, s80
	v_lshl_add_u64 v[226:227], s[8:9], 0, v[162:163]
	ds_read_b128 v[182:185], v177 offset:32768
	ds_read_b128 v[186:189], v177 offset:33792
	ds_read_b128 v[190:193], v177 offset:34816
	ds_read_b128 v[194:197], v177 offset:35840
	ds_read_b128 v[198:201], v177 offset:36864
	ds_read_b128 v[210:213], v177 offset:37888
	ds_read_b128 v[214:217], v177 offset:38912
	ds_read_b128 v[218:221], v177 offset:39936
	global_load_lds_dwordx4 v[226:227], off
	v_lshl_add_u64 v[226:227], s[8:9], 0, v[160:161]
	s_mov_b32 m0, s0
	s_nop 0
	global_load_lds_dwordx4 v[226:227], off
	s_waitcnt vmcnt(8)
	s_waitcnt lgkmcnt(0)
	s_barrier
	s_waitcnt lgkmcnt(0)
	v_mfma_i32_16x16x64_i8 v[154:157], v[66:69], v[182:185], v[154:157]
	v_mfma_i32_16x16x64_i8 v[146:149], v[106:109], v[182:185], v[146:149]
	v_mfma_i32_16x16x64_i8 v[138:141], v[106:109], v[190:193], v[138:141]
	v_mfma_i32_16x16x64_i8 v[150:153], v[66:69], v[190:193], v[150:153]
	v_mfma_i32_16x16x64_i8 v[142:145], v[66:69], v[198:201], v[142:145]
	v_mfma_i32_16x16x64_i8 v[130:133], v[106:109], v[198:201], v[130:133]
	v_mfma_i32_16x16x64_i8 v[122:125], v[106:109], v[214:217], v[122:125]
	v_mfma_i32_16x16x64_i8 v[134:137], v[66:69], v[214:217], v[134:137]
	v_mfma_i32_16x16x64_i8 v[154:157], v[70:73], v[186:189], v[154:157]
	v_mfma_i32_16x16x64_i8 v[146:149], v[110:113], v[186:189], v[146:149]
	v_mfma_i32_16x16x64_i8 v[138:141], v[110:113], v[194:197], v[138:141]
	v_mfma_i32_16x16x64_i8 v[150:153], v[70:73], v[194:197], v[150:153]
	v_mfma_i32_16x16x64_i8 v[142:145], v[70:73], v[210:213], v[142:145]
	v_mfma_i32_16x16x64_i8 v[130:133], v[110:113], v[210:213], v[130:133]
	v_mfma_i32_16x16x64_i8 v[122:125], v[110:113], v[218:221], v[122:125]
	v_mfma_i32_16x16x64_i8 v[134:137], v[70:73], v[218:221], v[134:137]
	v_mfma_i32_16x16x64_i8 v[102:105], v[114:117], v[182:185], v[102:105]
	v_mfma_i32_16x16x64_i8 v[94:97], v[126:129], v[182:185], v[94:97]
	v_mfma_i32_16x16x64_i8 v[86:89], v[126:129], v[190:193], v[86:89]
	v_mfma_i32_16x16x64_i8 v[98:101], v[114:117], v[190:193], v[98:101]
	v_mfma_i32_16x16x64_i8 v[90:93], v[114:117], v[198:201], v[90:93]
	v_mfma_i32_16x16x64_i8 v[78:81], v[126:129], v[198:201], v[78:81]
	v_mfma_i32_16x16x64_i8 v[74:77], v[126:129], v[214:217], v[74:77]
	v_mfma_i32_16x16x64_i8 v[82:85], v[114:117], v[214:217], v[82:85]
	v_mfma_i32_16x16x64_i8 v[102:105], v[118:121], v[186:189], v[102:105]
	v_mfma_i32_16x16x64_i8 v[94:97], v[178:181], v[186:189], v[94:97]
	v_mfma_i32_16x16x64_i8 v[86:89], v[178:181], v[194:197], v[86:89]
	v_mfma_i32_16x16x64_i8 v[98:101], v[118:121], v[194:197], v[98:101]
	v_mfma_i32_16x16x64_i8 v[90:93], v[118:121], v[210:213], v[90:93]
	v_mfma_i32_16x16x64_i8 v[78:81], v[178:181], v[210:213], v[78:81]
	v_mfma_i32_16x16x64_i8 v[74:77], v[178:181], v[218:221], v[74:77]
	v_mfma_i32_16x16x64_i8 v[82:85], v[118:121], v[218:221], v[82:85]
	s_barrier
; #define PG8_STAGE(bufoff, gbase, voff) do { _Pragma("unroll") for (int _i = 0; _i < 2; ++_i) \
;         __builtin_amdgcn_global_load_lds((const unsigned*)((const char*)(gbase) + (voff)[_i]), (PG8_LAS unsigned*)(lds + (bufoff) + ldsw + _i * 8192), 16, 0, 0); } while (0)
; #define PG8_LDA(dst, b, h) do { _Pragma("unroll") for (int m = 0; m < 4; ++m) _Pragma("unroll") for (int k = 0; k < 2; ++k) dst[m][k] = *(const PG8_LAS bf16x8*)(lds + PG8_SA(b, h) + aoff + m * 2048 + k * 1024); } while (0)
; #define PG8_MMA(ai, bj, At, Bt) do { __builtin_amdgcn_s_setprio(1); _Pragma("unroll") for (int m = 0; m < 4; ++m) _Pragma("unroll") for (int n = 0; n < 2; ++n) _Pragma("unroll") for (int k = 0; k < 2; ++k) \
;         acc[ai][bj][m][n] = mma16<Epi::I8>(Bt[n][k], At[m][k], acc[ai][bj][m][n]); __builtin_amdgcn_s_setprio(0); } while (0)
; #define PG8_WAIT_V(n) asm volatile("s_waitcnt vmcnt(" #n ")" ::: "memory")
; #define PG8_WAIT_L(n) asm volatile("s_waitcnt lgkmcnt(" #n ")" ::: "memory")
; #define PG8_BAR __builtin_amdgcn_s_barrier()
; #define PG8_SCHED __builtin_amdgcn_sched_barrier(0)
; template <class Epi, class Sched, bool ALIGN_EPI = false, bool SP2 = false>
; __device__ __forceinline__ void gemm_phase(PG8_LAS unsigned char* lds, const Gemm g, const Sched& S, const Epi& E) {
;     ...
;             PG8_LDA(At, 1, 1); PG8_STAGE(PG8_SB(1, 0), b3, voffB); PG8_STAGE(PG8_SB(1, 1), b3 + hstep, voffB); PG8_STAGE(PG8_SA(1, 0), a3, voffA);
;             PG8_WAIT_V(8); PG8_WAIT_L(0); PG8_BAR; PG8_MMA(1, 0, At, B0); PG8_MMA(1, 1, At, B1); PG8_BAR; PG8_SCHED;
;     ...
;         if constexpr (ALIGN_EPI) { if (wr == 0) PG8_BAR; }
;         if constexpr (!Epi::AFTER_DRAIN) { E(acc, cur, wr, wc, fr, fq); S.done(cur); }
	s_add_i32 s8, s66, s81
	v_lshl_add_u64 v[168:169], v[168:169], 0, s[92:93]
	s_mov_b32 m0, s8
	ds_read_b128 v[182:185], v177 offset:49152
	ds_read_b128 v[186:189], v177 offset:50176
	ds_read_b128 v[190:193], v177 offset:51200
	ds_read_b128 v[194:197], v177 offset:52224
	ds_read_b128 v[198:201], v177 offset:53248
	ds_read_b128 v[210:213], v177 offset:54272
	ds_read_b128 v[214:217], v177 offset:55296
	ds_read_b128 v[218:221], v177 offset:56320
	global_load_lds_dwordx4 v[168:169], off
	s_add_i32 m0, s8, 0x2000
	s_add_u32 s8, s96, 0x40080
	v_lshl_add_u64 v[168:169], v[206:207], 0, s[92:93]
	s_addc_u32 s9, s97, 0
	s_add_i32 s66, s70, s81
	global_load_lds_dwordx4 v[168:169], off
	v_lshl_add_u64 v[168:169], s[8:9], 0, v[0:1]
	s_mov_b32 m0, s66
	s_nop 0
	global_load_lds_dwordx4 v[168:169], off
	v_lshl_add_u64 v[168:169], s[8:9], 0, v[158:159]
	s_add_i32 m0, s66, 0x2000
	s_nop 0
	global_load_lds_dwordx4 v[168:169], off
	v_lshl_add_u64 v[168:169], v[222:223], 0, s[92:93]
	s_mov_b32 m0, s13
	s_nop 0
	global_load_lds_dwordx4 v[168:169], off
	v_lshl_add_u64 v[168:169], v[224:225], 0, s[92:93]
	s_mov_b32 m0, s12
	s_nop 0
	global_load_lds_dwordx4 v[168:169], off
	s_waitcnt vmcnt(8)
	s_waitcnt lgkmcnt(0)
	s_barrier
	s_waitcnt lgkmcnt(0)
	v_mfma_i32_16x16x64_i8 v[62:65], v[66:69], v[182:185], v[62:65]
	v_mfma_i32_16x16x64_i8 v[54:57], v[106:109], v[182:185], v[54:57]
	v_mfma_i32_16x16x64_i8 v[46:49], v[106:109], v[190:193], v[46:49]
	v_mfma_i32_16x16x64_i8 v[58:61], v[66:69], v[190:193], v[58:61]
	v_mfma_i32_16x16x64_i8 v[50:53], v[66:69], v[198:201], v[50:53]
	v_mfma_i32_16x16x64_i8 v[38:41], v[106:109], v[198:201], v[38:41]
	v_mfma_i32_16x16x64_i8 v[34:37], v[106:109], v[214:217], v[34:37]
	v_mfma_i32_16x16x64_i8 v[42:45], v[66:69], v[214:217], v[42:45]
	v_mfma_i32_16x16x64_i8 v[62:65], v[70:73], v[186:189], v[62:65]
	v_mfma_i32_16x16x64_i8 v[54:57], v[110:113], v[186:189], v[54:57]
	v_mfma_i32_16x16x64_i8 v[46:49], v[110:113], v[194:197], v[46:49]
	v_mfma_i32_16x16x64_i8 v[58:61], v[70:73], v[194:197], v[58:61]
	v_mfma_i32_16x16x64_i8 v[50:53], v[70:73], v[210:213], v[50:53]
	v_mfma_i32_16x16x64_i8 v[38:41], v[110:113], v[210:213], v[38:41]
	v_mfma_i32_16x16x64_i8 v[34:37], v[110:113], v[218:221], v[34:37]
	v_mfma_i32_16x16x64_i8 v[42:45], v[70:73], v[218:221], v[42:45]
	v_mfma_i32_16x16x64_i8 v[30:33], v[114:117], v[182:185], v[30:33]
	v_mfma_i32_16x16x64_i8 v[22:25], v[126:129], v[182:185], v[22:25]
	v_mfma_i32_16x16x64_i8 v[14:17], v[126:129], v[190:193], v[14:17]
	v_mfma_i32_16x16x64_i8 v[26:29], v[114:117], v[190:193], v[26:29]
	v_mfma_i32_16x16x64_i8 v[18:21], v[114:117], v[198:201], v[18:21]
	v_mfma_i32_16x16x64_i8 v[6:9], v[126:129], v[198:201], v[6:9]
	v_mfma_i32_16x16x64_i8 v[2:5], v[126:129], v[214:217], v[2:5]
	v_mfma_i32_16x16x64_i8 v[10:13], v[114:117], v[214:217], v[10:13]
	v_mfma_i32_16x16x64_i8 v[30:33], v[118:121], v[186:189], v[30:33]
	v_mfma_i32_16x16x64_i8 v[22:25], v[178:181], v[186:189], v[22:25]
	v_mfma_i32_16x16x64_i8 v[14:17], v[178:181], v[194:197], v[14:17]
	v_mfma_i32_16x16x64_i8 v[26:29], v[118:121], v[194:197], v[26:29]
	v_mfma_i32_16x16x64_i8 v[18:21], v[118:121], v[210:213], v[18:21]
	v_mfma_i32_16x16x64_i8 v[6:9], v[178:181], v[210:213], v[6:9]
	v_mfma_i32_16x16x64_i8 v[2:5], v[178:181], v[218:221], v[2:5]
	v_mfma_i32_16x16x64_i8 v[10:13], v[118:121], v[218:221], v[10:13]
	s_barrier
	s_add_i32 s10, s10, 2
	s_add_u32 s69, s69, 0x100
	s_addc_u32 s68, s68, 0
	s_cmp_gt_u32 s10, 13
	s_mov_b64 s[8:9], s[84:85]
	s_cbranch_scc0 .LBB0_291
.Lpeelx291:
	s_setprio 0
	s_and_b64 vcc, exec, s[48:49]
	s_cbranch_vccz .LBB0_294
	s_barrier

; #define PG8_STAGE(bufoff, gbase, voff) do { _Pragma("unroll") for (int _i = 0; _i < 2; ++_i) \
;         __builtin_amdgcn_global_load_lds((const unsigned*)((const char*)(gbase) + (voff)[_i]), (PG8_LAS unsigned*)(lds + (bufoff) + ldsw + _i * 8192), 16, 0, 0); } while (0)
; #define PG8_LDA(dst, b, h) do { _Pragma("unroll") for (int m = 0; m < 4; ++m) _Pragma("unroll") for (int k = 0; k < 2; ++k) dst[m][k] = *(const PG8_LAS bf16x8*)(lds + PG8_SA(b, h) + aoff + m * 2048 + k * 1024); } while (0)
; #define PG8_LDB(dst, b, h) do { _Pragma("unroll") for (int n = 0; n < 2; ++n) _Pragma("unroll") for (int k = 0; k < 2; ++k) dst[n][k] = *(const PG8_LAS bf16x8*)(lds + PG8_SB(b, h) + boff + n * 2048 + k * 1024); } while (0)
; #define PG8_MMA(ai, bj, At, Bt) do { __builtin_amdgcn_s_setprio(1); _Pragma("unroll") for (int m = 0; m < 4; ++m) _Pragma("unroll") for (int n = 0; n < 2; ++n) _Pragma("unroll") for (int k = 0; k < 2; ++k) \
;         acc[ai][bj][m][n] = mma16<Epi::I8>(Bt[n][k], At[m][k], acc[ai][bj][m][n]); __builtin_amdgcn_s_setprio(0); } while (0)
; #define PG8_WAIT_V(n) asm volatile("s_waitcnt vmcnt(" #n ")" ::: "memory")
; #define PG8_WAIT_L(n) asm volatile("s_waitcnt lgkmcnt(" #n ")" ::: "memory")
; #define PG8_BAR __builtin_amdgcn_s_barrier()
; template <class Epi, class Sched, bool ALIGN_EPI = false, bool SP2 = false>
; __device__ __forceinline__ void gemm_phase(PG8_LAS unsigned char* lds, const Gemm g, const Sched& S, const Epi& E) {
;     ...
;             const bool last = (t == nt - 2);
;             const char* a1 = cA + (size_t)(t + 1) * kstep;
;             const char* a2 = last ? nA : cA + (size_t)(t + 2) * kstep; const char* b2 = last ? nB : cB + (size_t)(t + 2) * kstep;
;             const char* a3 = a2 + kstep; const char* b3 = b2 + kstep;
;             if (last && has_next) S.a_ready(nxt);
;             if constexpr (SP2) {
;             PG8_LDB(B0, 0, 0); PG8_LDB(B1, 0, 1); PG8_SCHED; PG8_LDA(At, 0, 0); PG8_STAGE(PG8_SA(1, 1), a1 + hstep, voffA);
;             PG8_WAIT_V(8); PG8_WAIT_L(0); PG8_BAR; PG8_MMA(0, 0, At, B0); PG8_MMA(0, 1, At, B1); PG8_BAR; PG8_SCHED;
;             PG8_LDA(At, 0, 1); PG8_STAGE(PG8_SB(0, 0), b2, voffB); PG8_STAGE(PG8_SB(0, 1), b2 + hstep, voffB); PG8_STAGE(PG8_SA(0, 0), a2, voffA);
;             PG8_WAIT_V(8); PG8_WAIT_L(0); PG8_BAR; PG8_MMA(1, 0, At, B0); PG8_MMA(1, 1, At, B1); PG8_BAR; PG8_SCHED;
.Lprio327:
	s_add_u32 s68, s8, 0x100
	s_addc_u32 s69, s9, 0
	s_add_i32 s84, 0, 0x10000
	s_cmp_eq_u32 s4, 28
	s_cselect_b32 vcc_hi, s1, s69
	s_cselect_b32 vcc_lo, s5, s68
	v_add_u32_e32 v0, s84, v188
	s_cselect_b32 s71, s7, s96
	s_cselect_b32 s70, s85, s97
	s_add_i32 s10, 0, 0x14000
	ds_read_b128 v[52:55], v0
	ds_read_b128 v[56:59], v0 offset:1024
	ds_read_b128 v[76:79], v0 offset:2048
	ds_read_b128 v[80:83], v0 offset:3072
	v_add_u32_e32 v0, s10, v188
	ds_read_b128 v[116:119], v0
	ds_read_b128 v[120:123], v0 offset:1024
	ds_read_b128 v[168:171], v0 offset:2048
	ds_read_b128 v[172:175], v0 offset:3072
	v_lshl_add_u64 v[2:3], s[8:9], 0, v[164:165]
	s_add_i32 m0, s58, 0xc000
	ds_read_b128 v[176:179], v189
	ds_read_b128 v[180:183], v189 offset:1024
	ds_read_b128 v[190:193], v189 offset:2048
	ds_read_b128 v[194:197], v189 offset:3072
	ds_read_b128 v[198:201], v189 offset:4096
	ds_read_b128 v[210:213], v189 offset:5120
	ds_read_b128 v[214:217], v189 offset:6144
	ds_read_b128 v[218:221], v189 offset:7168
	global_load_lds_dwordx4 v[2:3], off
	v_lshl_add_u64 v[2:3], s[8:9], 0, v[166:167]
	s_add_i32 m0, s58, 0xe000
	s_nop 0
	global_load_lds_dwordx4 v[2:3], off
	s_waitcnt vmcnt(8)
	s_waitcnt lgkmcnt(0)
	s_barrier
	s_waitcnt lgkmcnt(0)
	v_mfma_f32_16x16x32_bf16 v[152:155], v[52:55], v[176:179], 0
	v_mfma_f32_16x16x32_bf16 v[144:147], v[76:79], v[176:179], 0
	v_mfma_f32_16x16x32_bf16 v[140:143], v[76:79], v[190:193], 0
	v_mfma_f32_16x16x32_bf16 v[148:151], v[52:55], v[190:193], 0
	v_mfma_f32_16x16x32_bf16 v[136:139], v[52:55], v[198:201], 0
	v_mfma_f32_16x16x32_bf16 v[132:135], v[76:79], v[198:201], 0
	v_mfma_f32_16x16x32_bf16 v[124:127], v[76:79], v[214:217], 0
	v_mfma_f32_16x16x32_bf16 v[128:131], v[52:55], v[214:217], 0
	v_mfma_f32_16x16x32_bf16 v[152:155], v[56:59], v[180:183], v[152:155]
	v_mfma_f32_16x16x32_bf16 v[144:147], v[80:83], v[180:183], v[144:147]
	v_mfma_f32_16x16x32_bf16 v[140:143], v[80:83], v[194:197], v[140:143]
	v_mfma_f32_16x16x32_bf16 v[148:151], v[56:59], v[194:197], v[148:151]
	v_mfma_f32_16x16x32_bf16 v[136:139], v[56:59], v[210:213], v[136:139]
	v_mfma_f32_16x16x32_bf16 v[132:135], v[80:83], v[210:213], v[132:135]
	v_mfma_f32_16x16x32_bf16 v[124:127], v[80:83], v[218:221], v[124:127]
	v_mfma_f32_16x16x32_bf16 v[128:131], v[56:59], v[218:221], v[128:131]
	v_mfma_f32_16x16x32_bf16 v[112:115], v[116:119], v[176:179], 0
	v_mfma_f32_16x16x32_bf16 v[104:107], v[168:171], v[176:179], 0
	v_mfma_f32_16x16x32_bf16 v[100:103], v[168:171], v[190:193], 0
	v_mfma_f32_16x16x32_bf16 v[108:111], v[116:119], v[190:193], 0
	v_mfma_f32_16x16x32_bf16 v[96:99], v[116:119], v[198:201], 0
	v_mfma_f32_16x16x32_bf16 v[92:95], v[168:171], v[198:201], 0
	v_mfma_f32_16x16x32_bf16 v[84:87], v[168:171], v[214:217], 0
	v_mfma_f32_16x16x32_bf16 v[88:91], v[116:119], v[214:217], 0
	v_mfma_f32_16x16x32_bf16 v[112:115], v[120:123], v[180:183], v[112:115]
	v_mfma_f32_16x16x32_bf16 v[104:107], v[172:175], v[180:183], v[104:107]
	v_mfma_f32_16x16x32_bf16 v[100:103], v[172:175], v[194:197], v[100:103]
	v_mfma_f32_16x16x32_bf16 v[108:111], v[120:123], v[194:197], v[108:111]
	v_mfma_f32_16x16x32_bf16 v[96:99], v[120:123], v[210:213], v[96:99]
	v_mfma_f32_16x16x32_bf16 v[92:95], v[172:175], v[210:213], v[92:95]
	v_mfma_f32_16x16x32_bf16 v[84:87], v[172:175], v[218:221], v[84:87]
	v_mfma_f32_16x16x32_bf16 v[88:91], v[120:123], v[218:221], v[88:91]
	s_barrier
	s_add_i32 s8, s84, s80
	v_lshl_add_u64 v[184:185], s[70:71], 0, v[158:159]
	s_mov_b32 m0, s8
	ds_read_b128 v[176:179], v189 offset:16384
	ds_read_b128 v[180:183], v189 offset:17408
	ds_read_b128 v[190:193], v189 offset:18432
	ds_read_b128 v[194:197], v189 offset:19456
	ds_read_b128 v[198:201], v189 offset:20480
	ds_read_b128 v[210:213], v189 offset:21504
	ds_read_b128 v[214:217], v189 offset:22528
	ds_read_b128 v[218:221], v189 offset:23552
	global_load_lds_dwordx4 v[184:185], off
	s_add_i32 m0, s8, 0x2000
	s_add_u32 s8, s70, 0x80000
	v_lshl_add_u64 v[206:207], s[70:71], 0, v[162:163]
	s_addc_u32 s9, s71, 0
	s_add_i32 s10, s10, s80
	global_load_lds_dwordx4 v[206:207], off
	v_lshl_add_u64 v[2:3], s[8:9], 0, v[158:159]
	s_mov_b32 m0, s10
	v_lshl_add_u64 v[222:223], vcc, 0, v[156:157]
	global_load_lds_dwordx4 v[2:3], off
	v_lshl_add_u64 v[2:3], s[8:9], 0, v[162:163]
	s_add_i32 m0, s10, 0x2000
	v_lshl_add_u64 v[224:225], vcc, 0, v[160:161]
	global_load_lds_dwordx4 v[2:3], off
	s_mov_b32 m0, s58
	s_nop 0
	global_load_lds_dwordx4 v[222:223], off
	s_mov_b32 m0, s12
	s_nop 0
	global_load_lds_dwordx4 v[224:225], off
	s_waitcnt vmcnt(8)
	s_waitcnt lgkmcnt(0)
	s_barrier
	s_waitcnt lgkmcnt(0)
	v_mfma_f32_16x16x32_bf16 v[72:75], v[52:55], v[176:179], 0
	v_mfma_f32_16x16x32_bf16 v[64:67], v[76:79], v[176:179], 0
	v_mfma_f32_16x16x32_bf16 v[60:63], v[76:79], v[190:193], 0
	v_mfma_f32_16x16x32_bf16 v[68:71], v[52:55], v[190:193], 0
	v_mfma_f32_16x16x32_bf16 v[48:51], v[52:55], v[198:201], 0
	v_mfma_f32_16x16x32_bf16 v[44:47], v[76:79], v[198:201], 0
	v_mfma_f32_16x16x32_bf16 v[36:39], v[76:79], v[214:217], 0
	v_mfma_f32_16x16x32_bf16 v[40:43], v[52:55], v[214:217], 0
	v_mfma_f32_16x16x32_bf16 v[72:75], v[56:59], v[180:183], v[72:75]
	v_mfma_f32_16x16x32_bf16 v[64:67], v[80:83], v[180:183], v[64:67]
	v_mfma_f32_16x16x32_bf16 v[60:63], v[80:83], v[194:197], v[60:63]
	v_mfma_f32_16x16x32_bf16 v[68:71], v[56:59], v[194:197], v[68:71]
	v_mfma_f32_16x16x32_bf16 v[48:51], v[56:59], v[210:213], v[48:51]
	v_mfma_f32_16x16x32_bf16 v[44:47], v[80:83], v[210:213], v[44:47]
	v_mfma_f32_16x16x32_bf16 v[36:39], v[80:83], v[218:221], v[36:39]
	v_mfma_f32_16x16x32_bf16 v[40:43], v[56:59], v[218:221], v[40:43]
	v_mfma_f32_16x16x32_bf16 v[32:35], v[116:119], v[176:179], 0
	v_mfma_f32_16x16x32_bf16 v[24:27], v[168:171], v[176:179], 0
	v_mfma_f32_16x16x32_bf16 v[20:23], v[168:171], v[190:193], 0
	v_mfma_f32_16x16x32_bf16 v[28:31], v[116:119], v[190:193], 0
	v_mfma_f32_16x16x32_bf16 v[16:19], v[116:119], v[198:201], 0
	v_mfma_f32_16x16x32_bf16 v[12:15], v[168:171], v[198:201], 0
	v_mfma_f32_16x16x32_bf16 v[2:5], v[168:171], v[214:217], 0
	v_mfma_f32_16x16x32_bf16 v[8:11], v[116:119], v[214:217], 0
	v_mfma_f32_16x16x32_bf16 v[32:35], v[120:123], v[180:183], v[32:35]
	v_mfma_f32_16x16x32_bf16 v[24:27], v[172:175], v[180:183], v[24:27]
	v_mfma_f32_16x16x32_bf16 v[20:23], v[172:175], v[194:197], v[20:23]
	v_mfma_f32_16x16x32_bf16 v[28:31], v[120:123], v[194:197], v[28:31]
	v_mfma_f32_16x16x32_bf16 v[16:19], v[120:123], v[210:213], v[16:19]
	v_mfma_f32_16x16x32_bf16 v[12:15], v[172:175], v[210:213], v[12:15]
	v_mfma_f32_16x16x32_bf16 v[2:5], v[172:175], v[218:221], v[2:5]
	v_mfma_f32_16x16x32_bf16 v[8:11], v[120:123], v[218:221], v[8:11]
	s_barrier
; #define PG8_STAGE(bufoff, gbase, voff) do { _Pragma("unroll") for (int _i = 0; _i < 2; ++_i) \
;         __builtin_amdgcn_global_load_lds((const unsigned*)((const char*)(gbase) + (voff)[_i]), (PG8_LAS unsigned*)(lds + (bufoff) + ldsw + _i * 8192), 16, 0, 0); } while (0)
; #define PG8_LDA(dst, b, h) do { _Pragma("unroll") for (int m = 0; m < 4; ++m) _Pragma("unroll") for (int k = 0; k < 2; ++k) dst[m][k] = *(const PG8_LAS bf16x8*)(lds + PG8_SA(b, h) + aoff + m * 2048 + k * 1024); } while (0)
; #define PG8_LDB(dst, b, h) do { _Pragma("unroll") for (int n = 0; n < 2; ++n) _Pragma("unroll") for (int k = 0; k < 2; ++k) dst[n][k] = *(const PG8_LAS bf16x8*)(lds + PG8_SB(b, h) + boff + n * 2048 + k * 1024); } while (0)
; #define PG8_MMA(ai, bj, At, Bt) do { __builtin_amdgcn_s_setprio(1); _Pragma("unroll") for (int m = 0; m < 4; ++m) _Pragma("unroll") for (int n = 0; n < 2; ++n) _Pragma("unroll") for (int k = 0; k < 2; ++k) \
;         acc[ai][bj][m][n] = mma16<Epi::I8>(Bt[n][k], At[m][k], acc[ai][bj][m][n]); __builtin_amdgcn_s_setprio(0); } while (0)
; #define PG8_WAIT_V(n) asm volatile("s_waitcnt vmcnt(" #n ")" ::: "memory")
; #define PG8_WAIT_L(n) asm volatile("s_waitcnt lgkmcnt(" #n ")" ::: "memory")
; #define PG8_BAR __builtin_amdgcn_s_barrier()
; #define PG8_SCHED __builtin_amdgcn_sched_barrier(0)
; template <class Epi, class Sched, bool ALIGN_EPI = false, bool SP2 = false>
; __device__ __forceinline__ void gemm_phase(PG8_LAS unsigned char* lds, const Gemm g, const Sched& S, const Epi& E) {
;     ...
;         for (int t = 0; t < nt; t += 2) {
;     ...
;             PG8_LDB(B0, 1, 0); PG8_LDB(B1, 1, 1); PG8_SCHED; PG8_LDA(At, 1, 0); PG8_STAGE(PG8_SA(0, 1), a2 + hstep, voffA);
;             PG8_WAIT_V(8); PG8_WAIT_L(0); PG8_BAR; PG8_MMA(0, 0, At, B0); PG8_MMA(0, 1, At, B1); PG8_BAR; PG8_SCHED;
;             PG8_LDA(At, 1, 1); PG8_STAGE(PG8_SB(1, 0), b3, voffB); PG8_STAGE(PG8_SB(1, 1), b3 + hstep, voffB); PG8_STAGE(PG8_SA(1, 0), a3, voffA);
;             PG8_WAIT_V(8); PG8_WAIT_L(0); PG8_BAR; PG8_MMA(1, 0, At, B0); PG8_MMA(1, 1, At, B1); PG8_BAR; PG8_SCHED;
	s_add_i32 s10, 0, 0x18000
	v_add_u32_e32 v0, s10, v188
	s_add_i32 s11, 0, 0x1c000
	ds_read_b128 v[52:55], v0
	ds_read_b128 v[56:59], v0 offset:1024
	ds_read_b128 v[76:79], v0 offset:2048
	ds_read_b128 v[80:83], v0 offset:3072
	v_add_u32_e32 v0, s11, v188
	ds_read_b128 v[116:119], v0
	ds_read_b128 v[120:123], v0 offset:1024
	ds_read_b128 v[168:171], v0 offset:2048
	ds_read_b128 v[172:175], v0 offset:3072
	s_add_u32 s8, vcc_lo, 0x80000
	s_addc_u32 s9, vcc_hi, 0
	s_mov_b32 m0, s13
	v_lshl_add_u64 v[6:7], s[8:9], 0, v[156:157]
	ds_read_b128 v[176:179], v189 offset:32768
	ds_read_b128 v[180:183], v189 offset:33792
	ds_read_b128 v[190:193], v189 offset:34816
	ds_read_b128 v[194:197], v189 offset:35840
	ds_read_b128 v[198:201], v189 offset:36864
	ds_read_b128 v[210:213], v189 offset:37888
	ds_read_b128 v[214:217], v189 offset:38912
	ds_read_b128 v[218:221], v189 offset:39936
	global_load_lds_dwordx4 v[6:7], off
	v_lshl_add_u64 v[6:7], s[8:9], 0, v[160:161]
	s_mov_b32 m0, s66
	s_nop 0
	global_load_lds_dwordx4 v[6:7], off
	s_waitcnt vmcnt(8)
	s_waitcnt lgkmcnt(0)
	s_barrier
	s_waitcnt lgkmcnt(0)
	v_mfma_f32_16x16x32_bf16 v[152:155], v[52:55], v[176:179], v[152:155]
	v_mfma_f32_16x16x32_bf16 v[144:147], v[76:79], v[176:179], v[144:147]
	v_mfma_f32_16x16x32_bf16 v[140:143], v[76:79], v[190:193], v[140:143]
	v_mfma_f32_16x16x32_bf16 v[148:151], v[52:55], v[190:193], v[148:151]
	v_mfma_f32_16x16x32_bf16 v[136:139], v[52:55], v[198:201], v[136:139]
	v_mfma_f32_16x16x32_bf16 v[132:135], v[76:79], v[198:201], v[132:135]
	v_mfma_f32_16x16x32_bf16 v[124:127], v[76:79], v[214:217], v[124:127]
	v_mfma_f32_16x16x32_bf16 v[128:131], v[52:55], v[214:217], v[128:131]
	v_mfma_f32_16x16x32_bf16 v[152:155], v[56:59], v[180:183], v[152:155]
	v_mfma_f32_16x16x32_bf16 v[144:147], v[80:83], v[180:183], v[144:147]
	v_mfma_f32_16x16x32_bf16 v[140:143], v[80:83], v[194:197], v[140:143]
	v_mfma_f32_16x16x32_bf16 v[148:151], v[56:59], v[194:197], v[148:151]
	v_mfma_f32_16x16x32_bf16 v[136:139], v[56:59], v[210:213], v[136:139]
	v_mfma_f32_16x16x32_bf16 v[132:135], v[80:83], v[210:213], v[132:135]
	v_mfma_f32_16x16x32_bf16 v[124:127], v[80:83], v[218:221], v[124:127]
	v_mfma_f32_16x16x32_bf16 v[128:131], v[56:59], v[218:221], v[128:131]
	v_mfma_f32_16x16x32_bf16 v[112:115], v[116:119], v[176:179], v[112:115]
	v_mfma_f32_16x16x32_bf16 v[104:107], v[168:171], v[176:179], v[104:107]
	v_mfma_f32_16x16x32_bf16 v[100:103], v[168:171], v[190:193], v[100:103]
	v_mfma_f32_16x16x32_bf16 v[108:111], v[116:119], v[190:193], v[108:111]
	v_mfma_f32_16x16x32_bf16 v[96:99], v[116:119], v[198:201], v[96:99]
	v_mfma_f32_16x16x32_bf16 v[92:95], v[168:171], v[198:201], v[92:95]
	v_mfma_f32_16x16x32_bf16 v[84:87], v[168:171], v[214:217], v[84:87]
	v_mfma_f32_16x16x32_bf16 v[88:91], v[116:119], v[214:217], v[88:91]
	v_mfma_f32_16x16x32_bf16 v[112:115], v[120:123], v[180:183], v[112:115]
	v_mfma_f32_16x16x32_bf16 v[104:107], v[172:175], v[180:183], v[104:107]
	v_mfma_f32_16x16x32_bf16 v[100:103], v[172:175], v[194:197], v[100:103]
	v_mfma_f32_16x16x32_bf16 v[108:111], v[120:123], v[194:197], v[108:111]
	v_mfma_f32_16x16x32_bf16 v[96:99], v[120:123], v[210:213], v[96:99]
	v_mfma_f32_16x16x32_bf16 v[92:95], v[172:175], v[210:213], v[92:95]
	v_mfma_f32_16x16x32_bf16 v[84:87], v[172:175], v[218:221], v[84:87]
	v_mfma_f32_16x16x32_bf16 v[88:91], v[120:123], v[218:221], v[88:91]
	s_barrier
	s_add_i32 s8, s10, s80
	v_lshl_add_u64 v[6:7], v[184:185], 0, s[92:93]
	s_mov_b32 m0, s8
	ds_read_b128 v[176:179], v189 offset:49152
	ds_read_b128 v[180:183], v189 offset:50176
	ds_read_b128 v[190:193], v189 offset:51200
	ds_read_b128 v[194:197], v189 offset:52224
	ds_read_b128 v[198:201], v189 offset:53248
	ds_read_b128 v[210:213], v189 offset:54272
	ds_read_b128 v[214:217], v189 offset:55296
	ds_read_b128 v[218:221], v189 offset:56320
	global_load_lds_dwordx4 v[6:7], off
	s_add_i32 m0, s8, 0x2000
	s_add_u32 s8, s70, 0x80080
	v_lshl_add_u64 v[6:7], v[206:207], 0, s[92:93]
	s_addc_u32 s9, s71, 0
	s_add_i32 s10, s11, s80
	global_load_lds_dwordx4 v[6:7], off
	v_lshl_add_u64 v[6:7], s[8:9], 0, v[158:159]
	s_mov_b32 m0, s10
	s_nop 0
	global_load_lds_dwordx4 v[6:7], off
	v_lshl_add_u64 v[6:7], s[8:9], 0, v[162:163]
	s_add_i32 m0, s10, 0x2000
	s_nop 0
	global_load_lds_dwordx4 v[6:7], off
	v_lshl_add_u64 v[6:7], v[222:223], 0, s[92:93]
	s_mov_b32 m0, s67
	s_nop 0
	global_load_lds_dwordx4 v[6:7], off
	v_lshl_add_u64 v[6:7], v[224:225], 0, s[92:93]
	s_mov_b32 m0, s81
	s_nop 0
	global_load_lds_dwordx4 v[6:7], off
	s_waitcnt vmcnt(8)
	s_waitcnt lgkmcnt(0)
	s_barrier
	s_waitcnt lgkmcnt(0)
	v_mfma_f32_16x16x32_bf16 v[72:75], v[52:55], v[176:179], v[72:75]
	v_mfma_f32_16x16x32_bf16 v[64:67], v[76:79], v[176:179], v[64:67]
	v_mfma_f32_16x16x32_bf16 v[60:63], v[76:79], v[190:193], v[60:63]
	v_mfma_f32_16x16x32_bf16 v[68:71], v[52:55], v[190:193], v[68:71]
	v_mfma_f32_16x16x32_bf16 v[48:51], v[52:55], v[198:201], v[48:51]
	v_mfma_f32_16x16x32_bf16 v[44:47], v[76:79], v[198:201], v[44:47]
	v_mfma_f32_16x16x32_bf16 v[36:39], v[76:79], v[214:217], v[36:39]
	v_mfma_f32_16x16x32_bf16 v[40:43], v[52:55], v[214:217], v[40:43]
	v_mfma_f32_16x16x32_bf16 v[72:75], v[56:59], v[180:183], v[72:75]
	v_mfma_f32_16x16x32_bf16 v[64:67], v[80:83], v[180:183], v[64:67]
	v_mfma_f32_16x16x32_bf16 v[60:63], v[80:83], v[194:197], v[60:63]
	v_mfma_f32_16x16x32_bf16 v[68:71], v[56:59], v[194:197], v[68:71]
	v_mfma_f32_16x16x32_bf16 v[48:51], v[56:59], v[210:213], v[48:51]
	v_mfma_f32_16x16x32_bf16 v[44:47], v[80:83], v[210:213], v[44:47]
	v_mfma_f32_16x16x32_bf16 v[36:39], v[80:83], v[218:221], v[36:39]
	v_mfma_f32_16x16x32_bf16 v[40:43], v[56:59], v[218:221], v[40:43]
	v_mfma_f32_16x16x32_bf16 v[32:35], v[116:119], v[176:179], v[32:35]
	v_mfma_f32_16x16x32_bf16 v[24:27], v[168:171], v[176:179], v[24:27]
	v_mfma_f32_16x16x32_bf16 v[20:23], v[168:171], v[190:193], v[20:23]
	v_mfma_f32_16x16x32_bf16 v[28:31], v[116:119], v[190:193], v[28:31]
	v_mfma_f32_16x16x32_bf16 v[16:19], v[116:119], v[198:201], v[16:19]
	v_mfma_f32_16x16x32_bf16 v[12:15], v[168:171], v[198:201], v[12:15]
	v_mfma_f32_16x16x32_bf16 v[2:5], v[168:171], v[214:217], v[2:5]
	v_mfma_f32_16x16x32_bf16 v[6:9], v[116:119], v[214:217], v[8:11]
	v_mfma_f32_16x16x32_bf16 v[32:35], v[120:123], v[180:183], v[32:35]
	v_mfma_f32_16x16x32_bf16 v[24:27], v[172:175], v[180:183], v[24:27]
	v_mfma_f32_16x16x32_bf16 v[20:23], v[172:175], v[194:197], v[20:23]
	v_mfma_f32_16x16x32_bf16 v[28:31], v[120:123], v[194:197], v[28:31]
	v_mfma_f32_16x16x32_bf16 v[16:19], v[120:123], v[210:213], v[16:19]
	v_mfma_f32_16x16x32_bf16 v[12:15], v[172:175], v[210:213], v[12:15]
	v_mfma_f32_16x16x32_bf16 v[8:11], v[120:123], v[218:221], v[6:9]
	v_mfma_f32_16x16x32_bf16 v[4:7], v[172:175], v[218:221], v[2:5]
	s_barrier
	s_add_i32 s4, s4, 2
	s_add_u32 s97, s97, 0x100
	s_addc_u32 s96, s96, 0
	s_cmp_gt_u32 s4, 29
	s_mov_b64 s[8:9], s[68:69]
	s_cbranch_scc0 .LBB0_327
	s_branch .Lpeelx327
; #define PG8_STAGE(bufoff, gbase, voff) do { _Pragma("unroll") for (int _i = 0; _i < 2; ++_i) \
;         __builtin_amdgcn_global_load_lds((const unsigned*)((const char*)(gbase) + (voff)[_i]), (PG8_LAS unsigned*)(lds + (bufoff) + ldsw + _i * 8192), 16, 0, 0); } while (0)
; #define PG8_LDA(dst, b, h) do { _Pragma("unroll") for (int m = 0; m < 4; ++m) _Pragma("unroll") for (int k = 0; k < 2; ++k) dst[m][k] = *(const PG8_LAS bf16x8*)(lds + PG8_SA(b, h) + aoff + m * 2048 + k * 1024); } while (0)
; #define PG8_LDB(dst, b, h) do { _Pragma("unroll") for (int n = 0; n < 2; ++n) _Pragma("unroll") for (int k = 0; k < 2; ++k) dst[n][k] = *(const PG8_LAS bf16x8*)(lds + PG8_SB(b, h) + boff + n * 2048 + k * 1024); } while (0)
; #define PG8_MMA(ai, bj, At, Bt) do { __builtin_amdgcn_s_setprio(1); _Pragma("unroll") for (int m = 0; m < 4; ++m) _Pragma("unroll") for (int n = 0; n < 2; ++n) _Pragma("unroll") for (int k = 0; k < 2; ++k) \
;         acc[ai][bj][m][n] = mma16<Epi::I8>(Bt[n][k], At[m][k], acc[ai][bj][m][n]); __builtin_amdgcn_s_setprio(0); } while (0)
; #define PG8_WAIT_V(n) asm volatile("s_waitcnt vmcnt(" #n ")" ::: "memory")
; #define PG8_WAIT_L(n) asm volatile("s_waitcnt lgkmcnt(" #n ")" ::: "memory")
; #define PG8_BAR __builtin_amdgcn_s_barrier()
; #define PG8_SCHED __builtin_amdgcn_sched_barrier(0)
; template <class Epi, class Sched, bool ALIGN_EPI = false, bool SP2 = false>
; __device__ __forceinline__ void gemm_phase(PG8_LAS unsigned char* lds, const Gemm g, const Sched& S, const Epi& E) {
;     ...
;             PG8_LDB(B0, 0, 0); PG8_LDB(B1, 0, 1); PG8_SCHED; PG8_LDA(At, 0, 0); PG8_STAGE(PG8_SA(1, 1), a1 + hstep, voffA);
;             PG8_WAIT_V(8); PG8_WAIT_L(0); PG8_BAR; PG8_MMA(0, 0, At, B0); PG8_MMA(0, 1, At, B1); PG8_BAR; PG8_SCHED;
;             PG8_LDA(At, 0, 1); PG8_STAGE(PG8_SB(0, 0), b2, voffB); PG8_STAGE(PG8_SB(0, 1), b2 + hstep, voffB); PG8_STAGE(PG8_SA(0, 0), a2, voffA);
;             PG8_WAIT_V(8); PG8_WAIT_L(0); PG8_BAR; PG8_MMA(1, 0, At, B0); PG8_MMA(1, 1, At, B1); PG8_BAR; PG8_SCHED;
.LBB0_327:
	s_add_u32 s68, s8, 0x100
	s_addc_u32 s69, s9, 0
	s_add_i32 s84, 0, 0x10000
	s_cmp_eq_u32 s4, 28
	s_cselect_b32 vcc_hi, s1, s69
	s_cselect_b32 vcc_lo, s5, s68
	v_add_u32_e32 v0, s84, v188
	s_cselect_b32 s71, s7, s96
	s_cselect_b32 s70, s85, s97
	s_add_i32 s10, 0, 0x14000
	ds_read_b128 v[52:55], v0
	ds_read_b128 v[56:59], v0 offset:1024
	ds_read_b128 v[76:79], v0 offset:2048
	ds_read_b128 v[80:83], v0 offset:3072
	v_add_u32_e32 v0, s10, v188
	ds_read_b128 v[116:119], v0
	ds_read_b128 v[120:123], v0 offset:1024
	ds_read_b128 v[168:171], v0 offset:2048
	ds_read_b128 v[172:175], v0 offset:3072
	v_lshl_add_u64 v[2:3], s[8:9], 0, v[164:165]
	s_add_i32 m0, s58, 0xc000
	ds_read_b128 v[176:179], v189
	ds_read_b128 v[180:183], v189 offset:1024
	ds_read_b128 v[190:193], v189 offset:2048
	ds_read_b128 v[194:197], v189 offset:3072
	ds_read_b128 v[198:201], v189 offset:4096
	ds_read_b128 v[210:213], v189 offset:5120
	ds_read_b128 v[214:217], v189 offset:6144
	ds_read_b128 v[218:221], v189 offset:7168
	global_load_lds_dwordx4 v[2:3], off
	v_lshl_add_u64 v[2:3], s[8:9], 0, v[166:167]
	s_add_i32 m0, s58, 0xe000
	s_nop 0
	global_load_lds_dwordx4 v[2:3], off
	s_waitcnt vmcnt(8)
	s_waitcnt lgkmcnt(0)
	s_barrier
	s_waitcnt lgkmcnt(0)
	v_mfma_f32_16x16x32_bf16 v[152:155], v[52:55], v[176:179], v[152:155]
	v_mfma_f32_16x16x32_bf16 v[144:147], v[76:79], v[176:179], v[144:147]
	v_mfma_f32_16x16x32_bf16 v[140:143], v[76:79], v[190:193], v[140:143]
	v_mfma_f32_16x16x32_bf16 v[148:151], v[52:55], v[190:193], v[148:151]
	v_mfma_f32_16x16x32_bf16 v[136:139], v[52:55], v[198:201], v[136:139]
	v_mfma_f32_16x16x32_bf16 v[132:135], v[76:79], v[198:201], v[132:135]
	v_mfma_f32_16x16x32_bf16 v[124:127], v[76:79], v[214:217], v[124:127]
	v_mfma_f32_16x16x32_bf16 v[128:131], v[52:55], v[214:217], v[128:131]
	v_mfma_f32_16x16x32_bf16 v[152:155], v[56:59], v[180:183], v[152:155]
	v_mfma_f32_16x16x32_bf16 v[144:147], v[80:83], v[180:183], v[144:147]
	v_mfma_f32_16x16x32_bf16 v[140:143], v[80:83], v[194:197], v[140:143]
	v_mfma_f32_16x16x32_bf16 v[148:151], v[56:59], v[194:197], v[148:151]
	v_mfma_f32_16x16x32_bf16 v[136:139], v[56:59], v[210:213], v[136:139]
	v_mfma_f32_16x16x32_bf16 v[132:135], v[80:83], v[210:213], v[132:135]
	v_mfma_f32_16x16x32_bf16 v[124:127], v[80:83], v[218:221], v[124:127]
	v_mfma_f32_16x16x32_bf16 v[128:131], v[56:59], v[218:221], v[128:131]
	v_mfma_f32_16x16x32_bf16 v[112:115], v[116:119], v[176:179], v[112:115]
	v_mfma_f32_16x16x32_bf16 v[104:107], v[168:171], v[176:179], v[104:107]
	v_mfma_f32_16x16x32_bf16 v[100:103], v[168:171], v[190:193], v[100:103]
	v_mfma_f32_16x16x32_bf16 v[108:111], v[116:119], v[190:193], v[108:111]
	v_mfma_f32_16x16x32_bf16 v[96:99], v[116:119], v[198:201], v[96:99]
	v_mfma_f32_16x16x32_bf16 v[92:95], v[168:171], v[198:201], v[92:95]
	v_mfma_f32_16x16x32_bf16 v[84:87], v[168:171], v[214:217], v[84:87]
	v_mfma_f32_16x16x32_bf16 v[88:91], v[116:119], v[214:217], v[88:91]
	v_mfma_f32_16x16x32_bf16 v[112:115], v[120:123], v[180:183], v[112:115]
	v_mfma_f32_16x16x32_bf16 v[104:107], v[172:175], v[180:183], v[104:107]
	v_mfma_f32_16x16x32_bf16 v[100:103], v[172:175], v[194:197], v[100:103]
	v_mfma_f32_16x16x32_bf16 v[108:111], v[120:123], v[194:197], v[108:111]
	v_mfma_f32_16x16x32_bf16 v[96:99], v[120:123], v[210:213], v[96:99]
	v_mfma_f32_16x16x32_bf16 v[92:95], v[172:175], v[210:213], v[92:95]
	v_mfma_f32_16x16x32_bf16 v[84:87], v[172:175], v[218:221], v[84:87]
	v_mfma_f32_16x16x32_bf16 v[88:91], v[120:123], v[218:221], v[88:91]
	s_barrier
	s_add_i32 s8, s84, s80
	v_lshl_add_u64 v[184:185], s[70:71], 0, v[158:159]
	s_mov_b32 m0, s8
	ds_read_b128 v[176:179], v189 offset:16384
	ds_read_b128 v[180:183], v189 offset:17408
	ds_read_b128 v[190:193], v189 offset:18432
	ds_read_b128 v[194:197], v189 offset:19456
	ds_read_b128 v[198:201], v189 offset:20480
	ds_read_b128 v[210:213], v189 offset:21504
	ds_read_b128 v[214:217], v189 offset:22528
	ds_read_b128 v[218:221], v189 offset:23552
	global_load_lds_dwordx4 v[184:185], off
	s_add_i32 m0, s8, 0x2000
	s_add_u32 s8, s70, 0x80000
	v_lshl_add_u64 v[206:207], s[70:71], 0, v[162:163]
	s_addc_u32 s9, s71, 0
	s_add_i32 s10, s10, s80
	global_load_lds_dwordx4 v[206:207], off
	v_lshl_add_u64 v[2:3], s[8:9], 0, v[158:159]
	s_mov_b32 m0, s10
	v_lshl_add_u64 v[222:223], vcc, 0, v[156:157]
	global_load_lds_dwordx4 v[2:3], off
	v_lshl_add_u64 v[2:3], s[8:9], 0, v[162:163]
	s_add_i32 m0, s10, 0x2000
	v_lshl_add_u64 v[224:225], vcc, 0, v[160:161]
	global_load_lds_dwordx4 v[2:3], off
	s_mov_b32 m0, s58
	s_nop 0
	global_load_lds_dwordx4 v[222:223], off
	s_mov_b32 m0, s12
	s_nop 0
	global_load_lds_dwordx4 v[224:225], off
	s_waitcnt vmcnt(8)
	s_waitcnt lgkmcnt(0)
	s_barrier
; #define PG8_STAGE(bufoff, gbase, voff) do { _Pragma("unroll") for (int _i = 0; _i < 2; ++_i) \
;         __builtin_amdgcn_global_load_lds((const unsigned*)((const char*)(gbase) + (voff)[_i]), (PG8_LAS unsigned*)(lds + (bufoff) + ldsw + _i * 8192), 16, 0, 0); } while (0)
; #define PG8_LDA(dst, b, h) do { _Pragma("unroll") for (int m = 0; m < 4; ++m) _Pragma("unroll") for (int k = 0; k < 2; ++k) dst[m][k] = *(const PG8_LAS bf16x8*)(lds + PG8_SA(b, h) + aoff + m * 2048 + k * 1024); } while (0)
; #define PG8_LDB(dst, b, h) do { _Pragma("unroll") for (int n = 0; n < 2; ++n) _Pragma("unroll") for (int k = 0; k < 2; ++k) dst[n][k] = *(const PG8_LAS bf16x8*)(lds + PG8_SB(b, h) + boff + n * 2048 + k * 1024); } while (0)
; #define PG8_MMA(ai, bj, At, Bt) do { __builtin_amdgcn_s_setprio(1); _Pragma("unroll") for (int m = 0; m < 4; ++m) _Pragma("unroll") for (int n = 0; n < 2; ++n) _Pragma("unroll") for (int k = 0; k < 2; ++k) \
;         acc[ai][bj][m][n] = mma16<Epi::I8>(Bt[n][k], At[m][k], acc[ai][bj][m][n]); __builtin_amdgcn_s_setprio(0); } while (0)
; #define PG8_WAIT_V(n) asm volatile("s_waitcnt vmcnt(" #n ")" ::: "memory")
; #define PG8_WAIT_L(n) asm volatile("s_waitcnt lgkmcnt(" #n ")" ::: "memory")
; #define PG8_BAR __builtin_amdgcn_s_barrier()
; #define PG8_SCHED __builtin_amdgcn_sched_barrier(0)
; template <class Epi, class Sched, bool ALIGN_EPI = false, bool SP2 = false>
; __device__ __forceinline__ void gemm_phase(PG8_LAS unsigned char* lds, const Gemm g, const Sched& S, const Epi& E) {
;     ...
;             PG8_WAIT_V(8); PG8_WAIT_L(0); PG8_BAR; PG8_MMA(1, 0, At, B0); PG8_MMA(1, 1, At, B1); PG8_BAR; PG8_SCHED;
;             PG8_LDB(B0, 1, 0); PG8_LDB(B1, 1, 1); PG8_SCHED; PG8_LDA(At, 1, 0); PG8_STAGE(PG8_SA(0, 1), a2 + hstep, voffA);
;             PG8_WAIT_V(8); PG8_WAIT_L(0); PG8_BAR; PG8_MMA(0, 0, At, B0); PG8_MMA(0, 1, At, B1); PG8_BAR; PG8_SCHED;
	s_waitcnt lgkmcnt(0)
	v_mfma_f32_16x16x32_bf16 v[72:75], v[52:55], v[176:179], v[72:75]
	v_mfma_f32_16x16x32_bf16 v[64:67], v[76:79], v[176:179], v[64:67]
	v_mfma_f32_16x16x32_bf16 v[60:63], v[76:79], v[190:193], v[60:63]
	v_mfma_f32_16x16x32_bf16 v[68:71], v[52:55], v[190:193], v[68:71]
	v_mfma_f32_16x16x32_bf16 v[48:51], v[52:55], v[198:201], v[48:51]
	v_mfma_f32_16x16x32_bf16 v[44:47], v[76:79], v[198:201], v[44:47]
	v_mfma_f32_16x16x32_bf16 v[36:39], v[76:79], v[214:217], v[36:39]
	v_mfma_f32_16x16x32_bf16 v[40:43], v[52:55], v[214:217], v[40:43]
	v_mfma_f32_16x16x32_bf16 v[72:75], v[56:59], v[180:183], v[72:75]
	v_mfma_f32_16x16x32_bf16 v[64:67], v[80:83], v[180:183], v[64:67]
	v_mfma_f32_16x16x32_bf16 v[60:63], v[80:83], v[194:197], v[60:63]
	v_mfma_f32_16x16x32_bf16 v[68:71], v[56:59], v[194:197], v[68:71]
	v_mfma_f32_16x16x32_bf16 v[48:51], v[56:59], v[210:213], v[48:51]
	v_mfma_f32_16x16x32_bf16 v[44:47], v[80:83], v[210:213], v[44:47]
	v_mfma_f32_16x16x32_bf16 v[36:39], v[80:83], v[218:221], v[36:39]
	v_mfma_f32_16x16x32_bf16 v[40:43], v[56:59], v[218:221], v[40:43]
	v_mfma_f32_16x16x32_bf16 v[32:35], v[116:119], v[176:179], v[32:35]
	v_mfma_f32_16x16x32_bf16 v[24:27], v[168:171], v[176:179], v[24:27]
	v_mfma_f32_16x16x32_bf16 v[20:23], v[168:171], v[190:193], v[20:23]
	v_mfma_f32_16x16x32_bf16 v[28:31], v[116:119], v[190:193], v[28:31]
	v_mfma_f32_16x16x32_bf16 v[16:19], v[116:119], v[198:201], v[16:19]
	v_mfma_f32_16x16x32_bf16 v[12:15], v[168:171], v[198:201], v[12:15]
	v_mfma_f32_16x16x32_bf16 v[2:5], v[168:171], v[214:217], v[4:7]
	v_mfma_f32_16x16x32_bf16 v[8:11], v[116:119], v[214:217], v[8:11]
	v_mfma_f32_16x16x32_bf16 v[32:35], v[120:123], v[180:183], v[32:35]
	v_mfma_f32_16x16x32_bf16 v[24:27], v[172:175], v[180:183], v[24:27]
	v_mfma_f32_16x16x32_bf16 v[20:23], v[172:175], v[194:197], v[20:23]
	v_mfma_f32_16x16x32_bf16 v[28:31], v[120:123], v[194:197], v[28:31]
	v_mfma_f32_16x16x32_bf16 v[16:19], v[120:123], v[210:213], v[16:19]
	v_mfma_f32_16x16x32_bf16 v[12:15], v[172:175], v[210:213], v[12:15]
	v_mfma_f32_16x16x32_bf16 v[2:5], v[172:175], v[218:221], v[2:5]
	v_mfma_f32_16x16x32_bf16 v[8:11], v[120:123], v[218:221], v[8:11]
	s_barrier
	s_add_i32 s10, 0, 0x18000
	v_add_u32_e32 v0, s10, v188
	s_add_i32 s11, 0, 0x1c000
	ds_read_b128 v[52:55], v0
	ds_read_b128 v[56:59], v0 offset:1024
	ds_read_b128 v[76:79], v0 offset:2048
	ds_read_b128 v[80:83], v0 offset:3072
	v_add_u32_e32 v0, s11, v188
	ds_read_b128 v[116:119], v0
	ds_read_b128 v[120:123], v0 offset:1024
	ds_read_b128 v[168:171], v0 offset:2048
	ds_read_b128 v[172:175], v0 offset:3072
	s_add_u32 s8, vcc_lo, 0x80000
	s_addc_u32 s9, vcc_hi, 0
	s_mov_b32 m0, s13
	v_lshl_add_u64 v[6:7], s[8:9], 0, v[156:157]
	ds_read_b128 v[176:179], v189 offset:32768
	ds_read_b128 v[180:183], v189 offset:33792
	ds_read_b128 v[190:193], v189 offset:34816
	ds_read_b128 v[194:197], v189 offset:35840
	ds_read_b128 v[198:201], v189 offset:36864
	ds_read_b128 v[210:213], v189 offset:37888
	ds_read_b128 v[214:217], v189 offset:38912
	ds_read_b128 v[218:221], v189 offset:39936
	global_load_lds_dwordx4 v[6:7], off
	v_lshl_add_u64 v[6:7], s[8:9], 0, v[160:161]
	s_mov_b32 m0, s66
	s_nop 0
	global_load_lds_dwordx4 v[6:7], off
	s_waitcnt vmcnt(8)
	s_waitcnt lgkmcnt(0)
	s_barrier
	s_waitcnt lgkmcnt(0)
	v_mfma_f32_16x16x32_bf16 v[152:155], v[52:55], v[176:179], v[152:155]
	v_mfma_f32_16x16x32_bf16 v[144:147], v[76:79], v[176:179], v[144:147]
	v_mfma_f32_16x16x32_bf16 v[140:143], v[76:79], v[190:193], v[140:143]
	v_mfma_f32_16x16x32_bf16 v[148:151], v[52:55], v[190:193], v[148:151]
	v_mfma_f32_16x16x32_bf16 v[136:139], v[52:55], v[198:201], v[136:139]
	v_mfma_f32_16x16x32_bf16 v[132:135], v[76:79], v[198:201], v[132:135]
	v_mfma_f32_16x16x32_bf16 v[124:127], v[76:79], v[214:217], v[124:127]
	v_mfma_f32_16x16x32_bf16 v[128:131], v[52:55], v[214:217], v[128:131]
	v_mfma_f32_16x16x32_bf16 v[152:155], v[56:59], v[180:183], v[152:155]
	v_mfma_f32_16x16x32_bf16 v[144:147], v[80:83], v[180:183], v[144:147]
	v_mfma_f32_16x16x32_bf16 v[140:143], v[80:83], v[194:197], v[140:143]
	v_mfma_f32_16x16x32_bf16 v[148:151], v[56:59], v[194:197], v[148:151]
	v_mfma_f32_16x16x32_bf16 v[136:139], v[56:59], v[210:213], v[136:139]
	v_mfma_f32_16x16x32_bf16 v[132:135], v[80:83], v[210:213], v[132:135]
	v_mfma_f32_16x16x32_bf16 v[124:127], v[80:83], v[218:221], v[124:127]
	v_mfma_f32_16x16x32_bf16 v[128:131], v[56:59], v[218:221], v[128:131]
	v_mfma_f32_16x16x32_bf16 v[112:115], v[116:119], v[176:179], v[112:115]
	v_mfma_f32_16x16x32_bf16 v[104:107], v[168:171], v[176:179], v[104:107]
	v_mfma_f32_16x16x32_bf16 v[100:103], v[168:171], v[190:193], v[100:103]
	v_mfma_f32_16x16x32_bf16 v[108:111], v[116:119], v[190:193], v[108:111]
	v_mfma_f32_16x16x32_bf16 v[96:99], v[116:119], v[198:201], v[96:99]
	v_mfma_f32_16x16x32_bf16 v[92:95], v[168:171], v[198:201], v[92:95]
	v_mfma_f32_16x16x32_bf16 v[84:87], v[168:171], v[214:217], v[84:87]
	v_mfma_f32_16x16x32_bf16 v[88:91], v[116:119], v[214:217], v[88:91]
	v_mfma_f32_16x16x32_bf16 v[112:115], v[120:123], v[180:183], v[112:115]
	v_mfma_f32_16x16x32_bf16 v[104:107], v[172:175], v[180:183], v[104:107]
	v_mfma_f32_16x16x32_bf16 v[100:103], v[172:175], v[194:197], v[100:103]
	v_mfma_f32_16x16x32_bf16 v[108:111], v[120:123], v[194:197], v[108:111]
	v_mfma_f32_16x16x32_bf16 v[96:99], v[120:123], v[210:213], v[96:99]
	v_mfma_f32_16x16x32_bf16 v[92:95], v[172:175], v[210:213], v[92:95]
	v_mfma_f32_16x16x32_bf16 v[84:87], v[172:175], v[218:221], v[84:87]
	v_mfma_f32_16x16x32_bf16 v[88:91], v[120:123], v[218:221], v[88:91]
	s_barrier
; #define PG8_STAGE(bufoff, gbase, voff) do { _Pragma("unroll") for (int _i = 0; _i < 2; ++_i) \
;         __builtin_amdgcn_global_load_lds((const unsigned*)((const char*)(gbase) + (voff)[_i]), (PG8_LAS unsigned*)(lds + (bufoff) + ldsw + _i * 8192), 16, 0, 0); } while (0)
; #define PG8_LDA(dst, b, h) do { _Pragma("unroll") for (int m = 0; m < 4; ++m) _Pragma("unroll") for (int k = 0; k < 2; ++k) dst[m][k] = *(const PG8_LAS bf16x8*)(lds + PG8_SA(b, h) + aoff + m * 2048 + k * 1024); } while (0)
; #define PG8_MMA(ai, bj, At, Bt) do { __builtin_amdgcn_s_setprio(1); _Pragma("unroll") for (int m = 0; m < 4; ++m) _Pragma("unroll") for (int n = 0; n < 2; ++n) _Pragma("unroll") for (int k = 0; k < 2; ++k) \
;         acc[ai][bj][m][n] = mma16<Epi::I8>(Bt[n][k], At[m][k], acc[ai][bj][m][n]); __builtin_amdgcn_s_setprio(0); } while (0)
; #define PG8_WAIT_V(n) asm volatile("s_waitcnt vmcnt(" #n ")" ::: "memory")
; #define PG8_WAIT_L(n) asm volatile("s_waitcnt lgkmcnt(" #n ")" ::: "memory")
; #define PG8_BAR __builtin_amdgcn_s_barrier()
; #define PG8_SCHED __builtin_amdgcn_sched_barrier(0)
; template <class Epi, class Sched, bool ALIGN_EPI = false, bool SP2 = false>
; __device__ __forceinline__ void gemm_phase(PG8_LAS unsigned char* lds, const Gemm g, const Sched& S, const Epi& E) {
;     ...
;             PG8_LDA(At, 1, 1); PG8_STAGE(PG8_SB(1, 0), b3, voffB); PG8_STAGE(PG8_SB(1, 1), b3 + hstep, voffB); PG8_STAGE(PG8_SA(1, 0), a3, voffA);
;             PG8_WAIT_V(8); PG8_WAIT_L(0); PG8_BAR; PG8_MMA(1, 0, At, B0); PG8_MMA(1, 1, At, B1); PG8_BAR; PG8_SCHED;
;     ...
;         if constexpr (ALIGN_EPI) { if (wr == 0) PG8_BAR; }
;         if constexpr (!Epi::AFTER_DRAIN) { E(acc, cur, wr, wc, fr, fq); S.done(cur); }
	s_add_i32 s8, s10, s80
	v_lshl_add_u64 v[6:7], v[184:185], 0, s[92:93]
	s_mov_b32 m0, s8
	ds_read_b128 v[176:179], v189 offset:49152
	ds_read_b128 v[180:183], v189 offset:50176
	ds_read_b128 v[190:193], v189 offset:51200
	ds_read_b128 v[194:197], v189 offset:52224
	ds_read_b128 v[198:201], v189 offset:53248
	ds_read_b128 v[210:213], v189 offset:54272
	ds_read_b128 v[214:217], v189 offset:55296
	ds_read_b128 v[218:221], v189 offset:56320
	global_load_lds_dwordx4 v[6:7], off
	s_add_i32 m0, s8, 0x2000
	s_add_u32 s8, s70, 0x80080
	v_lshl_add_u64 v[6:7], v[206:207], 0, s[92:93]
	s_addc_u32 s9, s71, 0
	s_add_i32 s10, s11, s80
	global_load_lds_dwordx4 v[6:7], off
	v_lshl_add_u64 v[6:7], s[8:9], 0, v[158:159]
	s_mov_b32 m0, s10
	s_nop 0
	global_load_lds_dwordx4 v[6:7], off
	v_lshl_add_u64 v[6:7], s[8:9], 0, v[162:163]
	s_add_i32 m0, s10, 0x2000
	s_nop 0
	global_load_lds_dwordx4 v[6:7], off
	v_lshl_add_u64 v[6:7], v[222:223], 0, s[92:93]
	s_mov_b32 m0, s67
	s_nop 0
	global_load_lds_dwordx4 v[6:7], off
	v_lshl_add_u64 v[6:7], v[224:225], 0, s[92:93]
	s_mov_b32 m0, s81
	s_nop 0
	global_load_lds_dwordx4 v[6:7], off
	s_waitcnt vmcnt(8)
	s_waitcnt lgkmcnt(0)
	s_barrier
	s_waitcnt lgkmcnt(0)
	v_mfma_f32_16x16x32_bf16 v[72:75], v[52:55], v[176:179], v[72:75]
	v_mfma_f32_16x16x32_bf16 v[64:67], v[76:79], v[176:179], v[64:67]
	v_mfma_f32_16x16x32_bf16 v[60:63], v[76:79], v[190:193], v[60:63]
	v_mfma_f32_16x16x32_bf16 v[68:71], v[52:55], v[190:193], v[68:71]
	v_mfma_f32_16x16x32_bf16 v[48:51], v[52:55], v[198:201], v[48:51]
	v_mfma_f32_16x16x32_bf16 v[44:47], v[76:79], v[198:201], v[44:47]
	v_mfma_f32_16x16x32_bf16 v[36:39], v[76:79], v[214:217], v[36:39]
	v_mfma_f32_16x16x32_bf16 v[40:43], v[52:55], v[214:217], v[40:43]
	v_mfma_f32_16x16x32_bf16 v[72:75], v[56:59], v[180:183], v[72:75]
	v_mfma_f32_16x16x32_bf16 v[64:67], v[80:83], v[180:183], v[64:67]
	v_mfma_f32_16x16x32_bf16 v[60:63], v[80:83], v[194:197], v[60:63]
	v_mfma_f32_16x16x32_bf16 v[68:71], v[56:59], v[194:197], v[68:71]
	v_mfma_f32_16x16x32_bf16 v[48:51], v[56:59], v[210:213], v[48:51]
	v_mfma_f32_16x16x32_bf16 v[44:47], v[80:83], v[210:213], v[44:47]
	v_mfma_f32_16x16x32_bf16 v[36:39], v[80:83], v[218:221], v[36:39]
	v_mfma_f32_16x16x32_bf16 v[40:43], v[56:59], v[218:221], v[40:43]
	v_mfma_f32_16x16x32_bf16 v[32:35], v[116:119], v[176:179], v[32:35]
	v_mfma_f32_16x16x32_bf16 v[24:27], v[168:171], v[176:179], v[24:27]
	v_mfma_f32_16x16x32_bf16 v[20:23], v[168:171], v[190:193], v[20:23]
	v_mfma_f32_16x16x32_bf16 v[28:31], v[116:119], v[190:193], v[28:31]
	v_mfma_f32_16x16x32_bf16 v[16:19], v[116:119], v[198:201], v[16:19]
	v_mfma_f32_16x16x32_bf16 v[12:15], v[168:171], v[198:201], v[12:15]
	v_mfma_f32_16x16x32_bf16 v[2:5], v[168:171], v[214:217], v[2:5]
	v_mfma_f32_16x16x32_bf16 v[6:9], v[116:119], v[214:217], v[8:11]
	v_mfma_f32_16x16x32_bf16 v[32:35], v[120:123], v[180:183], v[32:35]
	v_mfma_f32_16x16x32_bf16 v[24:27], v[172:175], v[180:183], v[24:27]
	v_mfma_f32_16x16x32_bf16 v[20:23], v[172:175], v[194:197], v[20:23]
	v_mfma_f32_16x16x32_bf16 v[28:31], v[120:123], v[194:197], v[28:31]
	v_mfma_f32_16x16x32_bf16 v[16:19], v[120:123], v[210:213], v[16:19]
	v_mfma_f32_16x16x32_bf16 v[12:15], v[172:175], v[210:213], v[12:15]
	v_mfma_f32_16x16x32_bf16 v[8:11], v[120:123], v[218:221], v[6:9]
	v_mfma_f32_16x16x32_bf16 v[4:7], v[172:175], v[218:221], v[2:5]
	s_barrier
	s_add_i32 s4, s4, 2
	s_add_u32 s97, s97, 0x100
	s_addc_u32 s96, s96, 0
	s_cmp_gt_u32 s4, 29
	s_mov_b64 s[8:9], s[68:69]
	s_cbranch_scc0 .LBB0_327
.Lpeelx327:
	s_setprio 0
	s_and_b64 vcc, exec, s[44:45]
	s_cbranch_vccz .LBB0_330
	s_barrier

; #define PG8_STAGE(bufoff, gbase, voff) do { _Pragma("unroll") for (int _i = 0; _i < 2; ++_i) \
;         __builtin_amdgcn_global_load_lds((const unsigned*)((const char*)(gbase) + (voff)[_i]), (PG8_LAS unsigned*)(lds + (bufoff) + ldsw + _i * 8192), 16, 0, 0); } while (0)
; #define PG8_LDA(dst, b, h) do { _Pragma("unroll") for (int m = 0; m < 4; ++m) _Pragma("unroll") for (int k = 0; k < 2; ++k) dst[m][k] = *(const PG8_LAS bf16x8*)(lds + PG8_SA(b, h) + aoff + m * 2048 + k * 1024); } while (0)
; #define PG8_LDB(dst, b, h) do { _Pragma("unroll") for (int n = 0; n < 2; ++n) _Pragma("unroll") for (int k = 0; k < 2; ++k) dst[n][k] = *(const PG8_LAS bf16x8*)(lds + PG8_SB(b, h) + boff + n * 2048 + k * 1024); } while (0)
; #define PG8_MMA(ai, bj, At, Bt) do { __builtin_amdgcn_s_setprio(1); _Pragma("unroll") for (int m = 0; m < 4; ++m) _Pragma("unroll") for (int n = 0; n < 2; ++n) _Pragma("unroll") for (int k = 0; k < 2; ++k) \
;         acc[ai][bj][m][n] = mma16<Epi::I8>(Bt[n][k], At[m][k], acc[ai][bj][m][n]); __builtin_amdgcn_s_setprio(0); } while (0)
; #define PG8_WAIT_V(n) asm volatile("s_waitcnt vmcnt(" #n ")" ::: "memory")
; #define PG8_WAIT_L(n) asm volatile("s_waitcnt lgkmcnt(" #n ")" ::: "memory")
; #define PG8_BAR __builtin_amdgcn_s_barrier()
; template <class Epi, class Sched, bool ALIGN_EPI = false, bool SP2 = false>
; __device__ __forceinline__ void gemm_phase(PG8_LAS unsigned char* lds, const Gemm g, const Sched& S, const Epi& E) {
;     ...
;             const bool last = (t == nt - 2);
;             const char* a1 = cA + (size_t)(t + 1) * kstep;
;             const char* a2 = last ? nA : cA + (size_t)(t + 2) * kstep; const char* b2 = last ? nB : cB + (size_t)(t + 2) * kstep;
;             const char* a3 = a2 + kstep; const char* b3 = b2 + kstep;
;             if (last && has_next) S.a_ready(nxt);
;             if constexpr (SP2) {
;             PG8_LDB(B0, 0, 0); PG8_LDB(B1, 0, 1); PG8_SCHED; PG8_LDA(At, 0, 0); PG8_STAGE(PG8_SA(1, 1), a1 + hstep, voffA);
;             PG8_WAIT_V(8); PG8_WAIT_L(0); PG8_BAR; PG8_MMA(0, 0, At, B0); PG8_MMA(0, 1, At, B1); PG8_BAR; PG8_SCHED;
;             PG8_LDA(At, 0, 1); PG8_STAGE(PG8_SB(0, 0), b2, voffB); PG8_STAGE(PG8_SB(0, 1), b2 + hstep, voffB); PG8_STAGE(PG8_SA(0, 0), a2, voffA);
;             PG8_WAIT_V(8); PG8_WAIT_L(0); PG8_BAR; PG8_MMA(1, 0, At, B0); PG8_MMA(1, 1, At, B1); PG8_BAR; PG8_SCHED;
.Lprio385:
	s_add_u32 s70, s8, 0x100
	s_addc_u32 s71, s9, 0
	s_add_i32 s84, 0, 0x10000
	s_cmp_eq_u32 s5, 12
	s_cselect_b32 vcc_hi, s1, s71
	s_cselect_b32 vcc_lo, s7, s70
	v_add_u32_e32 v0, s84, v214
	s_cselect_b32 s83, s69, s68
	s_cselect_b32 s82, s81, s85
	s_add_i32 s10, 0, 0x14000
	ds_read_b128 v[44:47], v0
	ds_read_b128 v[52:55], v0 offset:1024
	ds_read_b128 v[60:63], v0 offset:2048
	ds_read_b128 v[64:67], v0 offset:3072
	v_add_u32_e32 v0, s10, v214
	ds_read_b128 v[84:87], v0
	ds_read_b128 v[88:91], v0 offset:1024
	ds_read_b128 v[92:95], v0 offset:2048
	ds_read_b128 v[100:103], v0 offset:3072
	v_lshl_add_u64 v[2:3], s[8:9], 0, v[184:185]
	s_add_i32 m0, s13, 0xc000
	ds_read_b128 v[124:127], v215
	ds_read_b128 v[128:131], v215 offset:1024
	ds_read_b128 v[140:143], v215 offset:2048
	ds_read_b128 v[188:191], v215 offset:3072
	ds_read_b128 v[192:195], v215 offset:4096
	ds_read_b128 v[196:199], v215 offset:5120
	ds_read_b128 v[216:219], v215 offset:6144
	ds_read_b128 v[220:223], v215 offset:7168
	global_load_lds_dwordx4 v[2:3], off
	v_lshl_add_u64 v[2:3], s[8:9], 0, v[186:187]
	s_add_i32 m0, s13, 0xe000
	s_nop 0
	global_load_lds_dwordx4 v[2:3], off
	s_waitcnt vmcnt(8)
	s_waitcnt lgkmcnt(0)
	s_barrier
	s_waitcnt lgkmcnt(0)
	v_mfma_i32_16x16x64_i8 v[172:175], v[44:47], v[124:127], 0
	v_mfma_i32_16x16x64_i8 v[164:167], v[60:63], v[124:127], 0
	v_mfma_i32_16x16x64_i8 v[160:163], v[60:63], v[140:143], 0
	v_mfma_i32_16x16x64_i8 v[168:171], v[44:47], v[140:143], 0
	v_mfma_i32_16x16x64_i8 v[156:159], v[44:47], v[192:195], 0
	v_mfma_i32_16x16x64_i8 v[152:155], v[60:63], v[192:195], 0
	v_mfma_i32_16x16x64_i8 v[144:147], v[60:63], v[216:219], 0
	v_mfma_i32_16x16x64_i8 v[148:151], v[44:47], v[216:219], 0
	v_mfma_i32_16x16x64_i8 v[172:175], v[52:55], v[128:131], v[172:175]
	v_mfma_i32_16x16x64_i8 v[164:167], v[64:67], v[128:131], v[164:167]
	v_mfma_i32_16x16x64_i8 v[160:163], v[64:67], v[188:191], v[160:163]
	v_mfma_i32_16x16x64_i8 v[168:171], v[52:55], v[188:191], v[168:171]
	v_mfma_i32_16x16x64_i8 v[156:159], v[52:55], v[196:199], v[156:159]
	v_mfma_i32_16x16x64_i8 v[152:155], v[64:67], v[196:199], v[152:155]
	v_mfma_i32_16x16x64_i8 v[144:147], v[64:67], v[220:223], v[144:147]
	v_mfma_i32_16x16x64_i8 v[148:151], v[52:55], v[220:223], v[148:151]
	v_mfma_i32_16x16x64_i8 v[136:139], v[84:87], v[124:127], 0
	v_mfma_i32_16x16x64_i8 v[120:123], v[92:95], v[124:127], 0
	v_mfma_i32_16x16x64_i8 v[116:119], v[92:95], v[140:143], 0
	v_mfma_i32_16x16x64_i8 v[108:111], v[92:95], v[192:195], 0
	v_mfma_i32_16x16x64_i8 v[112:115], v[84:87], v[192:195], 0
	v_mfma_i32_16x16x64_i8 v[104:107], v[84:87], v[216:219], 0
	v_mfma_i32_16x16x64_i8 v[96:99], v[92:95], v[216:219], 0
	v_mfma_i32_16x16x64_i8 v[136:139], v[88:91], v[128:131], v[136:139]
	v_mfma_i32_16x16x64_i8 v[120:123], v[100:103], v[128:131], v[120:123]
	v_mfma_i32_16x16x64_i8 v[116:119], v[100:103], v[188:191], v[116:119]
	v_mfma_i32_16x16x64_i8 v[108:111], v[100:103], v[196:199], v[108:111]
	v_mfma_i32_16x16x64_i8 v[112:115], v[88:91], v[196:199], v[112:115]
	v_mfma_i32_16x16x64_i8 v[104:107], v[88:91], v[220:223], v[104:107]
	v_mfma_i32_16x16x64_i8 v[96:99], v[100:103], v[220:223], v[96:99]
	v_mfma_i32_16x16x64_i8 v[124:127], v[84:87], v[140:143], 0
	v_mfma_i32_16x16x64_i8 v[124:127], v[88:91], v[188:191], v[124:127]
	s_barrier
	s_add_i32 s8, s84, s12
	v_lshl_add_u64 v[200:201], s[82:83], 0, v[178:179]
	s_mov_b32 m0, s8
	ds_read_b128 v[128:131], v215 offset:16384
	ds_read_b128 v[132:135], v215 offset:17408
	ds_read_b128 v[140:143], v215 offset:18432
	ds_read_b128 v[188:191], v215 offset:19456
	ds_read_b128 v[192:195], v215 offset:20480
	ds_read_b128 v[196:199], v215 offset:21504
	ds_read_b128 v[216:219], v215 offset:22528
	ds_read_b128 v[220:223], v215 offset:23552
	global_load_lds_dwordx4 v[200:201], off
	s_add_i32 m0, s8, 0x2000
	s_add_u32 s8, s82, 0x40000
	v_lshl_add_u64 v[206:207], s[82:83], 0, v[182:183]
	s_addc_u32 s9, s83, 0
	s_add_i32 s10, s10, s12
	global_load_lds_dwordx4 v[206:207], off
	v_lshl_add_u64 v[2:3], s[8:9], 0, v[178:179]
	s_mov_b32 m0, s10
	v_lshl_add_u64 v[210:211], vcc, 0, v[176:177]
	global_load_lds_dwordx4 v[2:3], off
	v_lshl_add_u64 v[2:3], s[8:9], 0, v[182:183]
	s_add_i32 m0, s10, 0x2000
	v_lshl_add_u64 v[224:225], vcc, 0, v[180:181]
	global_load_lds_dwordx4 v[2:3], off
	s_mov_b32 m0, s13
	s_nop 0
	global_load_lds_dwordx4 v[210:211], off
	s_mov_b32 m0, s66
	s_nop 0
	global_load_lds_dwordx4 v[224:225], off
	s_waitcnt vmcnt(8)
	s_waitcnt lgkmcnt(0)
	s_barrier
	s_waitcnt lgkmcnt(0)
	v_mfma_i32_16x16x64_i8 v[80:83], v[44:47], v[128:131], 0
	v_mfma_i32_16x16x64_i8 v[72:75], v[60:63], v[128:131], 0
	v_mfma_i32_16x16x64_i8 v[68:71], v[60:63], v[140:143], 0
	v_mfma_i32_16x16x64_i8 v[76:79], v[44:47], v[140:143], 0
	v_mfma_i32_16x16x64_i8 v[56:59], v[44:47], v[192:195], 0
	v_mfma_i32_16x16x64_i8 v[48:51], v[60:63], v[192:195], 0
	v_mfma_i32_16x16x64_i8 v[36:39], v[60:63], v[216:219], 0
	v_mfma_i32_16x16x64_i8 v[40:43], v[44:47], v[216:219], 0
	v_mfma_i32_16x16x64_i8 v[80:83], v[52:55], v[132:135], v[80:83]
	v_mfma_i32_16x16x64_i8 v[72:75], v[64:67], v[132:135], v[72:75]
	v_mfma_i32_16x16x64_i8 v[68:71], v[64:67], v[188:191], v[68:71]
	v_mfma_i32_16x16x64_i8 v[76:79], v[52:55], v[188:191], v[76:79]
	v_mfma_i32_16x16x64_i8 v[56:59], v[52:55], v[196:199], v[56:59]
	v_mfma_i32_16x16x64_i8 v[48:51], v[64:67], v[196:199], v[48:51]
	v_mfma_i32_16x16x64_i8 v[36:39], v[64:67], v[220:223], v[36:39]
	v_mfma_i32_16x16x64_i8 v[40:43], v[52:55], v[220:223], v[40:43]
	v_mfma_i32_16x16x64_i8 v[32:35], v[84:87], v[128:131], 0
	v_mfma_i32_16x16x64_i8 v[24:27], v[92:95], v[128:131], 0
	v_mfma_i32_16x16x64_i8 v[20:23], v[92:95], v[140:143], 0
	v_mfma_i32_16x16x64_i8 v[28:31], v[84:87], v[140:143], 0
	v_mfma_i32_16x16x64_i8 v[16:19], v[84:87], v[192:195], 0
	v_mfma_i32_16x16x64_i8 v[12:15], v[92:95], v[192:195], 0
	v_mfma_i32_16x16x64_i8 v[2:5], v[92:95], v[216:219], 0
	v_mfma_i32_16x16x64_i8 v[8:11], v[84:87], v[216:219], 0
	v_mfma_i32_16x16x64_i8 v[32:35], v[88:91], v[132:135], v[32:35]
	v_mfma_i32_16x16x64_i8 v[24:27], v[100:103], v[132:135], v[24:27]
	v_mfma_i32_16x16x64_i8 v[20:23], v[100:103], v[188:191], v[20:23]
	v_mfma_i32_16x16x64_i8 v[28:31], v[88:91], v[188:191], v[28:31]
	v_mfma_i32_16x16x64_i8 v[16:19], v[88:91], v[196:199], v[16:19]
	v_mfma_i32_16x16x64_i8 v[12:15], v[100:103], v[196:199], v[12:15]
	v_mfma_i32_16x16x64_i8 v[2:5], v[100:103], v[220:223], v[2:5]
	v_mfma_i32_16x16x64_i8 v[8:11], v[88:91], v[220:223], v[8:11]
	s_barrier
; #define PG8_STAGE(bufoff, gbase, voff) do { _Pragma("unroll") for (int _i = 0; _i < 2; ++_i) \
;         __builtin_amdgcn_global_load_lds((const unsigned*)((const char*)(gbase) + (voff)[_i]), (PG8_LAS unsigned*)(lds + (bufoff) + ldsw + _i * 8192), 16, 0, 0); } while (0)
; #define PG8_LDA(dst, b, h) do { _Pragma("unroll") for (int m = 0; m < 4; ++m) _Pragma("unroll") for (int k = 0; k < 2; ++k) dst[m][k] = *(const PG8_LAS bf16x8*)(lds + PG8_SA(b, h) + aoff + m * 2048 + k * 1024); } while (0)
; #define PG8_LDB(dst, b, h) do { _Pragma("unroll") for (int n = 0; n < 2; ++n) _Pragma("unroll") for (int k = 0; k < 2; ++k) dst[n][k] = *(const PG8_LAS bf16x8*)(lds + PG8_SB(b, h) + boff + n * 2048 + k * 1024); } while (0)
; #define PG8_MMA(ai, bj, At, Bt) do { __builtin_amdgcn_s_setprio(1); _Pragma("unroll") for (int m = 0; m < 4; ++m) _Pragma("unroll") for (int n = 0; n < 2; ++n) _Pragma("unroll") for (int k = 0; k < 2; ++k) \
;         acc[ai][bj][m][n] = mma16<Epi::I8>(Bt[n][k], At[m][k], acc[ai][bj][m][n]); __builtin_amdgcn_s_setprio(0); } while (0)
; #define PG8_WAIT_V(n) asm volatile("s_waitcnt vmcnt(" #n ")" ::: "memory")
; #define PG8_WAIT_L(n) asm volatile("s_waitcnt lgkmcnt(" #n ")" ::: "memory")
; #define PG8_BAR __builtin_amdgcn_s_barrier()
; #define PG8_SCHED __builtin_amdgcn_sched_barrier(0)
; template <class Epi, class Sched, bool ALIGN_EPI = false, bool SP2 = false>
; __device__ __forceinline__ void gemm_phase(PG8_LAS unsigned char* lds, const Gemm g, const Sched& S, const Epi& E) {
;     ...
;         for (int t = 0; t < nt; t += 2) {
;     ...
;             PG8_LDB(B0, 1, 0); PG8_LDB(B1, 1, 1); PG8_SCHED; PG8_LDA(At, 1, 0); PG8_STAGE(PG8_SA(0, 1), a2 + hstep, voffA);
;             PG8_WAIT_V(8); PG8_WAIT_L(0); PG8_BAR; PG8_MMA(0, 0, At, B0); PG8_MMA(0, 1, At, B1); PG8_BAR; PG8_SCHED;
;             PG8_LDA(At, 1, 1); PG8_STAGE(PG8_SB(1, 0), b3, voffB); PG8_STAGE(PG8_SB(1, 1), b3 + hstep, voffB); PG8_STAGE(PG8_SA(1, 0), a3, voffA);
;             PG8_WAIT_V(8); PG8_WAIT_L(0); PG8_BAR; PG8_MMA(1, 0, At, B0); PG8_MMA(1, 1, At, B1); PG8_BAR; PG8_SCHED;
	s_add_i32 s10, 0, 0x18000
	v_add_u32_e32 v0, s10, v214
	s_add_i32 s11, 0, 0x1c000
	ds_read_b128 v[44:47], v0
	ds_read_b128 v[52:55], v0 offset:1024
	ds_read_b128 v[60:63], v0 offset:2048
	ds_read_b128 v[64:67], v0 offset:3072
	v_add_u32_e32 v0, s11, v214
	ds_read_b128 v[84:87], v0
	ds_read_b128 v[88:91], v0 offset:1024
	ds_read_b128 v[92:95], v0 offset:2048
	ds_read_b128 v[100:103], v0 offset:3072
	s_add_u32 s8, vcc_lo, 0x40000
	s_addc_u32 s9, vcc_hi, 0
	s_mov_b32 m0, s67
	v_lshl_add_u64 v[6:7], s[8:9], 0, v[176:177]
	ds_read_b128 v[128:131], v215 offset:32768
	ds_read_b128 v[132:135], v215 offset:33792
	ds_read_b128 v[140:143], v215 offset:34816
	ds_read_b128 v[188:191], v215 offset:35840
	ds_read_b128 v[192:195], v215 offset:36864
	ds_read_b128 v[196:199], v215 offset:37888
	ds_read_b128 v[216:219], v215 offset:38912
	ds_read_b128 v[220:223], v215 offset:39936
	global_load_lds_dwordx4 v[6:7], off
	v_lshl_add_u64 v[6:7], s[8:9], 0, v[180:181]
	s_mov_b32 m0, s80
	s_nop 0
	global_load_lds_dwordx4 v[6:7], off
	s_waitcnt vmcnt(8)
	s_waitcnt lgkmcnt(0)
	s_barrier
	s_waitcnt lgkmcnt(0)
	v_mfma_i32_16x16x64_i8 v[172:175], v[44:47], v[128:131], v[172:175]
	v_mfma_i32_16x16x64_i8 v[164:167], v[60:63], v[128:131], v[164:167]
	v_mfma_i32_16x16x64_i8 v[160:163], v[60:63], v[140:143], v[160:163]
	v_mfma_i32_16x16x64_i8 v[168:171], v[44:47], v[140:143], v[168:171]
	v_mfma_i32_16x16x64_i8 v[156:159], v[44:47], v[192:195], v[156:159]
	v_mfma_i32_16x16x64_i8 v[152:155], v[60:63], v[192:195], v[152:155]
	v_mfma_i32_16x16x64_i8 v[144:147], v[60:63], v[216:219], v[144:147]
	v_mfma_i32_16x16x64_i8 v[148:151], v[44:47], v[216:219], v[148:151]
	v_mfma_i32_16x16x64_i8 v[172:175], v[52:55], v[132:135], v[172:175]
	v_mfma_i32_16x16x64_i8 v[164:167], v[64:67], v[132:135], v[164:167]
	v_mfma_i32_16x16x64_i8 v[160:163], v[64:67], v[188:191], v[160:163]
	v_mfma_i32_16x16x64_i8 v[168:171], v[52:55], v[188:191], v[168:171]
	v_mfma_i32_16x16x64_i8 v[156:159], v[52:55], v[196:199], v[156:159]
	v_mfma_i32_16x16x64_i8 v[152:155], v[64:67], v[196:199], v[152:155]
	v_mfma_i32_16x16x64_i8 v[144:147], v[64:67], v[220:223], v[144:147]
	v_mfma_i32_16x16x64_i8 v[148:151], v[52:55], v[220:223], v[148:151]
	v_mfma_i32_16x16x64_i8 v[136:139], v[84:87], v[128:131], v[136:139]
	v_mfma_i32_16x16x64_i8 v[120:123], v[92:95], v[128:131], v[120:123]
	v_mfma_i32_16x16x64_i8 v[116:119], v[92:95], v[140:143], v[116:119]
	v_mfma_i32_16x16x64_i8 v[124:127], v[84:87], v[140:143], v[124:127]
	v_mfma_i32_16x16x64_i8 v[112:115], v[84:87], v[192:195], v[112:115]
	v_mfma_i32_16x16x64_i8 v[108:111], v[92:95], v[192:195], v[108:111]
	v_mfma_i32_16x16x64_i8 v[96:99], v[92:95], v[216:219], v[96:99]
	v_mfma_i32_16x16x64_i8 v[104:107], v[84:87], v[216:219], v[104:107]
	v_mfma_i32_16x16x64_i8 v[136:139], v[88:91], v[132:135], v[136:139]
	v_mfma_i32_16x16x64_i8 v[120:123], v[100:103], v[132:135], v[120:123]
	v_mfma_i32_16x16x64_i8 v[116:119], v[100:103], v[188:191], v[116:119]
	v_mfma_i32_16x16x64_i8 v[132:135], v[88:91], v[188:191], v[124:127]
	v_mfma_i32_16x16x64_i8 v[112:115], v[88:91], v[196:199], v[112:115]
	v_mfma_i32_16x16x64_i8 v[108:111], v[100:103], v[196:199], v[108:111]
	v_mfma_i32_16x16x64_i8 v[96:99], v[100:103], v[220:223], v[96:99]
	v_mfma_i32_16x16x64_i8 v[104:107], v[88:91], v[220:223], v[104:107]
	s_barrier
	s_add_i32 s8, s10, s12
	v_lshl_add_u64 v[6:7], v[200:201], 0, s[92:93]
	s_mov_b32 m0, s8
	ds_read_b128 v[124:127], v215 offset:49152
	ds_read_b128 v[128:131], v215 offset:50176
	ds_read_b128 v[140:143], v215 offset:51200
	ds_read_b128 v[188:191], v215 offset:52224
	ds_read_b128 v[192:195], v215 offset:53248
	ds_read_b128 v[196:199], v215 offset:54272
	ds_read_b128 v[216:219], v215 offset:55296
	ds_read_b128 v[220:223], v215 offset:56320
	global_load_lds_dwordx4 v[6:7], off
	s_add_i32 m0, s8, 0x2000
	s_add_u32 s8, s82, 0x40080
	v_lshl_add_u64 v[6:7], v[206:207], 0, s[92:93]
	s_addc_u32 s9, s83, 0
	s_add_i32 s10, s11, s12
	global_load_lds_dwordx4 v[6:7], off
	v_lshl_add_u64 v[6:7], s[8:9], 0, v[178:179]
	s_mov_b32 m0, s10
	s_nop 0
	global_load_lds_dwordx4 v[6:7], off
	v_lshl_add_u64 v[6:7], s[8:9], 0, v[182:183]
	s_add_i32 m0, s10, 0x2000
	s_nop 0
	global_load_lds_dwordx4 v[6:7], off
	v_lshl_add_u64 v[6:7], v[210:211], 0, s[92:93]
	s_mov_b32 m0, s58
	s_nop 0
	global_load_lds_dwordx4 v[6:7], off
	v_lshl_add_u64 v[6:7], v[224:225], 0, s[92:93]
	s_mov_b32 m0, s4
	s_nop 0
	global_load_lds_dwordx4 v[6:7], off
	s_waitcnt vmcnt(8)
	s_waitcnt lgkmcnt(0)
	s_barrier
	s_waitcnt lgkmcnt(0)
	v_mfma_i32_16x16x64_i8 v[80:83], v[44:47], v[124:127], v[80:83]
	v_mfma_i32_16x16x64_i8 v[72:75], v[60:63], v[124:127], v[72:75]
	v_mfma_i32_16x16x64_i8 v[68:71], v[60:63], v[140:143], v[68:71]
	v_mfma_i32_16x16x64_i8 v[76:79], v[44:47], v[140:143], v[76:79]
	v_mfma_i32_16x16x64_i8 v[56:59], v[44:47], v[192:195], v[56:59]
	v_mfma_i32_16x16x64_i8 v[48:51], v[60:63], v[192:195], v[48:51]
	v_mfma_i32_16x16x64_i8 v[36:39], v[60:63], v[216:219], v[36:39]
	v_mfma_i32_16x16x64_i8 v[40:43], v[44:47], v[216:219], v[40:43]
	v_mfma_i32_16x16x64_i8 v[80:83], v[52:55], v[128:131], v[80:83]
	v_mfma_i32_16x16x64_i8 v[72:75], v[64:67], v[128:131], v[72:75]
	v_mfma_i32_16x16x64_i8 v[68:71], v[64:67], v[188:191], v[68:71]
	v_mfma_i32_16x16x64_i8 v[76:79], v[52:55], v[188:191], v[76:79]
	v_mfma_i32_16x16x64_i8 v[56:59], v[52:55], v[196:199], v[56:59]
	v_mfma_i32_16x16x64_i8 v[48:51], v[64:67], v[196:199], v[48:51]
	v_mfma_i32_16x16x64_i8 v[36:39], v[64:67], v[220:223], v[36:39]
	v_mfma_i32_16x16x64_i8 v[40:43], v[52:55], v[220:223], v[40:43]
	v_mfma_i32_16x16x64_i8 v[32:35], v[84:87], v[124:127], v[32:35]
	v_mfma_i32_16x16x64_i8 v[24:27], v[92:95], v[124:127], v[24:27]
	v_mfma_i32_16x16x64_i8 v[20:23], v[92:95], v[140:143], v[20:23]
	v_mfma_i32_16x16x64_i8 v[28:31], v[84:87], v[140:143], v[28:31]
	v_mfma_i32_16x16x64_i8 v[16:19], v[84:87], v[192:195], v[16:19]
	v_mfma_i32_16x16x64_i8 v[12:15], v[92:95], v[192:195], v[12:15]
	v_mfma_i32_16x16x64_i8 v[2:5], v[92:95], v[216:219], v[2:5]
	v_mfma_i32_16x16x64_i8 v[6:9], v[84:87], v[216:219], v[8:11]
	v_mfma_i32_16x16x64_i8 v[32:35], v[88:91], v[128:131], v[32:35]
	v_mfma_i32_16x16x64_i8 v[24:27], v[100:103], v[128:131], v[24:27]
	v_mfma_i32_16x16x64_i8 v[20:23], v[100:103], v[188:191], v[20:23]
	v_mfma_i32_16x16x64_i8 v[28:31], v[88:91], v[188:191], v[28:31]
	v_mfma_i32_16x16x64_i8 v[16:19], v[88:91], v[196:199], v[16:19]
	v_mfma_i32_16x16x64_i8 v[12:15], v[100:103], v[196:199], v[12:15]
	v_mfma_i32_16x16x64_i8 v[8:11], v[88:91], v[220:223], v[6:9]
	v_mfma_i32_16x16x64_i8 v[4:7], v[100:103], v[220:223], v[2:5]
	s_barrier
	s_add_i32 s5, s5, 2
	s_add_u32 s85, s85, 0x100
	s_addc_u32 s68, s68, 0
	s_cmp_gt_u32 s5, 13
	s_mov_b64 s[8:9], s[70:71]
	s_cbranch_scc0 .LBB0_385
	s_branch .Lpeelx385
; #define PG8_STAGE(bufoff, gbase, voff) do { _Pragma("unroll") for (int _i = 0; _i < 2; ++_i) \
;         __builtin_amdgcn_global_load_lds((const unsigned*)((const char*)(gbase) + (voff)[_i]), (PG8_LAS unsigned*)(lds + (bufoff) + ldsw + _i * 8192), 16, 0, 0); } while (0)
; #define PG8_LDA(dst, b, h) do { _Pragma("unroll") for (int m = 0; m < 4; ++m) _Pragma("unroll") for (int k = 0; k < 2; ++k) dst[m][k] = *(const PG8_LAS bf16x8*)(lds + PG8_SA(b, h) + aoff + m * 2048 + k * 1024); } while (0)
; #define PG8_LDB(dst, b, h) do { _Pragma("unroll") for (int n = 0; n < 2; ++n) _Pragma("unroll") for (int k = 0; k < 2; ++k) dst[n][k] = *(const PG8_LAS bf16x8*)(lds + PG8_SB(b, h) + boff + n * 2048 + k * 1024); } while (0)
; #define PG8_MMA(ai, bj, At, Bt) do { __builtin_amdgcn_s_setprio(1); _Pragma("unroll") for (int m = 0; m < 4; ++m) _Pragma("unroll") for (int n = 0; n < 2; ++n) _Pragma("unroll") for (int k = 0; k < 2; ++k) \
;         acc[ai][bj][m][n] = mma16<Epi::I8>(Bt[n][k], At[m][k], acc[ai][bj][m][n]); __builtin_amdgcn_s_setprio(0); } while (0)
; #define PG8_WAIT_V(n) asm volatile("s_waitcnt vmcnt(" #n ")" ::: "memory")
; #define PG8_WAIT_L(n) asm volatile("s_waitcnt lgkmcnt(" #n ")" ::: "memory")
; #define PG8_BAR __builtin_amdgcn_s_barrier()
; #define PG8_SCHED __builtin_amdgcn_sched_barrier(0)
; template <class Epi, class Sched, bool ALIGN_EPI = false, bool SP2 = false>
; __device__ __forceinline__ void gemm_phase(PG8_LAS unsigned char* lds, const Gemm g, const Sched& S, const Epi& E) {
;     ...
;             PG8_LDB(B0, 0, 0); PG8_LDB(B1, 0, 1); PG8_SCHED; PG8_LDA(At, 0, 0); PG8_STAGE(PG8_SA(1, 1), a1 + hstep, voffA);
;             PG8_WAIT_V(8); PG8_WAIT_L(0); PG8_BAR; PG8_MMA(0, 0, At, B0); PG8_MMA(0, 1, At, B1); PG8_BAR; PG8_SCHED;
;             PG8_LDA(At, 0, 1); PG8_STAGE(PG8_SB(0, 0), b2, voffB); PG8_STAGE(PG8_SB(0, 1), b2 + hstep, voffB); PG8_STAGE(PG8_SA(0, 0), a2, voffA);
;             PG8_WAIT_V(8); PG8_WAIT_L(0); PG8_BAR; PG8_MMA(1, 0, At, B0); PG8_MMA(1, 1, At, B1); PG8_BAR; PG8_SCHED;
.LBB0_385:
	s_add_u32 s70, s8, 0x100
	s_addc_u32 s71, s9, 0
	s_add_i32 s84, 0, 0x10000
	s_cmp_eq_u32 s5, 12
	s_cselect_b32 vcc_hi, s1, s71
	s_cselect_b32 vcc_lo, s7, s70
	v_add_u32_e32 v0, s84, v214
	s_cselect_b32 s83, s69, s68
	s_cselect_b32 s82, s81, s85
	s_add_i32 s10, 0, 0x14000
	ds_read_b128 v[44:47], v0
	ds_read_b128 v[52:55], v0 offset:1024
	ds_read_b128 v[60:63], v0 offset:2048
	ds_read_b128 v[64:67], v0 offset:3072
	v_add_u32_e32 v0, s10, v214
	ds_read_b128 v[84:87], v0
	ds_read_b128 v[88:91], v0 offset:1024
	ds_read_b128 v[92:95], v0 offset:2048
	ds_read_b128 v[100:103], v0 offset:3072
	v_lshl_add_u64 v[2:3], s[8:9], 0, v[184:185]
	s_add_i32 m0, s13, 0xc000
	ds_read_b128 v[124:127], v215
	ds_read_b128 v[128:131], v215 offset:1024
	ds_read_b128 v[140:143], v215 offset:2048
	ds_read_b128 v[188:191], v215 offset:3072
	ds_read_b128 v[192:195], v215 offset:4096
	ds_read_b128 v[196:199], v215 offset:5120
	ds_read_b128 v[216:219], v215 offset:6144
	ds_read_b128 v[220:223], v215 offset:7168
	global_load_lds_dwordx4 v[2:3], off
	v_lshl_add_u64 v[2:3], s[8:9], 0, v[186:187]
	s_add_i32 m0, s13, 0xe000
	s_nop 0
	global_load_lds_dwordx4 v[2:3], off
	s_waitcnt vmcnt(8)
	s_waitcnt lgkmcnt(0)
	s_barrier
	s_waitcnt lgkmcnt(0)
	v_mfma_i32_16x16x64_i8 v[172:175], v[44:47], v[124:127], v[172:175]
	v_mfma_i32_16x16x64_i8 v[164:167], v[60:63], v[124:127], v[164:167]
	v_mfma_i32_16x16x64_i8 v[160:163], v[60:63], v[140:143], v[160:163]
	v_mfma_i32_16x16x64_i8 v[168:171], v[44:47], v[140:143], v[168:171]
	v_mfma_i32_16x16x64_i8 v[156:159], v[44:47], v[192:195], v[156:159]
	v_mfma_i32_16x16x64_i8 v[152:155], v[60:63], v[192:195], v[152:155]
	v_mfma_i32_16x16x64_i8 v[144:147], v[60:63], v[216:219], v[144:147]
	v_mfma_i32_16x16x64_i8 v[148:151], v[44:47], v[216:219], v[148:151]
	v_mfma_i32_16x16x64_i8 v[172:175], v[52:55], v[128:131], v[172:175]
	v_mfma_i32_16x16x64_i8 v[164:167], v[64:67], v[128:131], v[164:167]
	v_mfma_i32_16x16x64_i8 v[160:163], v[64:67], v[188:191], v[160:163]
	v_mfma_i32_16x16x64_i8 v[168:171], v[52:55], v[188:191], v[168:171]
	v_mfma_i32_16x16x64_i8 v[156:159], v[52:55], v[196:199], v[156:159]
	v_mfma_i32_16x16x64_i8 v[152:155], v[64:67], v[196:199], v[152:155]
	v_mfma_i32_16x16x64_i8 v[144:147], v[64:67], v[220:223], v[144:147]
	v_mfma_i32_16x16x64_i8 v[148:151], v[52:55], v[220:223], v[148:151]
	v_mfma_i32_16x16x64_i8 v[136:139], v[84:87], v[124:127], v[136:139]
	v_mfma_i32_16x16x64_i8 v[120:123], v[92:95], v[124:127], v[120:123]
	v_mfma_i32_16x16x64_i8 v[116:119], v[92:95], v[140:143], v[116:119]
	v_mfma_i32_16x16x64_i8 v[108:111], v[92:95], v[192:195], v[108:111]
	v_mfma_i32_16x16x64_i8 v[112:115], v[84:87], v[192:195], v[112:115]
	v_mfma_i32_16x16x64_i8 v[104:107], v[84:87], v[216:219], v[104:107]
	v_mfma_i32_16x16x64_i8 v[96:99], v[92:95], v[216:219], v[96:99]
	v_mfma_i32_16x16x64_i8 v[136:139], v[88:91], v[128:131], v[136:139]
	v_mfma_i32_16x16x64_i8 v[120:123], v[100:103], v[128:131], v[120:123]
	v_mfma_i32_16x16x64_i8 v[116:119], v[100:103], v[188:191], v[116:119]
	v_mfma_i32_16x16x64_i8 v[108:111], v[100:103], v[196:199], v[108:111]
	v_mfma_i32_16x16x64_i8 v[112:115], v[88:91], v[196:199], v[112:115]
	v_mfma_i32_16x16x64_i8 v[104:107], v[88:91], v[220:223], v[104:107]
	v_mfma_i32_16x16x64_i8 v[96:99], v[100:103], v[220:223], v[96:99]
	v_mfma_i32_16x16x64_i8 v[124:127], v[84:87], v[140:143], v[132:135]
	v_mfma_i32_16x16x64_i8 v[124:127], v[88:91], v[188:191], v[124:127]
	s_barrier
	s_add_i32 s8, s84, s12
	v_lshl_add_u64 v[200:201], s[82:83], 0, v[178:179]
	s_mov_b32 m0, s8
	ds_read_b128 v[128:131], v215 offset:16384
	ds_read_b128 v[132:135], v215 offset:17408
	ds_read_b128 v[140:143], v215 offset:18432
	ds_read_b128 v[188:191], v215 offset:19456
	ds_read_b128 v[192:195], v215 offset:20480
	ds_read_b128 v[196:199], v215 offset:21504
	ds_read_b128 v[216:219], v215 offset:22528
	ds_read_b128 v[220:223], v215 offset:23552
	global_load_lds_dwordx4 v[200:201], off
	s_add_i32 m0, s8, 0x2000
	s_add_u32 s8, s82, 0x40000
	v_lshl_add_u64 v[206:207], s[82:83], 0, v[182:183]
	s_addc_u32 s9, s83, 0
	s_add_i32 s10, s10, s12
	global_load_lds_dwordx4 v[206:207], off
	v_lshl_add_u64 v[2:3], s[8:9], 0, v[178:179]
	s_mov_b32 m0, s10
	v_lshl_add_u64 v[210:211], vcc, 0, v[176:177]
	global_load_lds_dwordx4 v[2:3], off
	v_lshl_add_u64 v[2:3], s[8:9], 0, v[182:183]
	s_add_i32 m0, s10, 0x2000
	v_lshl_add_u64 v[224:225], vcc, 0, v[180:181]
	global_load_lds_dwordx4 v[2:3], off
	s_mov_b32 m0, s13
	s_nop 0
	global_load_lds_dwordx4 v[210:211], off
	s_mov_b32 m0, s66
	s_nop 0
	global_load_lds_dwordx4 v[224:225], off
	s_waitcnt vmcnt(8)
	s_waitcnt lgkmcnt(0)
	s_barrier
; #define PG8_STAGE(bufoff, gbase, voff) do { _Pragma("unroll") for (int _i = 0; _i < 2; ++_i) \
;         __builtin_amdgcn_global_load_lds((const unsigned*)((const char*)(gbase) + (voff)[_i]), (PG8_LAS unsigned*)(lds + (bufoff) + ldsw + _i * 8192), 16, 0, 0); } while (0)
; #define PG8_LDA(dst, b, h) do { _Pragma("unroll") for (int m = 0; m < 4; ++m) _Pragma("unroll") for (int k = 0; k < 2; ++k) dst[m][k] = *(const PG8_LAS bf16x8*)(lds + PG8_SA(b, h) + aoff + m * 2048 + k * 1024); } while (0)
; #define PG8_LDB(dst, b, h) do { _Pragma("unroll") for (int n = 0; n < 2; ++n) _Pragma("unroll") for (int k = 0; k < 2; ++k) dst[n][k] = *(const PG8_LAS bf16x8*)(lds + PG8_SB(b, h) + boff + n * 2048 + k * 1024); } while (0)
; #define PG8_MMA(ai, bj, At, Bt) do { __builtin_amdgcn_s_setprio(1); _Pragma("unroll") for (int m = 0; m < 4; ++m) _Pragma("unroll") for (int n = 0; n < 2; ++n) _Pragma("unroll") for (int k = 0; k < 2; ++k) \
;         acc[ai][bj][m][n] = mma16<Epi::I8>(Bt[n][k], At[m][k], acc[ai][bj][m][n]); __builtin_amdgcn_s_setprio(0); } while (0)
; #define PG8_WAIT_V(n) asm volatile("s_waitcnt vmcnt(" #n ")" ::: "memory")
; #define PG8_WAIT_L(n) asm volatile("s_waitcnt lgkmcnt(" #n ")" ::: "memory")
; #define PG8_BAR __builtin_amdgcn_s_barrier()
; #define PG8_SCHED __builtin_amdgcn_sched_barrier(0)
; template <class Epi, class Sched, bool ALIGN_EPI = false, bool SP2 = false>
; __device__ __forceinline__ void gemm_phase(PG8_LAS unsigned char* lds, const Gemm g, const Sched& S, const Epi& E) {
;     ...
;             PG8_WAIT_V(8); PG8_WAIT_L(0); PG8_BAR; PG8_MMA(1, 0, At, B0); PG8_MMA(1, 1, At, B1); PG8_BAR; PG8_SCHED;
;             PG8_LDB(B0, 1, 0); PG8_LDB(B1, 1, 1); PG8_SCHED; PG8_LDA(At, 1, 0); PG8_STAGE(PG8_SA(0, 1), a2 + hstep, voffA);
;             PG8_WAIT_V(8); PG8_WAIT_L(0); PG8_BAR; PG8_MMA(0, 0, At, B0); PG8_MMA(0, 1, At, B1); PG8_BAR; PG8_SCHED;
	s_waitcnt lgkmcnt(0)
	v_mfma_i32_16x16x64_i8 v[80:83], v[44:47], v[128:131], v[80:83]
	v_mfma_i32_16x16x64_i8 v[72:75], v[60:63], v[128:131], v[72:75]
	v_mfma_i32_16x16x64_i8 v[68:71], v[60:63], v[140:143], v[68:71]
	v_mfma_i32_16x16x64_i8 v[76:79], v[44:47], v[140:143], v[76:79]
	v_mfma_i32_16x16x64_i8 v[56:59], v[44:47], v[192:195], v[56:59]
	v_mfma_i32_16x16x64_i8 v[48:51], v[60:63], v[192:195], v[48:51]
	v_mfma_i32_16x16x64_i8 v[36:39], v[60:63], v[216:219], v[36:39]
	v_mfma_i32_16x16x64_i8 v[40:43], v[44:47], v[216:219], v[40:43]
	v_mfma_i32_16x16x64_i8 v[80:83], v[52:55], v[132:135], v[80:83]
	v_mfma_i32_16x16x64_i8 v[72:75], v[64:67], v[132:135], v[72:75]
	v_mfma_i32_16x16x64_i8 v[68:71], v[64:67], v[188:191], v[68:71]
	v_mfma_i32_16x16x64_i8 v[76:79], v[52:55], v[188:191], v[76:79]
	v_mfma_i32_16x16x64_i8 v[56:59], v[52:55], v[196:199], v[56:59]
	v_mfma_i32_16x16x64_i8 v[48:51], v[64:67], v[196:199], v[48:51]
	v_mfma_i32_16x16x64_i8 v[36:39], v[64:67], v[220:223], v[36:39]
	v_mfma_i32_16x16x64_i8 v[40:43], v[52:55], v[220:223], v[40:43]
	v_mfma_i32_16x16x64_i8 v[32:35], v[84:87], v[128:131], v[32:35]
	v_mfma_i32_16x16x64_i8 v[24:27], v[92:95], v[128:131], v[24:27]
	v_mfma_i32_16x16x64_i8 v[20:23], v[92:95], v[140:143], v[20:23]
	v_mfma_i32_16x16x64_i8 v[28:31], v[84:87], v[140:143], v[28:31]
	v_mfma_i32_16x16x64_i8 v[16:19], v[84:87], v[192:195], v[16:19]
	v_mfma_i32_16x16x64_i8 v[12:15], v[92:95], v[192:195], v[12:15]
	v_mfma_i32_16x16x64_i8 v[2:5], v[92:95], v[216:219], v[4:7]
	v_mfma_i32_16x16x64_i8 v[8:11], v[84:87], v[216:219], v[8:11]
	v_mfma_i32_16x16x64_i8 v[32:35], v[88:91], v[132:135], v[32:35]
	v_mfma_i32_16x16x64_i8 v[24:27], v[100:103], v[132:135], v[24:27]
	v_mfma_i32_16x16x64_i8 v[20:23], v[100:103], v[188:191], v[20:23]
	v_mfma_i32_16x16x64_i8 v[28:31], v[88:91], v[188:191], v[28:31]
	v_mfma_i32_16x16x64_i8 v[16:19], v[88:91], v[196:199], v[16:19]
	v_mfma_i32_16x16x64_i8 v[12:15], v[100:103], v[196:199], v[12:15]
	v_mfma_i32_16x16x64_i8 v[2:5], v[100:103], v[220:223], v[2:5]
	v_mfma_i32_16x16x64_i8 v[8:11], v[88:91], v[220:223], v[8:11]
	s_barrier
	s_add_i32 s10, 0, 0x18000
	v_add_u32_e32 v0, s10, v214
	s_add_i32 s11, 0, 0x1c000
	ds_read_b128 v[44:47], v0
	ds_read_b128 v[52:55], v0 offset:1024
	ds_read_b128 v[60:63], v0 offset:2048
	ds_read_b128 v[64:67], v0 offset:3072
	v_add_u32_e32 v0, s11, v214
	ds_read_b128 v[84:87], v0
	ds_read_b128 v[88:91], v0 offset:1024
	ds_read_b128 v[92:95], v0 offset:2048
	ds_read_b128 v[100:103], v0 offset:3072
	s_add_u32 s8, vcc_lo, 0x40000
	s_addc_u32 s9, vcc_hi, 0
	s_mov_b32 m0, s67
	v_lshl_add_u64 v[6:7], s[8:9], 0, v[176:177]
	ds_read_b128 v[128:131], v215 offset:32768
	ds_read_b128 v[132:135], v215 offset:33792
	ds_read_b128 v[140:143], v215 offset:34816
	ds_read_b128 v[188:191], v215 offset:35840
	ds_read_b128 v[192:195], v215 offset:36864
	ds_read_b128 v[196:199], v215 offset:37888
	ds_read_b128 v[216:219], v215 offset:38912
	ds_read_b128 v[220:223], v215 offset:39936
	global_load_lds_dwordx4 v[6:7], off
	v_lshl_add_u64 v[6:7], s[8:9], 0, v[180:181]
	s_mov_b32 m0, s80
	s_nop 0
	global_load_lds_dwordx4 v[6:7], off
	s_waitcnt vmcnt(8)
	s_waitcnt lgkmcnt(0)
	s_barrier
	s_waitcnt lgkmcnt(0)
	v_mfma_i32_16x16x64_i8 v[172:175], v[44:47], v[128:131], v[172:175]
	v_mfma_i32_16x16x64_i8 v[164:167], v[60:63], v[128:131], v[164:167]
	v_mfma_i32_16x16x64_i8 v[160:163], v[60:63], v[140:143], v[160:163]
	v_mfma_i32_16x16x64_i8 v[168:171], v[44:47], v[140:143], v[168:171]
	v_mfma_i32_16x16x64_i8 v[156:159], v[44:47], v[192:195], v[156:159]
	v_mfma_i32_16x16x64_i8 v[152:155], v[60:63], v[192:195], v[152:155]
	v_mfma_i32_16x16x64_i8 v[144:147], v[60:63], v[216:219], v[144:147]
	v_mfma_i32_16x16x64_i8 v[148:151], v[44:47], v[216:219], v[148:151]
	v_mfma_i32_16x16x64_i8 v[172:175], v[52:55], v[132:135], v[172:175]
	v_mfma_i32_16x16x64_i8 v[164:167], v[64:67], v[132:135], v[164:167]
	v_mfma_i32_16x16x64_i8 v[160:163], v[64:67], v[188:191], v[160:163]
	v_mfma_i32_16x16x64_i8 v[168:171], v[52:55], v[188:191], v[168:171]
	v_mfma_i32_16x16x64_i8 v[156:159], v[52:55], v[196:199], v[156:159]
	v_mfma_i32_16x16x64_i8 v[152:155], v[64:67], v[196:199], v[152:155]
	v_mfma_i32_16x16x64_i8 v[144:147], v[64:67], v[220:223], v[144:147]
	v_mfma_i32_16x16x64_i8 v[148:151], v[52:55], v[220:223], v[148:151]
	v_mfma_i32_16x16x64_i8 v[136:139], v[84:87], v[128:131], v[136:139]
	v_mfma_i32_16x16x64_i8 v[120:123], v[92:95], v[128:131], v[120:123]
	v_mfma_i32_16x16x64_i8 v[116:119], v[92:95], v[140:143], v[116:119]
	v_mfma_i32_16x16x64_i8 v[124:127], v[84:87], v[140:143], v[124:127]
	v_mfma_i32_16x16x64_i8 v[112:115], v[84:87], v[192:195], v[112:115]
	v_mfma_i32_16x16x64_i8 v[108:111], v[92:95], v[192:195], v[108:111]
	v_mfma_i32_16x16x64_i8 v[96:99], v[92:95], v[216:219], v[96:99]
	v_mfma_i32_16x16x64_i8 v[104:107], v[84:87], v[216:219], v[104:107]
	v_mfma_i32_16x16x64_i8 v[136:139], v[88:91], v[132:135], v[136:139]
	v_mfma_i32_16x16x64_i8 v[120:123], v[100:103], v[132:135], v[120:123]
	v_mfma_i32_16x16x64_i8 v[116:119], v[100:103], v[188:191], v[116:119]
	v_mfma_i32_16x16x64_i8 v[132:135], v[88:91], v[188:191], v[124:127]
	v_mfma_i32_16x16x64_i8 v[112:115], v[88:91], v[196:199], v[112:115]
	v_mfma_i32_16x16x64_i8 v[108:111], v[100:103], v[196:199], v[108:111]
	v_mfma_i32_16x16x64_i8 v[96:99], v[100:103], v[220:223], v[96:99]
	v_mfma_i32_16x16x64_i8 v[104:107], v[88:91], v[220:223], v[104:107]
	s_barrier
; #define PG8_STAGE(bufoff, gbase, voff) do { _Pragma("unroll") for (int _i = 0; _i < 2; ++_i) \
;         __builtin_amdgcn_global_load_lds((const unsigned*)((const char*)(gbase) + (voff)[_i]), (PG8_LAS unsigned*)(lds + (bufoff) + ldsw + _i * 8192), 16, 0, 0); } while (0)
; #define PG8_LDA(dst, b, h) do { _Pragma("unroll") for (int m = 0; m < 4; ++m) _Pragma("unroll") for (int k = 0; k < 2; ++k) dst[m][k] = *(const PG8_LAS bf16x8*)(lds + PG8_SA(b, h) + aoff + m * 2048 + k * 1024); } while (0)
; #define PG8_MMA(ai, bj, At, Bt) do { __builtin_amdgcn_s_setprio(1); _Pragma("unroll") for (int m = 0; m < 4; ++m) _Pragma("unroll") for (int n = 0; n < 2; ++n) _Pragma("unroll") for (int k = 0; k < 2; ++k) \
;         acc[ai][bj][m][n] = mma16<Epi::I8>(Bt[n][k], At[m][k], acc[ai][bj][m][n]); __builtin_amdgcn_s_setprio(0); } while (0)
; #define PG8_WAIT_V(n) asm volatile("s_waitcnt vmcnt(" #n ")" ::: "memory")
; #define PG8_WAIT_L(n) asm volatile("s_waitcnt lgkmcnt(" #n ")" ::: "memory")
; #define PG8_BAR __builtin_amdgcn_s_barrier()
; #define PG8_SCHED __builtin_amdgcn_sched_barrier(0)
; template <class Epi, class Sched, bool ALIGN_EPI = false, bool SP2 = false>
; __device__ __forceinline__ void gemm_phase(PG8_LAS unsigned char* lds, const Gemm g, const Sched& S, const Epi& E) {
;     ...
;             PG8_LDA(At, 1, 1); PG8_STAGE(PG8_SB(1, 0), b3, voffB); PG8_STAGE(PG8_SB(1, 1), b3 + hstep, voffB); PG8_STAGE(PG8_SA(1, 0), a3, voffA);
;             PG8_WAIT_V(8); PG8_WAIT_L(0); PG8_BAR; PG8_MMA(1, 0, At, B0); PG8_MMA(1, 1, At, B1); PG8_BAR; PG8_SCHED;
;     ...
;         if constexpr (ALIGN_EPI) { if (wr == 0) PG8_BAR; }
;         if constexpr (!Epi::AFTER_DRAIN) { E(acc, cur, wr, wc, fr, fq); S.done(cur); }
	s_add_i32 s8, s10, s12
	v_lshl_add_u64 v[6:7], v[200:201], 0, s[92:93]
	s_mov_b32 m0, s8
	ds_read_b128 v[124:127], v215 offset:49152
	ds_read_b128 v[128:131], v215 offset:50176
	ds_read_b128 v[140:143], v215 offset:51200
	ds_read_b128 v[188:191], v215 offset:52224
	ds_read_b128 v[192:195], v215 offset:53248
	ds_read_b128 v[196:199], v215 offset:54272
	ds_read_b128 v[216:219], v215 offset:55296
	ds_read_b128 v[220:223], v215 offset:56320
	global_load_lds_dwordx4 v[6:7], off
	s_add_i32 m0, s8, 0x2000
	s_add_u32 s8, s82, 0x40080
	v_lshl_add_u64 v[6:7], v[206:207], 0, s[92:93]
	s_addc_u32 s9, s83, 0
	s_add_i32 s10, s11, s12
	global_load_lds_dwordx4 v[6:7], off
	v_lshl_add_u64 v[6:7], s[8:9], 0, v[178:179]
	s_mov_b32 m0, s10
	s_nop 0
	global_load_lds_dwordx4 v[6:7], off
	v_lshl_add_u64 v[6:7], s[8:9], 0, v[182:183]
	s_add_i32 m0, s10, 0x2000
	s_nop 0
	global_load_lds_dwordx4 v[6:7], off
	v_lshl_add_u64 v[6:7], v[210:211], 0, s[92:93]
	s_mov_b32 m0, s58
	s_nop 0
	global_load_lds_dwordx4 v[6:7], off
	v_lshl_add_u64 v[6:7], v[224:225], 0, s[92:93]
	s_mov_b32 m0, s4
	s_nop 0
	global_load_lds_dwordx4 v[6:7], off
	s_waitcnt vmcnt(8)
	s_waitcnt lgkmcnt(0)
	s_barrier
	s_waitcnt lgkmcnt(0)
	v_mfma_i32_16x16x64_i8 v[80:83], v[44:47], v[124:127], v[80:83]
	v_mfma_i32_16x16x64_i8 v[72:75], v[60:63], v[124:127], v[72:75]
	v_mfma_i32_16x16x64_i8 v[68:71], v[60:63], v[140:143], v[68:71]
	v_mfma_i32_16x16x64_i8 v[76:79], v[44:47], v[140:143], v[76:79]
	v_mfma_i32_16x16x64_i8 v[56:59], v[44:47], v[192:195], v[56:59]
	v_mfma_i32_16x16x64_i8 v[48:51], v[60:63], v[192:195], v[48:51]
	v_mfma_i32_16x16x64_i8 v[36:39], v[60:63], v[216:219], v[36:39]
	v_mfma_i32_16x16x64_i8 v[40:43], v[44:47], v[216:219], v[40:43]
	v_mfma_i32_16x16x64_i8 v[80:83], v[52:55], v[128:131], v[80:83]
	v_mfma_i32_16x16x64_i8 v[72:75], v[64:67], v[128:131], v[72:75]
	v_mfma_i32_16x16x64_i8 v[68:71], v[64:67], v[188:191], v[68:71]
	v_mfma_i32_16x16x64_i8 v[76:79], v[52:55], v[188:191], v[76:79]
	v_mfma_i32_16x16x64_i8 v[56:59], v[52:55], v[196:199], v[56:59]
	v_mfma_i32_16x16x64_i8 v[48:51], v[64:67], v[196:199], v[48:51]
	v_mfma_i32_16x16x64_i8 v[36:39], v[64:67], v[220:223], v[36:39]
	v_mfma_i32_16x16x64_i8 v[40:43], v[52:55], v[220:223], v[40:43]
	v_mfma_i32_16x16x64_i8 v[32:35], v[84:87], v[124:127], v[32:35]
	v_mfma_i32_16x16x64_i8 v[24:27], v[92:95], v[124:127], v[24:27]
	v_mfma_i32_16x16x64_i8 v[20:23], v[92:95], v[140:143], v[20:23]
	v_mfma_i32_16x16x64_i8 v[28:31], v[84:87], v[140:143], v[28:31]
	v_mfma_i32_16x16x64_i8 v[16:19], v[84:87], v[192:195], v[16:19]
	v_mfma_i32_16x16x64_i8 v[12:15], v[92:95], v[192:195], v[12:15]
	v_mfma_i32_16x16x64_i8 v[2:5], v[92:95], v[216:219], v[2:5]
	v_mfma_i32_16x16x64_i8 v[6:9], v[84:87], v[216:219], v[8:11]
	v_mfma_i32_16x16x64_i8 v[32:35], v[88:91], v[128:131], v[32:35]
	v_mfma_i32_16x16x64_i8 v[24:27], v[100:103], v[128:131], v[24:27]
	v_mfma_i32_16x16x64_i8 v[20:23], v[100:103], v[188:191], v[20:23]
	v_mfma_i32_16x16x64_i8 v[28:31], v[88:91], v[188:191], v[28:31]
	v_mfma_i32_16x16x64_i8 v[16:19], v[88:91], v[196:199], v[16:19]
	v_mfma_i32_16x16x64_i8 v[12:15], v[100:103], v[196:199], v[12:15]
	v_mfma_i32_16x16x64_i8 v[8:11], v[88:91], v[220:223], v[6:9]
	v_mfma_i32_16x16x64_i8 v[4:7], v[100:103], v[220:223], v[2:5]
	s_barrier
	s_add_i32 s5, s5, 2
	s_add_u32 s85, s85, 0x100
	s_addc_u32 s68, s68, 0
	s_cmp_gt_u32 s5, 13
	s_mov_b64 s[8:9], s[70:71]
	s_cbranch_scc0 .LBB0_385
.Lpeelx385:
	s_setprio 0
	s_and_b64 vcc, exec, s[40:41]
	s_cbranch_vccz .LBB0_388
	s_barrier
